# GEMM 8-phase loops: loop-carried pointer increments and loop compare moved from behind the last MMA group into the preceding load segment
# baseline (speedup 1.0000x reference)
.LBB0_190:
	ds_read_b128 v[180:183], v172
	ds_read_b128 v[184:187], v172 offset:1024
	ds_read_b128 v[188:191], v172 offset:2048
	ds_read_b128 v[192:195], v172 offset:3072
	v_add_u32_e32 v178, 0xc000, v152
	v_lshl_add_u64 v[244:245], s[20:21], 0, v[146:147]
	v_readfirstlane_b32 s1, v178
	v_add_u32_e32 v179, 0xe000, v152
	v_lshl_add_u64 v[224:225], v[244:245], 0, s[48:49]
	s_mov_b32 m0, s1
	v_lshl_add_u64 v[246:247], s[20:21], 0, v[148:149]
	v_readfirstlane_b32 s1, v179
	ds_read_b128 v[174:177], v161
	ds_read_b128 v[196:199], v161 offset:1024
	ds_read_b128 v[200:203], v160
	ds_read_b128 v[204:207], v160 offset:1024
	ds_read_b128 v[208:211], v159
	ds_read_b128 v[212:215], v159 offset:1024
	ds_read_b128 v[216:219], v158
	ds_read_b128 v[220:223], v158 offset:1024
	global_load_lds_dwordx4 v[224:225], off
	v_lshl_add_u64 v[224:225], v[246:247], 0, s[48:49]
	s_mov_b32 m0, s1
	s_nop 0
	global_load_lds_dwordx4 v[224:225], off
	s_waitcnt lgkmcnt(8)
	s_barrier
	s_waitcnt lgkmcnt(0)
	v_mfma_f32_16x16x32_bf16 v[124:127], v[180:183], v[174:177], v[124:127]
	v_mfma_f32_16x16x32_bf16 v[120:123], v[188:191], v[174:177], v[120:123]
	v_mfma_f32_16x16x32_bf16 v[116:119], v[180:183], v[200:203], v[116:119]
	v_mfma_f32_16x16x32_bf16 v[112:115], v[188:191], v[200:203], v[112:115]
	v_mfma_f32_16x16x32_bf16 v[108:111], v[180:183], v[208:211], v[108:111]
	v_mfma_f32_16x16x32_bf16 v[104:107], v[188:191], v[208:211], v[104:107]
	v_mfma_f32_16x16x32_bf16 v[100:103], v[180:183], v[216:219], v[100:103]
	v_mfma_f32_16x16x32_bf16 v[96:99], v[188:191], v[216:219], v[96:99]
	v_mfma_f32_16x16x32_bf16 v[124:127], v[184:187], v[196:199], v[124:127]
	v_mfma_f32_16x16x32_bf16 v[120:123], v[192:195], v[196:199], v[120:123]
	v_mfma_f32_16x16x32_bf16 v[116:119], v[184:187], v[204:207], v[116:119]
	v_mfma_f32_16x16x32_bf16 v[112:115], v[192:195], v[204:207], v[112:115]
	v_mfma_f32_16x16x32_bf16 v[108:111], v[184:187], v[212:215], v[108:111]
	v_mfma_f32_16x16x32_bf16 v[104:107], v[192:195], v[212:215], v[104:107]
	v_mfma_f32_16x16x32_bf16 v[100:103], v[184:187], v[220:223], v[100:103]
	v_mfma_f32_16x16x32_bf16 v[96:99], v[192:195], v[220:223], v[96:99]
	s_barrier
	v_lshl_add_u64 v[248:249], s[20:21], 0, v[142:143]
	v_readfirstlane_b32 s1, v153
	v_add_u32_e32 v173, 0x2000, v153
	v_lshl_add_u64 v[240:241], v[248:249], 0, s[50:51]
	s_mov_b32 m0, s1
	v_lshl_add_u64 v[250:251], s[20:21], 0, v[144:145]
	v_readfirstlane_b32 s1, v173
	ds_read_b128 v[224:227], v169
	ds_read_b128 v[228:231], v169 offset:1024
	ds_read_b128 v[232:235], v169 offset:2048
	ds_read_b128 v[236:239], v169 offset:3072
	global_load_lds_dwordx4 v[240:241], off
	v_lshl_add_u64 v[240:241], v[250:251], 0, s[50:51]
	s_mov_b32 m0, s1
	s_nop 0
	global_load_lds_dwordx4 v[240:241], off
	s_barrier
	s_waitcnt lgkmcnt(0)
	v_mfma_f32_16x16x32_bf16 v[92:95], v[224:227], v[174:177], v[92:95]
	v_mfma_f32_16x16x32_bf16 v[88:91], v[232:235], v[174:177], v[88:91]
	v_mfma_f32_16x16x32_bf16 v[84:87], v[224:227], v[200:203], v[84:87]
	v_mfma_f32_16x16x32_bf16 v[80:83], v[232:235], v[200:203], v[80:83]
	v_mfma_f32_16x16x32_bf16 v[76:79], v[224:227], v[208:211], v[76:79]
	v_mfma_f32_16x16x32_bf16 v[72:75], v[232:235], v[208:211], v[72:75]
	v_mfma_f32_16x16x32_bf16 v[68:71], v[224:227], v[216:219], v[68:71]
	v_mfma_f32_16x16x32_bf16 v[64:67], v[232:235], v[216:219], v[64:67]
	v_mfma_f32_16x16x32_bf16 v[92:95], v[228:231], v[196:199], v[92:95]
	v_mfma_f32_16x16x32_bf16 v[88:91], v[236:239], v[196:199], v[88:91]
	v_mfma_f32_16x16x32_bf16 v[84:87], v[228:231], v[204:207], v[84:87]
	v_mfma_f32_16x16x32_bf16 v[80:83], v[236:239], v[204:207], v[80:83]
	v_mfma_f32_16x16x32_bf16 v[76:79], v[228:231], v[212:215], v[76:79]
	v_mfma_f32_16x16x32_bf16 v[72:75], v[236:239], v[212:215], v[72:75]
	v_mfma_f32_16x16x32_bf16 v[68:71], v[228:231], v[220:223], v[68:71]
	v_mfma_f32_16x16x32_bf16 v[64:67], v[236:239], v[220:223], v[64:67]
	v_readfirstlane_b32 s1, v152
	v_lshl_add_u64 v[174:175], v[244:245], 0, s[52:53]
	s_mov_b32 m0, s1
	s_barrier
	ds_read_b128 v[196:199], v161 offset:16384
	ds_read_b128 v[200:203], v161 offset:17408
	ds_read_b128 v[204:207], v160 offset:16384
	ds_read_b128 v[208:211], v160 offset:17408
	ds_read_b128 v[212:215], v159 offset:16384
	ds_read_b128 v[216:219], v159 offset:17408
	ds_read_b128 v[220:223], v158 offset:16384
	ds_read_b128 v[240:243], v158 offset:17408
	global_load_lds_dwordx4 v[174:175], off
	v_add_u32_e32 v174, 0x2000, v152
	v_lshl_add_u64 v[176:177], v[246:247], 0, s[52:53]
	v_readfirstlane_b32 s1, v174
	s_mov_b32 m0, s1
	s_nop 0
	global_load_lds_dwordx4 v[176:177], off
	s_barrier
	s_waitcnt lgkmcnt(0)
	v_mfma_f32_16x16x32_bf16 v[60:63], v[180:183], v[196:199], v[60:63]
	v_mfma_f32_16x16x32_bf16 v[56:59], v[188:191], v[196:199], v[56:59]
	v_mfma_f32_16x16x32_bf16 v[52:55], v[180:183], v[204:207], v[52:55]
	v_mfma_f32_16x16x32_bf16 v[48:51], v[188:191], v[204:207], v[48:51]
	v_mfma_f32_16x16x32_bf16 v[44:47], v[180:183], v[212:215], v[44:47]
	v_mfma_f32_16x16x32_bf16 v[40:43], v[188:191], v[212:215], v[40:43]
	v_mfma_f32_16x16x32_bf16 v[36:39], v[180:183], v[220:223], v[36:39]
	v_mfma_f32_16x16x32_bf16 v[32:35], v[188:191], v[220:223], v[32:35]
	v_mfma_f32_16x16x32_bf16 v[60:63], v[184:187], v[200:203], v[60:63]
	v_mfma_f32_16x16x32_bf16 v[56:59], v[192:195], v[200:203], v[56:59]
	v_mfma_f32_16x16x32_bf16 v[52:55], v[184:187], v[208:211], v[52:55]
	v_mfma_f32_16x16x32_bf16 v[48:51], v[192:195], v[208:211], v[48:51]
	v_mfma_f32_16x16x32_bf16 v[44:47], v[184:187], v[216:219], v[44:47]
	v_mfma_f32_16x16x32_bf16 v[40:43], v[192:195], v[216:219], v[40:43]
	v_mfma_f32_16x16x32_bf16 v[36:39], v[184:187], v[240:243], v[36:39]
	v_mfma_f32_16x16x32_bf16 v[32:35], v[192:195], v[240:243], v[32:35]
	s_barrier
	v_readfirstlane_b32 s1, v151
	v_add_u32_e32 v175, 0x2000, v151
	v_lshl_add_u64 v[176:177], v[248:249], 0, s[54:55]
	s_mov_b32 m0, s1
	v_readfirstlane_b32 s1, v175
	global_load_lds_dwordx4 v[176:177], off
	v_lshl_add_u64 v[176:177], v[250:251], 0, s[54:55]
	s_mov_b32 m0, s1
	s_nop 0
	global_load_lds_dwordx4 v[176:177], off
	s_waitcnt vmcnt(6)
	s_barrier
	v_mfma_f32_16x16x32_bf16 v[28:31], v[224:227], v[196:199], v[28:31]
	v_mfma_f32_16x16x32_bf16 v[24:27], v[232:235], v[196:199], v[24:27]
	v_mfma_f32_16x16x32_bf16 v[20:23], v[224:227], v[204:207], v[20:23]
	v_mfma_f32_16x16x32_bf16 v[16:19], v[232:235], v[204:207], v[16:19]
	v_mfma_f32_16x16x32_bf16 v[12:15], v[224:227], v[212:215], v[12:15]
	v_mfma_f32_16x16x32_bf16 v[8:11], v[232:235], v[212:215], v[8:11]
	v_mfma_f32_16x16x32_bf16 v[4:7], v[224:227], v[220:223], v[4:7]
	v_mfma_f32_16x16x32_bf16 v[0:3], v[232:235], v[220:223], v[0:3]
	v_mfma_f32_16x16x32_bf16 v[28:31], v[228:231], v[200:203], v[28:31]
	v_mfma_f32_16x16x32_bf16 v[24:27], v[236:239], v[200:203], v[24:27]
	v_mfma_f32_16x16x32_bf16 v[20:23], v[228:231], v[208:211], v[20:23]
	v_mfma_f32_16x16x32_bf16 v[16:19], v[236:239], v[208:211], v[16:19]
	v_mfma_f32_16x16x32_bf16 v[12:15], v[228:231], v[216:219], v[12:15]
	v_mfma_f32_16x16x32_bf16 v[8:11], v[236:239], v[216:219], v[8:11]
	v_mfma_f32_16x16x32_bf16 v[4:7], v[228:231], v[240:243], v[4:7]
	v_mfma_f32_16x16x32_bf16 v[0:3], v[236:239], v[240:243], v[0:3]
	s_barrier
	ds_read_b128 v[180:183], v163
	ds_read_b128 v[184:187], v163 offset:1024
	ds_read_b128 v[188:191], v163 offset:2048
	ds_read_b128 v[192:195], v163 offset:3072
	v_add_u32_e32 v176, 0x4000, v152
	v_add_u32_e32 v177, 0x6000, v152
	v_readfirstlane_b32 s1, v176
	v_lshl_add_u64 v[228:229], v[244:245], 0, s[56:57]
	s_mov_b32 m0, s1
	v_readfirstlane_b32 s1, v177
	ds_read_b128 v[196:199], v161 offset:32768
	ds_read_b128 v[200:203], v161 offset:33792
	ds_read_b128 v[204:207], v160 offset:32768
	ds_read_b128 v[208:211], v160 offset:33792
	ds_read_b128 v[212:215], v159 offset:32768
	ds_read_b128 v[216:219], v159 offset:33792
	ds_read_b128 v[220:223], v158 offset:32768
	ds_read_b128 v[224:227], v158 offset:33792
	global_load_lds_dwordx4 v[228:229], off
	v_lshl_add_u64 v[228:229], v[246:247], 0, s[56:57]
	s_mov_b32 m0, s1
	s_nop 0
	global_load_lds_dwordx4 v[228:229], off
	s_waitcnt lgkmcnt(8)
	s_barrier
	s_waitcnt lgkmcnt(0)
	v_mfma_f32_16x16x32_bf16 v[124:127], v[180:183], v[196:199], v[124:127]
	v_mfma_f32_16x16x32_bf16 v[120:123], v[188:191], v[196:199], v[120:123]
	v_mfma_f32_16x16x32_bf16 v[116:119], v[180:183], v[204:207], v[116:119]
	v_mfma_f32_16x16x32_bf16 v[112:115], v[188:191], v[204:207], v[112:115]
	v_mfma_f32_16x16x32_bf16 v[108:111], v[180:183], v[212:215], v[108:111]
	v_mfma_f32_16x16x32_bf16 v[104:107], v[188:191], v[212:215], v[104:107]
	v_mfma_f32_16x16x32_bf16 v[100:103], v[180:183], v[220:223], v[100:103]
	v_mfma_f32_16x16x32_bf16 v[96:99], v[188:191], v[220:223], v[96:99]
	v_mfma_f32_16x16x32_bf16 v[124:127], v[184:187], v[200:203], v[124:127]
	v_mfma_f32_16x16x32_bf16 v[120:123], v[192:195], v[200:203], v[120:123]
	v_mfma_f32_16x16x32_bf16 v[116:119], v[184:187], v[208:211], v[116:119]
	v_mfma_f32_16x16x32_bf16 v[112:115], v[192:195], v[208:211], v[112:115]
	v_mfma_f32_16x16x32_bf16 v[108:111], v[184:187], v[216:219], v[108:111]
	v_mfma_f32_16x16x32_bf16 v[104:107], v[192:195], v[216:219], v[104:107]
	v_mfma_f32_16x16x32_bf16 v[100:103], v[184:187], v[224:227], v[100:103]
	v_mfma_f32_16x16x32_bf16 v[96:99], v[192:195], v[224:227], v[96:99]
	s_barrier
	v_readfirstlane_b32 s1, v167
	v_add_u32_e32 v254, 0x2000, v167
	v_lshl_add_u64 v[252:253], v[248:249], 0, s[58:59]
	s_mov_b32 m0, s1
	v_readfirstlane_b32 s1, v254
	ds_read_b128 v[228:231], v162
	ds_read_b128 v[232:235], v162 offset:1024
	ds_read_b128 v[236:239], v162 offset:2048
	ds_read_b128 v[240:243], v162 offset:3072
	global_load_lds_dwordx4 v[252:253], off
	v_lshl_add_u64 v[252:253], v[250:251], 0, s[58:59]
	s_mov_b32 m0, s1
	s_nop 0
	global_load_lds_dwordx4 v[252:253], off
	s_barrier
	s_waitcnt lgkmcnt(0)
	v_mfma_f32_16x16x32_bf16 v[92:95], v[228:231], v[196:199], v[92:95]
	v_mfma_f32_16x16x32_bf16 v[88:91], v[236:239], v[196:199], v[88:91]
	v_mfma_f32_16x16x32_bf16 v[84:87], v[228:231], v[204:207], v[84:87]
	v_mfma_f32_16x16x32_bf16 v[80:83], v[236:239], v[204:207], v[80:83]
	v_mfma_f32_16x16x32_bf16 v[76:79], v[228:231], v[212:215], v[76:79]
	v_mfma_f32_16x16x32_bf16 v[72:75], v[236:239], v[212:215], v[72:75]
	v_mfma_f32_16x16x32_bf16 v[68:71], v[228:231], v[220:223], v[68:71]
	v_mfma_f32_16x16x32_bf16 v[64:67], v[236:239], v[220:223], v[64:67]
	v_mfma_f32_16x16x32_bf16 v[92:95], v[232:235], v[200:203], v[92:95]
	v_mfma_f32_16x16x32_bf16 v[88:91], v[240:243], v[200:203], v[88:91]
	v_mfma_f32_16x16x32_bf16 v[84:87], v[232:235], v[208:211], v[84:87]
	v_mfma_f32_16x16x32_bf16 v[80:83], v[240:243], v[208:211], v[80:83]
	v_mfma_f32_16x16x32_bf16 v[76:79], v[232:235], v[216:219], v[76:79]
	v_mfma_f32_16x16x32_bf16 v[72:75], v[240:243], v[216:219], v[72:75]
	v_mfma_f32_16x16x32_bf16 v[68:71], v[232:235], v[224:227], v[68:71]
	v_mfma_f32_16x16x32_bf16 v[64:67], v[240:243], v[224:227], v[64:67]
	v_readfirstlane_b32 s1, v168
	v_lshl_add_u64 v[244:245], v[244:245], 0, s[60:61]
	s_mov_b32 m0, s1
	v_readfirstlane_b32 s1, v170
	s_barrier
	ds_read_b128 v[196:199], v161 offset:49152
	ds_read_b128 v[200:203], v161 offset:50176
	ds_read_b128 v[204:207], v160 offset:49152
	ds_read_b128 v[208:211], v160 offset:50176
	ds_read_b128 v[212:215], v159 offset:49152
	ds_read_b128 v[216:219], v159 offset:50176
	ds_read_b128 v[220:223], v158 offset:49152
	ds_read_b128 v[224:227], v158 offset:50176
	global_load_lds_dwordx4 v[244:245], off
	v_lshl_add_u64 v[244:245], v[246:247], 0, s[60:61]
	s_mov_b32 m0, s1
	s_nop 0
	global_load_lds_dwordx4 v[244:245], off
	s_barrier
	s_waitcnt lgkmcnt(0)
	v_mfma_f32_16x16x32_bf16 v[60:63], v[180:183], v[196:199], v[60:63]
	v_mfma_f32_16x16x32_bf16 v[56:59], v[188:191], v[196:199], v[56:59]
	v_mfma_f32_16x16x32_bf16 v[52:55], v[180:183], v[204:207], v[52:55]
	v_mfma_f32_16x16x32_bf16 v[48:51], v[188:191], v[204:207], v[48:51]
	v_mfma_f32_16x16x32_bf16 v[44:47], v[180:183], v[212:215], v[44:47]
	v_mfma_f32_16x16x32_bf16 v[40:43], v[188:191], v[212:215], v[40:43]
	v_mfma_f32_16x16x32_bf16 v[36:39], v[180:183], v[220:223], v[36:39]
	v_mfma_f32_16x16x32_bf16 v[32:35], v[188:191], v[220:223], v[32:35]
	v_mfma_f32_16x16x32_bf16 v[60:63], v[184:187], v[200:203], v[60:63]
	v_mfma_f32_16x16x32_bf16 v[56:59], v[192:195], v[200:203], v[56:59]
	v_mfma_f32_16x16x32_bf16 v[52:55], v[184:187], v[208:211], v[52:55]
	v_mfma_f32_16x16x32_bf16 v[48:51], v[192:195], v[208:211], v[48:51]
	v_mfma_f32_16x16x32_bf16 v[44:47], v[184:187], v[216:219], v[44:47]
	v_mfma_f32_16x16x32_bf16 v[40:43], v[192:195], v[216:219], v[40:43]
	v_mfma_f32_16x16x32_bf16 v[36:39], v[184:187], v[224:227], v[36:39]
	v_mfma_f32_16x16x32_bf16 v[32:35], v[192:195], v[224:227], v[32:35]
	s_barrier
	v_readfirstlane_b32 s1, v171
	v_add_u32_e32 v182, 0x2000, v171
	v_lshl_add_u64 v[180:181], v[248:249], 0, s[62:63]
	s_mov_b32 m0, s1
	v_readfirstlane_b32 s1, v182
	global_load_lds_dwordx4 v[180:181], off
	v_lshl_add_u64 v[180:181], v[250:251], 0, s[62:63]
	s_mov_b32 m0, s1
	s_nop 0
	global_load_lds_dwordx4 v[180:181], off
	s_add_i32 s0, s0, 2
	v_lshl_add_u64 v[142:143], v[142:143], 0, s[50:51]
	v_lshl_add_u64 v[144:145], v[144:145], 0, s[50:51]
	v_lshl_add_u64 v[146:147], v[146:147], 0, s[50:51]
	s_cmp_lt_u32 s0, 12
	v_lshl_add_u64 v[148:149], v[148:149], 0, s[50:51]
	s_waitcnt vmcnt(6)
	s_barrier
	v_mfma_f32_16x16x32_bf16 v[28:31], v[228:231], v[196:199], v[28:31]
	v_mfma_f32_16x16x32_bf16 v[24:27], v[236:239], v[196:199], v[24:27]
	v_mfma_f32_16x16x32_bf16 v[20:23], v[228:231], v[204:207], v[20:23]
	v_mfma_f32_16x16x32_bf16 v[16:19], v[236:239], v[204:207], v[16:19]
	v_mfma_f32_16x16x32_bf16 v[12:15], v[228:231], v[212:215], v[12:15]
	v_mfma_f32_16x16x32_bf16 v[8:11], v[236:239], v[212:215], v[8:11]
	v_mfma_f32_16x16x32_bf16 v[4:7], v[228:231], v[220:223], v[4:7]
	v_mfma_f32_16x16x32_bf16 v[0:3], v[236:239], v[220:223], v[0:3]
	v_mfma_f32_16x16x32_bf16 v[28:31], v[232:235], v[200:203], v[28:31]
	v_mfma_f32_16x16x32_bf16 v[24:27], v[240:243], v[200:203], v[24:27]
	v_mfma_f32_16x16x32_bf16 v[20:23], v[232:235], v[208:211], v[20:23]
	v_mfma_f32_16x16x32_bf16 v[16:19], v[240:243], v[208:211], v[16:19]
	v_mfma_f32_16x16x32_bf16 v[12:15], v[232:235], v[216:219], v[12:15]
	v_mfma_f32_16x16x32_bf16 v[8:11], v[240:243], v[216:219], v[8:11]
	v_mfma_f32_16x16x32_bf16 v[4:7], v[232:235], v[224:227], v[4:7]
	v_mfma_f32_16x16x32_bf16 v[0:3], v[240:243], v[224:227], v[0:3]
	s_barrier
	s_cbranch_scc1 .LBB0_190
	s_or_b32 s0, s6, 0x80
	s_ashr_i32 s1, s0, 31
	s_lshl_b64 s[0:1], s[0:1], 11
	s_add_u32 s0, s45, s0
	s_addc_u32 s1, s46, s1
	v_lshl_add_u64 v[170:171], s[0:1], 0, v[130:131]
	v_lshl_add_u64 v[138:139], v[138:139], 1, v[170:171]
	v_readfirstlane_b32 s2, v178
	v_lshl_add_u64 v[138:139], v[138:139], 0, s[64:65]
	s_mov_b32 m0, s2
	ds_read_b128 v[142:145], v172
	ds_read_b128 v[146:149], v172 offset:1024
	ds_read_b128 v[180:183], v172 offset:2048
	ds_read_b128 v[184:187], v172 offset:3072
	ds_read_b128 v[188:191], v161
	ds_read_b128 v[192:195], v161 offset:1024
	ds_read_b128 v[196:199], v160
	ds_read_b128 v[200:203], v160 offset:1024
	ds_read_b128 v[204:207], v159
	ds_read_b128 v[208:211], v159 offset:1024
	ds_read_b128 v[212:215], v158
	ds_read_b128 v[216:219], v158 offset:1024
	global_load_lds_dwordx4 v[138:139], off
	v_lshl_add_u64 v[138:139], s[0:1], 0, v[134:135]
	v_lshl_add_u64 v[138:139], v[140:141], 1, v[138:139]
	v_readfirstlane_b32 s0, v179
	v_lshl_add_u64 v[138:139], v[138:139], 0, s[64:65]
	s_mov_b32 m0, s0
	v_readlane_b32 s0, v255, 11
	global_load_lds_dwordx4 v[138:139], off
	s_add_i32 s82, s82, s0
	s_barrier
	s_waitcnt lgkmcnt(0)
	s_cmpk_gt_i32 s82, 0x54
	s_cselect_b64 s[66:67], -1, 0
	s_waitcnt lgkmcnt(0)
	v_mfma_f32_16x16x32_bf16 v[124:127], v[142:145], v[188:191], v[124:127]
	v_mfma_f32_16x16x32_bf16 v[116:119], v[142:145], v[196:199], v[116:119]
	v_mfma_f32_16x16x32_bf16 v[108:111], v[142:145], v[204:207], v[108:111]
	v_mfma_f32_16x16x32_bf16 v[100:103], v[142:145], v[212:215], v[100:103]
	v_mfma_f32_16x16x32_bf16 v[124:127], v[146:149], v[192:195], v[124:127]
	v_mfma_f32_16x16x32_bf16 v[120:123], v[180:183], v[188:191], v[120:123]
	v_mfma_f32_16x16x32_bf16 v[116:119], v[146:149], v[200:203], v[116:119]
	v_mfma_f32_16x16x32_bf16 v[112:115], v[180:183], v[196:199], v[112:115]
	v_mfma_f32_16x16x32_bf16 v[108:111], v[146:149], v[208:211], v[108:111]
	v_mfma_f32_16x16x32_bf16 v[104:107], v[180:183], v[204:207], v[104:107]
	v_mfma_f32_16x16x32_bf16 v[100:103], v[146:149], v[216:219], v[100:103]
	v_mfma_f32_16x16x32_bf16 v[96:99], v[180:183], v[212:215], v[96:99]
	v_mfma_f32_16x16x32_bf16 v[138:141], v[184:187], v[192:195], v[120:123]
	v_mfma_f32_16x16x32_bf16 v[220:223], v[184:187], v[200:203], v[112:115]
	v_mfma_f32_16x16x32_bf16 v[224:227], v[184:187], v[208:211], v[104:107]
	v_mfma_f32_16x16x32_bf16 v[228:231], v[184:187], v[216:219], v[96:99]
	s_barrier
	s_nop 1
	ds_read_b128 v[96:99], v169
	ds_read_b128 v[104:107], v169 offset:1024
	ds_read_b128 v[112:115], v169 offset:2048
	ds_read_b128 v[120:123], v169 offset:3072
	s_barrier
	s_waitcnt lgkmcnt(0)
	v_mfma_f32_16x16x32_bf16 v[92:95], v[96:99], v[188:191], v[92:95]
	v_mfma_f32_16x16x32_bf16 v[88:91], v[112:115], v[188:191], v[88:91]
	v_mfma_f32_16x16x32_bf16 v[84:87], v[96:99], v[196:199], v[84:87]
	v_mfma_f32_16x16x32_bf16 v[80:83], v[112:115], v[196:199], v[80:83]
	v_mfma_f32_16x16x32_bf16 v[76:79], v[96:99], v[204:207], v[76:79]
	v_mfma_f32_16x16x32_bf16 v[72:75], v[112:115], v[204:207], v[72:75]
	v_mfma_f32_16x16x32_bf16 v[68:71], v[96:99], v[212:215], v[68:71]
	v_mfma_f32_16x16x32_bf16 v[64:67], v[112:115], v[212:215], v[64:67]
	v_mfma_f32_16x16x32_bf16 v[92:95], v[104:107], v[192:195], v[92:95]
	v_mfma_f32_16x16x32_bf16 v[88:91], v[120:123], v[192:195], v[88:91]
	v_mfma_f32_16x16x32_bf16 v[84:87], v[104:107], v[200:203], v[84:87]
	v_mfma_f32_16x16x32_bf16 v[80:83], v[120:123], v[200:203], v[80:83]
	v_mfma_f32_16x16x32_bf16 v[76:79], v[104:107], v[208:211], v[76:79]
	v_mfma_f32_16x16x32_bf16 v[72:75], v[120:123], v[208:211], v[72:75]
	v_mfma_f32_16x16x32_bf16 v[68:71], v[104:107], v[216:219], v[68:71]
	v_mfma_f32_16x16x32_bf16 v[64:67], v[120:123], v[216:219], v[64:67]
	s_barrier
	ds_read_b128 v[168:171], v161 offset:16384
	ds_read_b128 v[188:191], v161 offset:17408
	ds_read_b128 v[192:195], v160 offset:16384
	ds_read_b128 v[196:199], v160 offset:17408
	ds_read_b128 v[200:203], v159 offset:16384
	ds_read_b128 v[204:207], v159 offset:17408
	ds_read_b128 v[208:211], v158 offset:16384
	ds_read_b128 v[212:215], v158 offset:17408
	s_waitcnt vmcnt(4)
	s_barrier
	s_waitcnt lgkmcnt(0)
	v_mfma_f32_16x16x32_bf16 v[60:63], v[142:145], v[168:171], v[60:63]
	v_mfma_f32_16x16x32_bf16 v[52:55], v[142:145], v[192:195], v[52:55]
	v_mfma_f32_16x16x32_bf16 v[44:47], v[142:145], v[200:203], v[44:47]
	v_mfma_f32_16x16x32_bf16 v[36:39], v[142:145], v[208:211], v[36:39]
	v_mfma_f32_16x16x32_bf16 v[60:63], v[146:149], v[188:191], v[60:63]
	v_mfma_f32_16x16x32_bf16 v[56:59], v[180:183], v[168:171], v[56:59]
	v_mfma_f32_16x16x32_bf16 v[52:55], v[146:149], v[196:199], v[52:55]
	v_mfma_f32_16x16x32_bf16 v[48:51], v[180:183], v[192:195], v[48:51]
	v_mfma_f32_16x16x32_bf16 v[44:47], v[146:149], v[204:207], v[44:47]
	v_mfma_f32_16x16x32_bf16 v[40:43], v[180:183], v[200:203], v[40:43]
	v_mfma_f32_16x16x32_bf16 v[36:39], v[146:149], v[212:215], v[36:39]
	v_mfma_f32_16x16x32_bf16 v[32:35], v[180:183], v[208:211], v[32:35]
	v_mfma_f32_16x16x32_bf16 v[216:219], v[184:187], v[188:191], v[56:59]
	v_mfma_f32_16x16x32_bf16 v[232:235], v[184:187], v[196:199], v[48:51]
	v_mfma_f32_16x16x32_bf16 v[236:239], v[184:187], v[204:207], v[40:43]
	v_mfma_f32_16x16x32_bf16 v[142:145], v[184:187], v[212:215], v[32:35]
	v_mfma_f32_16x16x32_bf16 v[28:31], v[96:99], v[168:171], v[28:31]
	v_mfma_f32_16x16x32_bf16 v[24:27], v[112:115], v[168:171], v[24:27]
	v_mfma_f32_16x16x32_bf16 v[20:23], v[96:99], v[192:195], v[20:23]
	v_mfma_f32_16x16x32_bf16 v[16:19], v[112:115], v[192:195], v[16:19]
	v_mfma_f32_16x16x32_bf16 v[12:15], v[96:99], v[200:203], v[12:15]
	v_mfma_f32_16x16x32_bf16 v[8:11], v[112:115], v[200:203], v[8:11]
	v_mfma_f32_16x16x32_bf16 v[4:7], v[96:99], v[208:211], v[4:7]
	v_mfma_f32_16x16x32_bf16 v[0:3], v[112:115], v[208:211], v[0:3]
	v_mfma_f32_16x16x32_bf16 v[28:31], v[104:107], v[188:191], v[28:31]
	v_mfma_f32_16x16x32_bf16 v[24:27], v[120:123], v[188:191], v[24:27]
	v_mfma_f32_16x16x32_bf16 v[20:23], v[104:107], v[196:199], v[20:23]
	v_mfma_f32_16x16x32_bf16 v[16:19], v[120:123], v[196:199], v[16:19]
	v_mfma_f32_16x16x32_bf16 v[12:15], v[104:107], v[204:207], v[12:15]
	v_mfma_f32_16x16x32_bf16 v[8:11], v[120:123], v[204:207], v[8:11]
	v_mfma_f32_16x16x32_bf16 v[4:7], v[104:107], v[212:215], v[4:7]
	v_mfma_f32_16x16x32_bf16 v[0:3], v[120:123], v[212:215], v[0:3]
	s_barrier
	ds_read_b128 v[32:35], v163
	ds_read_b128 v[146:149], v163 offset:1024
	ds_read_b128 v[168:171], v163 offset:2048
	ds_read_b128 v[178:181], v163 offset:3072
	ds_read_b128 v[40:43], v161 offset:32768
	ds_read_b128 v[48:51], v161 offset:33792
	ds_read_b128 v[56:59], v160 offset:32768
	ds_read_b128 v[182:185], v160 offset:33792
	ds_read_b128 v[186:189], v159 offset:32768
	ds_read_b128 v[190:193], v159 offset:33792
	ds_read_b128 v[194:197], v158 offset:32768
	ds_read_b128 v[198:201], v158 offset:33792
	s_waitcnt vmcnt(2)
	s_barrier
	s_waitcnt lgkmcnt(0)
	v_mfma_f32_16x16x32_bf16 v[96:99], v[32:35], v[40:43], v[124:127]
	v_mfma_f32_16x16x32_bf16 v[120:123], v[146:149], v[48:51], v[96:99]
	v_mfma_f32_16x16x32_bf16 v[96:99], v[168:171], v[40:43], v[138:141]
	v_mfma_f32_16x16x32_bf16 v[124:127], v[178:181], v[48:51], v[96:99]
	v_mfma_f32_16x16x32_bf16 v[96:99], v[32:35], v[56:59], v[116:119]
	v_mfma_f32_16x16x32_bf16 v[112:115], v[146:149], v[182:185], v[96:99]
	v_mfma_f32_16x16x32_bf16 v[96:99], v[168:171], v[56:59], v[220:223]
	v_mfma_f32_16x16x32_bf16 v[116:119], v[178:181], v[182:185], v[96:99]
	v_mfma_f32_16x16x32_bf16 v[96:99], v[32:35], v[186:189], v[108:111]
	v_mfma_f32_16x16x32_bf16 v[104:107], v[146:149], v[190:193], v[96:99]
	v_mfma_f32_16x16x32_bf16 v[96:99], v[168:171], v[186:189], v[224:227]
	v_mfma_f32_16x16x32_bf16 v[108:111], v[178:181], v[190:193], v[96:99]
	v_mfma_f32_16x16x32_bf16 v[96:99], v[32:35], v[194:197], v[100:103]
	v_mfma_f32_16x16x32_bf16 v[100:103], v[168:171], v[194:197], v[228:231]
	v_mfma_f32_16x16x32_bf16 v[96:99], v[146:149], v[198:201], v[96:99]
	v_mfma_f32_16x16x32_bf16 v[100:103], v[178:181], v[198:201], v[100:103]
	s_barrier
	ds_read_b128 v[138:141], v162
	ds_read_b128 v[202:205], v162 offset:1024
	ds_read_b128 v[206:209], v162 offset:2048
	ds_read_b128 v[210:213], v162 offset:3072
	s_waitcnt vmcnt(0)
	s_barrier
	s_waitcnt lgkmcnt(0)
	v_mfma_f32_16x16x32_bf16 v[92:95], v[138:141], v[40:43], v[92:95]
	v_mfma_f32_16x16x32_bf16 v[40:43], v[206:209], v[40:43], v[88:91]
	v_mfma_f32_16x16x32_bf16 v[88:91], v[210:213], v[48:51], v[40:43]
	v_mfma_f32_16x16x32_bf16 v[40:43], v[138:141], v[56:59], v[84:87]
	v_mfma_f32_16x16x32_bf16 v[84:87], v[202:205], v[182:185], v[40:43]
	v_mfma_f32_16x16x32_bf16 v[40:43], v[206:209], v[56:59], v[80:83]
	v_mfma_f32_16x16x32_bf16 v[80:83], v[210:213], v[182:185], v[40:43]
	v_mfma_f32_16x16x32_bf16 v[40:43], v[138:141], v[186:189], v[76:79]
	v_mfma_f32_16x16x32_bf16 v[76:79], v[202:205], v[190:193], v[40:43]
	v_mfma_f32_16x16x32_bf16 v[40:43], v[206:209], v[186:189], v[72:75]
	v_mfma_f32_16x16x32_bf16 v[72:75], v[210:213], v[190:193], v[40:43]
	v_mfma_f32_16x16x32_bf16 v[40:43], v[138:141], v[194:197], v[68:71]
	v_mfma_f32_16x16x32_bf16 v[68:71], v[202:205], v[198:201], v[40:43]
	v_mfma_f32_16x16x32_bf16 v[40:43], v[206:209], v[194:197], v[64:67]
	v_mfma_f32_16x16x32_bf16 v[92:95], v[202:205], v[48:51], v[92:95]
	v_mfma_f32_16x16x32_bf16 v[64:67], v[210:213], v[198:201], v[40:43]
	s_barrier
	ds_read_b128 v[182:185], v161 offset:49152
	ds_read_b128 v[186:189], v161 offset:50176
	ds_read_b128 v[190:193], v160 offset:49152
	ds_read_b128 v[160:163], v160 offset:50176
	ds_read_b128 v[194:197], v159 offset:49152
	ds_read_b128 v[198:201], v159 offset:50176
	ds_read_b128 v[220:223], v158 offset:49152
	ds_read_b128 v[224:227], v158 offset:50176
	s_barrier
	s_waitcnt lgkmcnt(0)
	v_mfma_f32_16x16x32_bf16 v[40:43], v[32:35], v[182:185], v[60:63]
	v_mfma_f32_16x16x32_bf16 v[56:59], v[146:149], v[186:189], v[40:43]
	v_mfma_f32_16x16x32_bf16 v[40:43], v[168:171], v[182:185], v[216:219]
	v_mfma_f32_16x16x32_bf16 v[60:63], v[178:181], v[186:189], v[40:43]
	v_mfma_f32_16x16x32_bf16 v[40:43], v[32:35], v[190:193], v[52:55]
	v_mfma_f32_16x16x32_bf16 v[48:51], v[146:149], v[160:163], v[40:43]
	v_mfma_f32_16x16x32_bf16 v[40:43], v[168:171], v[190:193], v[232:235]
	v_mfma_f32_16x16x32_bf16 v[52:55], v[178:181], v[160:163], v[40:43]
	v_mfma_f32_16x16x32_bf16 v[40:43], v[32:35], v[194:197], v[44:47]
	v_mfma_f32_16x16x32_bf16 v[44:47], v[168:171], v[194:197], v[236:239]
	v_mfma_f32_16x16x32_bf16 v[32:35], v[32:35], v[220:223], v[36:39]
	v_mfma_f32_16x16x32_bf16 v[36:39], v[168:171], v[220:223], v[142:145]
	v_mfma_f32_16x16x32_bf16 v[40:43], v[146:149], v[198:201], v[40:43]
	v_mfma_f32_16x16x32_bf16 v[44:47], v[178:181], v[198:201], v[44:47]
	v_mfma_f32_16x16x32_bf16 v[32:35], v[146:149], v[224:227], v[32:35]
	v_mfma_f32_16x16x32_bf16 v[36:39], v[178:181], v[224:227], v[36:39]
	v_mfma_f32_16x16x32_bf16 v[28:31], v[138:141], v[182:185], v[28:31]
	v_mfma_f32_16x16x32_bf16 v[24:27], v[206:209], v[182:185], v[24:27]
	v_mfma_f32_16x16x32_bf16 v[20:23], v[138:141], v[190:193], v[20:23]
	v_mfma_f32_16x16x32_bf16 v[16:19], v[206:209], v[190:193], v[16:19]
	v_mfma_f32_16x16x32_bf16 v[12:15], v[138:141], v[194:197], v[12:15]
	v_mfma_f32_16x16x32_bf16 v[8:11], v[206:209], v[194:197], v[8:11]
	v_mfma_f32_16x16x32_bf16 v[4:7], v[138:141], v[220:223], v[4:7]
	v_mfma_f32_16x16x32_bf16 v[0:3], v[206:209], v[220:223], v[0:3]
	v_mfma_f32_16x16x32_bf16 v[28:31], v[202:205], v[186:189], v[28:31]
	v_mfma_f32_16x16x32_bf16 v[24:27], v[210:213], v[186:189], v[24:27]
	v_mfma_f32_16x16x32_bf16 v[20:23], v[202:205], v[160:163], v[20:23]
	v_mfma_f32_16x16x32_bf16 v[16:19], v[210:213], v[160:163], v[16:19]
	v_mfma_f32_16x16x32_bf16 v[12:15], v[202:205], v[198:201], v[12:15]
	v_mfma_f32_16x16x32_bf16 v[8:11], v[210:213], v[198:201], v[8:11]
	v_mfma_f32_16x16x32_bf16 v[4:7], v[202:205], v[224:227], v[4:7]
	v_mfma_f32_16x16x32_bf16 v[0:3], v[210:213], v[224:227], v[0:3]
	s_and_b64 vcc, exec, s[66:67]
	s_barrier
	s_cbranch_vccnz .LBB0_193
	s_mul_hi_i32 s0, s82, 0x66666667
	s_lshr_b32 s1, s0, 31
	s_ashr_i32 s0, s0, 1
	s_add_i32 s0, s0, s1
	v_readlane_b32 s1, v255, 15
	s_add_i32 s1, s0, s1
	s_mul_i32 s0, s0, 5
	s_sub_i32 s0, s82, s0
	v_readlane_b32 s2, v255, 14
	s_add_i32 s2, s0, s2
	s_lshl_b32 s8, s2, 8
	s_ashr_i32 s9, s8, 31
	s_lshl_b32 s0, s1, 8
	s_lshl_b64 s[40:41], s[8:9], 11
	s_add_u32 s40, s20, s40
	s_addc_u32 s41, s21, s41
	v_lshl_add_u64 v[138:139], s[40:41], 0, v[130:131]
	v_readfirstlane_b32 s1, v153
	v_lshl_add_u64 v[138:139], v[138:139], 0, v[132:133]
	s_mov_b32 m0, s1
	v_readfirstlane_b32 s1, v173
	global_load_lds_dwordx4 v[138:139], off
	s_mov_b32 m0, s1
	s_ashr_i32 s1, s0, 31
	v_lshl_add_u64 v[138:139], s[40:41], 0, v[134:135]
	s_lshl_b64 s[40:41], s[0:1], 11
	s_add_u32 s40, s45, s40
	v_lshl_add_u64 v[138:139], v[138:139], 0, v[136:137]
	s_addc_u32 s41, s46, s41
	s_bitset1_b32 s8, 7
	global_load_lds_dwordx4 v[138:139], off
	v_lshl_add_u64 v[138:139], s[40:41], 0, v[130:131]
	v_readfirstlane_b32 s1, v152
	s_ashr_i32 s9, s8, 31
	v_lshl_add_u64 v[138:139], v[138:139], 0, v[132:133]
	s_mov_b32 m0, s1
	s_lshl_b64 s[8:9], s[8:9], 11
	global_load_lds_dwordx4 v[138:139], off
	v_lshl_add_u64 v[138:139], s[40:41], 0, v[134:135]
	v_readfirstlane_b32 s1, v174
	s_add_u32 s8, s20, s8
	v_lshl_add_u64 v[138:139], v[138:139], 0, v[136:137]
	s_mov_b32 m0, s1
	s_addc_u32 s9, s21, s9
	global_load_lds_dwordx4 v[138:139], off
	v_lshl_add_u64 v[138:139], s[8:9], 0, v[130:131]
	v_readfirstlane_b32 s1, v151
	v_lshl_add_u64 v[138:139], v[138:139], 0, v[132:133]
	s_mov_b32 m0, s1
	v_readfirstlane_b32 s1, v175
	s_bitset1_b32 s0, 7
	global_load_lds_dwordx4 v[138:139], off
	s_mov_b32 m0, s1
	s_ashr_i32 s1, s0, 31
	s_lshl_b64 s[0:1], s[0:1], 11
	s_add_u32 s0, s45, s0
	v_lshl_add_u64 v[138:139], s[8:9], 0, v[134:135]
	s_addc_u32 s1, s46, s1
	v_lshl_add_u64 v[138:139], v[138:139], 0, v[136:137]
	v_lshl_add_u64 v[130:131], s[0:1], 0, v[130:131]
	v_readfirstlane_b32 s2, v176
	global_load_lds_dwordx4 v[138:139], off
	v_lshl_add_u64 v[130:131], v[130:131], 0, v[132:133]
	s_mov_b32 m0, s2
	s_nop 0
	global_load_lds_dwordx4 v[130:131], off
	v_lshl_add_u64 v[130:131], s[0:1], 0, v[134:135]
	v_readfirstlane_b32 s0, v177
	v_lshl_add_u64 v[130:131], v[130:131], 0, v[136:137]
	s_mov_b32 m0, s0
	s_nop 0
	global_load_lds_dwordx4 v[130:131], off

.LBB0_1661:
	ds_read_b128 v[180:183], v172
	ds_read_b128 v[184:187], v172 offset:1024
	ds_read_b128 v[188:191], v172 offset:2048
	ds_read_b128 v[192:195], v172 offset:3072
	v_add_u32_e32 v178, 0xc000, v152
	v_lshl_add_u64 v[244:245], s[8:9], 0, v[146:147]
	v_readfirstlane_b32 s1, v178
	v_add_u32_e32 v179, 0xe000, v152
	v_lshl_add_u64 v[224:225], v[244:245], 0, s[12:13]
	s_mov_b32 m0, s1
	v_lshl_add_u64 v[246:247], s[8:9], 0, v[148:149]
	v_readfirstlane_b32 s1, v179
	ds_read_b128 v[174:177], v161
	ds_read_b128 v[196:199], v161 offset:1024
	ds_read_b128 v[200:203], v160
	ds_read_b128 v[204:207], v160 offset:1024
	ds_read_b128 v[208:211], v159
	ds_read_b128 v[212:215], v159 offset:1024
	ds_read_b128 v[216:219], v158
	ds_read_b128 v[220:223], v158 offset:1024
	global_load_lds_dwordx4 v[224:225], off
	v_lshl_add_u64 v[224:225], v[246:247], 0, s[12:13]
	s_mov_b32 m0, s1
	s_nop 0
	global_load_lds_dwordx4 v[224:225], off
	s_waitcnt lgkmcnt(8)
	s_barrier
	s_waitcnt lgkmcnt(0)
	v_mfma_f32_16x16x32_bf16 v[124:127], v[180:183], v[174:177], v[124:127]
	v_mfma_f32_16x16x32_bf16 v[120:123], v[188:191], v[174:177], v[120:123]
	v_mfma_f32_16x16x32_bf16 v[116:119], v[180:183], v[200:203], v[116:119]
	v_mfma_f32_16x16x32_bf16 v[112:115], v[188:191], v[200:203], v[112:115]
	v_mfma_f32_16x16x32_bf16 v[108:111], v[180:183], v[208:211], v[108:111]
	v_mfma_f32_16x16x32_bf16 v[104:107], v[188:191], v[208:211], v[104:107]
	v_mfma_f32_16x16x32_bf16 v[100:103], v[180:183], v[216:219], v[100:103]
	v_mfma_f32_16x16x32_bf16 v[96:99], v[188:191], v[216:219], v[96:99]
	v_mfma_f32_16x16x32_bf16 v[124:127], v[184:187], v[196:199], v[124:127]
	v_mfma_f32_16x16x32_bf16 v[120:123], v[192:195], v[196:199], v[120:123]
	v_mfma_f32_16x16x32_bf16 v[116:119], v[184:187], v[204:207], v[116:119]
	v_mfma_f32_16x16x32_bf16 v[112:115], v[192:195], v[204:207], v[112:115]
	v_mfma_f32_16x16x32_bf16 v[108:111], v[184:187], v[212:215], v[108:111]
	v_mfma_f32_16x16x32_bf16 v[104:107], v[192:195], v[212:215], v[104:107]
	v_mfma_f32_16x16x32_bf16 v[100:103], v[184:187], v[220:223], v[100:103]
	v_mfma_f32_16x16x32_bf16 v[96:99], v[192:195], v[220:223], v[96:99]
	s_barrier
	v_lshl_add_u64 v[248:249], s[8:9], 0, v[142:143]
	v_readfirstlane_b32 s1, v153
	v_add_u32_e32 v173, 0x2000, v153
	v_lshl_add_u64 v[240:241], v[248:249], 0, s[14:15]
	s_mov_b32 m0, s1
	v_lshl_add_u64 v[250:251], s[8:9], 0, v[144:145]
	v_readfirstlane_b32 s1, v173
	ds_read_b128 v[224:227], v168
	ds_read_b128 v[228:231], v168 offset:1024
	ds_read_b128 v[232:235], v168 offset:2048
	ds_read_b128 v[236:239], v168 offset:3072
	global_load_lds_dwordx4 v[240:241], off
	v_lshl_add_u64 v[240:241], v[250:251], 0, s[14:15]
	s_mov_b32 m0, s1
	s_nop 0
	global_load_lds_dwordx4 v[240:241], off
	s_barrier
	s_waitcnt lgkmcnt(0)
	v_mfma_f32_16x16x32_bf16 v[92:95], v[224:227], v[174:177], v[92:95]
	v_mfma_f32_16x16x32_bf16 v[88:91], v[232:235], v[174:177], v[88:91]
	v_mfma_f32_16x16x32_bf16 v[84:87], v[224:227], v[200:203], v[84:87]
	v_mfma_f32_16x16x32_bf16 v[80:83], v[232:235], v[200:203], v[80:83]
	v_mfma_f32_16x16x32_bf16 v[76:79], v[224:227], v[208:211], v[76:79]
	v_mfma_f32_16x16x32_bf16 v[72:75], v[232:235], v[208:211], v[72:75]
	v_mfma_f32_16x16x32_bf16 v[68:71], v[224:227], v[216:219], v[68:71]
	v_mfma_f32_16x16x32_bf16 v[64:67], v[232:235], v[216:219], v[64:67]
	v_mfma_f32_16x16x32_bf16 v[92:95], v[228:231], v[196:199], v[92:95]
	v_mfma_f32_16x16x32_bf16 v[88:91], v[236:239], v[196:199], v[88:91]
	v_mfma_f32_16x16x32_bf16 v[84:87], v[228:231], v[204:207], v[84:87]
	v_mfma_f32_16x16x32_bf16 v[80:83], v[236:239], v[204:207], v[80:83]
	v_mfma_f32_16x16x32_bf16 v[76:79], v[228:231], v[212:215], v[76:79]
	v_mfma_f32_16x16x32_bf16 v[72:75], v[236:239], v[212:215], v[72:75]
	v_mfma_f32_16x16x32_bf16 v[68:71], v[228:231], v[220:223], v[68:71]
	v_mfma_f32_16x16x32_bf16 v[64:67], v[236:239], v[220:223], v[64:67]
	v_readfirstlane_b32 s1, v152
	v_lshl_add_u64 v[174:175], v[244:245], 0, s[16:17]
	s_mov_b32 m0, s1
	s_barrier
	ds_read_b128 v[196:199], v161 offset:16384
	ds_read_b128 v[200:203], v161 offset:17408
	ds_read_b128 v[204:207], v160 offset:16384
	ds_read_b128 v[208:211], v160 offset:17408
	ds_read_b128 v[212:215], v159 offset:16384
	ds_read_b128 v[216:219], v159 offset:17408
	ds_read_b128 v[220:223], v158 offset:16384
	ds_read_b128 v[240:243], v158 offset:17408
	global_load_lds_dwordx4 v[174:175], off
	v_add_u32_e32 v174, 0x2000, v152
	v_lshl_add_u64 v[176:177], v[246:247], 0, s[16:17]
	v_readfirstlane_b32 s1, v174
	s_mov_b32 m0, s1
	s_nop 0
	global_load_lds_dwordx4 v[176:177], off
	s_barrier
	s_waitcnt lgkmcnt(0)
	v_mfma_f32_16x16x32_bf16 v[60:63], v[180:183], v[196:199], v[60:63]
	v_mfma_f32_16x16x32_bf16 v[56:59], v[188:191], v[196:199], v[56:59]
	v_mfma_f32_16x16x32_bf16 v[52:55], v[180:183], v[204:207], v[52:55]
	v_mfma_f32_16x16x32_bf16 v[48:51], v[188:191], v[204:207], v[48:51]
	v_mfma_f32_16x16x32_bf16 v[44:47], v[180:183], v[212:215], v[44:47]
	v_mfma_f32_16x16x32_bf16 v[40:43], v[188:191], v[212:215], v[40:43]
	v_mfma_f32_16x16x32_bf16 v[36:39], v[180:183], v[220:223], v[36:39]
	v_mfma_f32_16x16x32_bf16 v[32:35], v[188:191], v[220:223], v[32:35]
	v_mfma_f32_16x16x32_bf16 v[60:63], v[184:187], v[200:203], v[60:63]
	v_mfma_f32_16x16x32_bf16 v[56:59], v[192:195], v[200:203], v[56:59]
	v_mfma_f32_16x16x32_bf16 v[52:55], v[184:187], v[208:211], v[52:55]
	v_mfma_f32_16x16x32_bf16 v[48:51], v[192:195], v[208:211], v[48:51]
	v_mfma_f32_16x16x32_bf16 v[44:47], v[184:187], v[216:219], v[44:47]
	v_mfma_f32_16x16x32_bf16 v[40:43], v[192:195], v[216:219], v[40:43]
	v_mfma_f32_16x16x32_bf16 v[36:39], v[184:187], v[240:243], v[36:39]
	v_mfma_f32_16x16x32_bf16 v[32:35], v[192:195], v[240:243], v[32:35]
	s_barrier
	v_readfirstlane_b32 s1, v151
	v_add_u32_e32 v175, 0x2000, v151
	v_lshl_add_u64 v[176:177], v[248:249], 0, s[18:19]
	s_mov_b32 m0, s1
	v_readfirstlane_b32 s1, v175
	global_load_lds_dwordx4 v[176:177], off
	v_lshl_add_u64 v[176:177], v[250:251], 0, s[18:19]
	s_mov_b32 m0, s1
	s_nop 0
	global_load_lds_dwordx4 v[176:177], off
	s_waitcnt vmcnt(6)
	s_barrier
	v_mfma_f32_16x16x32_bf16 v[28:31], v[224:227], v[196:199], v[28:31]
	v_mfma_f32_16x16x32_bf16 v[24:27], v[232:235], v[196:199], v[24:27]
	v_mfma_f32_16x16x32_bf16 v[20:23], v[224:227], v[204:207], v[20:23]
	v_mfma_f32_16x16x32_bf16 v[16:19], v[232:235], v[204:207], v[16:19]
	v_mfma_f32_16x16x32_bf16 v[12:15], v[224:227], v[212:215], v[12:15]
	v_mfma_f32_16x16x32_bf16 v[8:11], v[232:235], v[212:215], v[8:11]
	v_mfma_f32_16x16x32_bf16 v[4:7], v[224:227], v[220:223], v[4:7]
	v_mfma_f32_16x16x32_bf16 v[0:3], v[232:235], v[220:223], v[0:3]
	v_mfma_f32_16x16x32_bf16 v[28:31], v[228:231], v[200:203], v[28:31]
	v_mfma_f32_16x16x32_bf16 v[24:27], v[236:239], v[200:203], v[24:27]
	v_mfma_f32_16x16x32_bf16 v[20:23], v[228:231], v[208:211], v[20:23]
	v_mfma_f32_16x16x32_bf16 v[16:19], v[236:239], v[208:211], v[16:19]
	v_mfma_f32_16x16x32_bf16 v[12:15], v[228:231], v[216:219], v[12:15]
	v_mfma_f32_16x16x32_bf16 v[8:11], v[236:239], v[216:219], v[8:11]
	v_mfma_f32_16x16x32_bf16 v[4:7], v[228:231], v[240:243], v[4:7]
	v_mfma_f32_16x16x32_bf16 v[0:3], v[236:239], v[240:243], v[0:3]
	s_barrier
	ds_read_b128 v[180:183], v163
	ds_read_b128 v[184:187], v163 offset:1024
	ds_read_b128 v[188:191], v163 offset:2048
	ds_read_b128 v[192:195], v163 offset:3072
	v_add_u32_e32 v176, 0x4000, v152
	v_add_u32_e32 v177, 0x6000, v152
	v_readfirstlane_b32 s1, v176
	v_lshl_add_u64 v[228:229], v[244:245], 0, s[20:21]
	s_mov_b32 m0, s1
	v_readfirstlane_b32 s1, v177
	ds_read_b128 v[196:199], v161 offset:32768
	ds_read_b128 v[200:203], v161 offset:33792
	ds_read_b128 v[204:207], v160 offset:32768
	ds_read_b128 v[208:211], v160 offset:33792
	ds_read_b128 v[212:215], v159 offset:32768
	ds_read_b128 v[216:219], v159 offset:33792
	ds_read_b128 v[220:223], v158 offset:32768
	ds_read_b128 v[224:227], v158 offset:33792
	global_load_lds_dwordx4 v[228:229], off
	v_lshl_add_u64 v[228:229], v[246:247], 0, s[20:21]
	s_mov_b32 m0, s1
	s_nop 0
	global_load_lds_dwordx4 v[228:229], off
	s_waitcnt lgkmcnt(8)
	s_barrier
	s_waitcnt lgkmcnt(0)
	v_mfma_f32_16x16x32_bf16 v[124:127], v[180:183], v[196:199], v[124:127]
	v_mfma_f32_16x16x32_bf16 v[120:123], v[188:191], v[196:199], v[120:123]
	v_mfma_f32_16x16x32_bf16 v[116:119], v[180:183], v[204:207], v[116:119]
	v_mfma_f32_16x16x32_bf16 v[112:115], v[188:191], v[204:207], v[112:115]
	v_mfma_f32_16x16x32_bf16 v[108:111], v[180:183], v[212:215], v[108:111]
	v_mfma_f32_16x16x32_bf16 v[104:107], v[188:191], v[212:215], v[104:107]
	v_mfma_f32_16x16x32_bf16 v[100:103], v[180:183], v[220:223], v[100:103]
	v_mfma_f32_16x16x32_bf16 v[96:99], v[188:191], v[220:223], v[96:99]
	v_mfma_f32_16x16x32_bf16 v[124:127], v[184:187], v[200:203], v[124:127]
	v_mfma_f32_16x16x32_bf16 v[120:123], v[192:195], v[200:203], v[120:123]
	v_mfma_f32_16x16x32_bf16 v[116:119], v[184:187], v[208:211], v[116:119]
	v_mfma_f32_16x16x32_bf16 v[112:115], v[192:195], v[208:211], v[112:115]
	v_mfma_f32_16x16x32_bf16 v[108:111], v[184:187], v[216:219], v[108:111]
	v_mfma_f32_16x16x32_bf16 v[104:107], v[192:195], v[216:219], v[104:107]
	v_mfma_f32_16x16x32_bf16 v[100:103], v[184:187], v[224:227], v[100:103]
	v_mfma_f32_16x16x32_bf16 v[96:99], v[192:195], v[224:227], v[96:99]
	s_barrier
	v_readfirstlane_b32 s1, v167
	v_add_u32_e32 v254, 0x2000, v167
	v_lshl_add_u64 v[252:253], v[248:249], 0, s[24:25]
	s_mov_b32 m0, s1
	v_readfirstlane_b32 s1, v254
	ds_read_b128 v[228:231], v162
	ds_read_b128 v[232:235], v162 offset:1024
	ds_read_b128 v[236:239], v162 offset:2048
	ds_read_b128 v[240:243], v162 offset:3072
	global_load_lds_dwordx4 v[252:253], off
	v_lshl_add_u64 v[252:253], v[250:251], 0, s[24:25]
	s_mov_b32 m0, s1
	s_nop 0
	global_load_lds_dwordx4 v[252:253], off
	s_barrier
	s_waitcnt lgkmcnt(0)
	v_mfma_f32_16x16x32_bf16 v[92:95], v[228:231], v[196:199], v[92:95]
	v_mfma_f32_16x16x32_bf16 v[88:91], v[236:239], v[196:199], v[88:91]
	v_mfma_f32_16x16x32_bf16 v[84:87], v[228:231], v[204:207], v[84:87]
	v_mfma_f32_16x16x32_bf16 v[80:83], v[236:239], v[204:207], v[80:83]
	v_mfma_f32_16x16x32_bf16 v[76:79], v[228:231], v[212:215], v[76:79]
	v_mfma_f32_16x16x32_bf16 v[72:75], v[236:239], v[212:215], v[72:75]
	v_mfma_f32_16x16x32_bf16 v[68:71], v[228:231], v[220:223], v[68:71]
	v_mfma_f32_16x16x32_bf16 v[64:67], v[236:239], v[220:223], v[64:67]
	v_mfma_f32_16x16x32_bf16 v[92:95], v[232:235], v[200:203], v[92:95]
	v_mfma_f32_16x16x32_bf16 v[88:91], v[240:243], v[200:203], v[88:91]
	v_mfma_f32_16x16x32_bf16 v[84:87], v[232:235], v[208:211], v[84:87]
	v_mfma_f32_16x16x32_bf16 v[80:83], v[240:243], v[208:211], v[80:83]
	v_mfma_f32_16x16x32_bf16 v[76:79], v[232:235], v[216:219], v[76:79]
	v_mfma_f32_16x16x32_bf16 v[72:75], v[240:243], v[216:219], v[72:75]
	v_mfma_f32_16x16x32_bf16 v[68:71], v[232:235], v[224:227], v[68:71]
	v_mfma_f32_16x16x32_bf16 v[64:67], v[240:243], v[224:227], v[64:67]
	v_readfirstlane_b32 s1, v169
	v_lshl_add_u64 v[244:245], v[244:245], 0, s[26:27]
	s_mov_b32 m0, s1
	v_readfirstlane_b32 s1, v170
	s_barrier
	ds_read_b128 v[196:199], v161 offset:49152
	ds_read_b128 v[200:203], v161 offset:50176
	ds_read_b128 v[204:207], v160 offset:49152
	ds_read_b128 v[208:211], v160 offset:50176
	ds_read_b128 v[212:215], v159 offset:49152
	ds_read_b128 v[216:219], v159 offset:50176
	ds_read_b128 v[220:223], v158 offset:49152
	ds_read_b128 v[224:227], v158 offset:50176
	global_load_lds_dwordx4 v[244:245], off
	v_lshl_add_u64 v[244:245], v[246:247], 0, s[26:27]
	s_mov_b32 m0, s1
	s_nop 0
	global_load_lds_dwordx4 v[244:245], off
	s_barrier
	s_waitcnt lgkmcnt(0)
	v_mfma_f32_16x16x32_bf16 v[60:63], v[180:183], v[196:199], v[60:63]
	v_mfma_f32_16x16x32_bf16 v[56:59], v[188:191], v[196:199], v[56:59]
	v_mfma_f32_16x16x32_bf16 v[52:55], v[180:183], v[204:207], v[52:55]
	v_mfma_f32_16x16x32_bf16 v[48:51], v[188:191], v[204:207], v[48:51]
	v_mfma_f32_16x16x32_bf16 v[44:47], v[180:183], v[212:215], v[44:47]
	v_mfma_f32_16x16x32_bf16 v[40:43], v[188:191], v[212:215], v[40:43]
	v_mfma_f32_16x16x32_bf16 v[36:39], v[180:183], v[220:223], v[36:39]
	v_mfma_f32_16x16x32_bf16 v[32:35], v[188:191], v[220:223], v[32:35]
	v_mfma_f32_16x16x32_bf16 v[60:63], v[184:187], v[200:203], v[60:63]
	v_mfma_f32_16x16x32_bf16 v[56:59], v[192:195], v[200:203], v[56:59]
	v_mfma_f32_16x16x32_bf16 v[52:55], v[184:187], v[208:211], v[52:55]
	v_mfma_f32_16x16x32_bf16 v[48:51], v[192:195], v[208:211], v[48:51]
	v_mfma_f32_16x16x32_bf16 v[44:47], v[184:187], v[216:219], v[44:47]
	v_mfma_f32_16x16x32_bf16 v[40:43], v[192:195], v[216:219], v[40:43]
	v_mfma_f32_16x16x32_bf16 v[36:39], v[184:187], v[224:227], v[36:39]
	v_mfma_f32_16x16x32_bf16 v[32:35], v[192:195], v[224:227], v[32:35]
	s_barrier
	v_readfirstlane_b32 s1, v171
	v_add_u32_e32 v182, 0x2000, v171
	v_lshl_add_u64 v[180:181], v[248:249], 0, s[28:29]
	s_mov_b32 m0, s1
	v_readfirstlane_b32 s1, v182
	global_load_lds_dwordx4 v[180:181], off
	v_lshl_add_u64 v[180:181], v[250:251], 0, s[28:29]
	s_mov_b32 m0, s1
	s_nop 0
	global_load_lds_dwordx4 v[180:181], off
	s_add_i32 s0, s0, 2
	v_lshl_add_u64 v[142:143], v[142:143], 0, s[30:31]
	v_lshl_add_u64 v[144:145], v[144:145], 0, s[30:31]
	v_lshl_add_u64 v[146:147], v[146:147], 0, s[30:31]
	s_cmp_lt_u32 s0, 12
	v_lshl_add_u64 v[148:149], v[148:149], 0, s[30:31]
	s_waitcnt vmcnt(6)
	s_barrier
	v_mfma_f32_16x16x32_bf16 v[28:31], v[228:231], v[196:199], v[28:31]
	v_mfma_f32_16x16x32_bf16 v[24:27], v[236:239], v[196:199], v[24:27]
	v_mfma_f32_16x16x32_bf16 v[20:23], v[228:231], v[204:207], v[20:23]
	v_mfma_f32_16x16x32_bf16 v[16:19], v[236:239], v[204:207], v[16:19]
	v_mfma_f32_16x16x32_bf16 v[12:15], v[228:231], v[212:215], v[12:15]
	v_mfma_f32_16x16x32_bf16 v[8:11], v[236:239], v[212:215], v[8:11]
	v_mfma_f32_16x16x32_bf16 v[4:7], v[228:231], v[220:223], v[4:7]
	v_mfma_f32_16x16x32_bf16 v[0:3], v[236:239], v[220:223], v[0:3]
	v_mfma_f32_16x16x32_bf16 v[28:31], v[232:235], v[200:203], v[28:31]
	v_mfma_f32_16x16x32_bf16 v[24:27], v[240:243], v[200:203], v[24:27]
	v_mfma_f32_16x16x32_bf16 v[20:23], v[232:235], v[208:211], v[20:23]
	v_mfma_f32_16x16x32_bf16 v[16:19], v[240:243], v[208:211], v[16:19]
	v_mfma_f32_16x16x32_bf16 v[12:15], v[232:235], v[216:219], v[12:15]
	v_mfma_f32_16x16x32_bf16 v[8:11], v[240:243], v[216:219], v[8:11]
	v_mfma_f32_16x16x32_bf16 v[4:7], v[232:235], v[224:227], v[4:7]
	v_mfma_f32_16x16x32_bf16 v[0:3], v[240:243], v[224:227], v[0:3]
	s_barrier
	s_cbranch_scc1 .LBB0_1661
	s_or_b32 s0, s36, 0x80
	s_ashr_i32 s1, s0, 31
	s_lshl_b64 s[0:1], s[0:1], 11
	s_add_u32 s0, s39, s0
	s_addc_u32 s1, s46, s1
	v_lshl_add_u64 v[170:171], s[0:1], 0, v[130:131]
	v_lshl_add_u64 v[138:139], v[138:139], 1, v[170:171]
	v_readfirstlane_b32 s2, v178
	v_lshl_add_u64 v[138:139], v[138:139], 0, s[34:35]
	s_mov_b32 m0, s2
	ds_read_b128 v[142:145], v172
	ds_read_b128 v[146:149], v172 offset:1024
	ds_read_b128 v[180:183], v172 offset:2048
	ds_read_b128 v[184:187], v172 offset:3072
	ds_read_b128 v[188:191], v161
	ds_read_b128 v[192:195], v161 offset:1024
	ds_read_b128 v[196:199], v160
	ds_read_b128 v[200:203], v160 offset:1024
	ds_read_b128 v[204:207], v159
	ds_read_b128 v[208:211], v159 offset:1024
	ds_read_b128 v[212:215], v158
	ds_read_b128 v[216:219], v158 offset:1024
	global_load_lds_dwordx4 v[138:139], off
	v_lshl_add_u64 v[138:139], s[0:1], 0, v[134:135]
	v_lshl_add_u64 v[138:139], v[140:141], 1, v[138:139]
	v_readfirstlane_b32 s0, v179
	v_lshl_add_u64 v[138:139], v[138:139], 0, s[34:35]
	s_mov_b32 m0, s0
	v_readlane_b32 s0, v255, 11
	global_load_lds_dwordx4 v[138:139], off
	s_add_i32 s70, s70, s0
	s_barrier
	s_waitcnt lgkmcnt(0)
	s_cmpk_gt_i32 s70, 0x7f
	s_cselect_b64 s[58:59], -1, 0
	s_waitcnt lgkmcnt(0)
	v_mfma_f32_16x16x32_bf16 v[124:127], v[142:145], v[188:191], v[124:127]
	v_mfma_f32_16x16x32_bf16 v[120:123], v[180:183], v[188:191], v[120:123]
	v_mfma_f32_16x16x32_bf16 v[116:119], v[142:145], v[196:199], v[116:119]
	v_mfma_f32_16x16x32_bf16 v[112:115], v[180:183], v[196:199], v[112:115]
	v_mfma_f32_16x16x32_bf16 v[108:111], v[142:145], v[204:207], v[108:111]
	v_mfma_f32_16x16x32_bf16 v[104:107], v[180:183], v[204:207], v[104:107]
	v_mfma_f32_16x16x32_bf16 v[100:103], v[142:145], v[212:215], v[100:103]
	v_mfma_f32_16x16x32_bf16 v[96:99], v[180:183], v[212:215], v[96:99]
	v_mfma_f32_16x16x32_bf16 v[124:127], v[146:149], v[192:195], v[124:127]
	v_mfma_f32_16x16x32_bf16 v[120:123], v[184:187], v[192:195], v[120:123]
	v_mfma_f32_16x16x32_bf16 v[116:119], v[146:149], v[200:203], v[116:119]
	v_mfma_f32_16x16x32_bf16 v[112:115], v[184:187], v[200:203], v[112:115]
	v_mfma_f32_16x16x32_bf16 v[108:111], v[146:149], v[208:211], v[108:111]
	v_mfma_f32_16x16x32_bf16 v[104:107], v[184:187], v[208:211], v[104:107]
	v_mfma_f32_16x16x32_bf16 v[100:103], v[146:149], v[216:219], v[100:103]
	v_mfma_f32_16x16x32_bf16 v[96:99], v[184:187], v[216:219], v[96:99]
	s_barrier
	ds_read_b128 v[138:141], v168
	ds_read_b128 v[220:223], v168 offset:1024
	ds_read_b128 v[224:227], v168 offset:2048
	ds_read_b128 v[168:171], v168 offset:3072
	s_barrier
	s_waitcnt lgkmcnt(0)
	v_mfma_f32_16x16x32_bf16 v[92:95], v[138:141], v[188:191], v[92:95]
	v_mfma_f32_16x16x32_bf16 v[88:91], v[224:227], v[188:191], v[88:91]
	v_mfma_f32_16x16x32_bf16 v[84:87], v[138:141], v[196:199], v[84:87]
	v_mfma_f32_16x16x32_bf16 v[80:83], v[224:227], v[196:199], v[80:83]
	v_mfma_f32_16x16x32_bf16 v[76:79], v[138:141], v[204:207], v[76:79]
	v_mfma_f32_16x16x32_bf16 v[72:75], v[224:227], v[204:207], v[72:75]
	v_mfma_f32_16x16x32_bf16 v[68:71], v[138:141], v[212:215], v[68:71]
	v_mfma_f32_16x16x32_bf16 v[64:67], v[224:227], v[212:215], v[64:67]
	v_mfma_f32_16x16x32_bf16 v[92:95], v[220:223], v[192:195], v[92:95]
	v_mfma_f32_16x16x32_bf16 v[88:91], v[168:171], v[192:195], v[88:91]
	v_mfma_f32_16x16x32_bf16 v[84:87], v[220:223], v[200:203], v[84:87]
	v_mfma_f32_16x16x32_bf16 v[80:83], v[168:171], v[200:203], v[80:83]
	v_mfma_f32_16x16x32_bf16 v[76:79], v[220:223], v[208:211], v[76:79]
	v_mfma_f32_16x16x32_bf16 v[72:75], v[168:171], v[208:211], v[72:75]
	v_mfma_f32_16x16x32_bf16 v[68:71], v[220:223], v[216:219], v[68:71]
	v_mfma_f32_16x16x32_bf16 v[64:67], v[168:171], v[216:219], v[64:67]
	s_barrier
	ds_read_b128 v[188:191], v161 offset:16384
	ds_read_b128 v[192:195], v161 offset:17408
	ds_read_b128 v[196:199], v160 offset:16384
	ds_read_b128 v[200:203], v160 offset:17408
	ds_read_b128 v[204:207], v159 offset:16384
	ds_read_b128 v[208:211], v159 offset:17408
	ds_read_b128 v[212:215], v158 offset:16384
	ds_read_b128 v[216:219], v158 offset:17408
	s_waitcnt vmcnt(4)
	s_barrier
	s_waitcnt lgkmcnt(0)
	v_mfma_f32_16x16x32_bf16 v[60:63], v[142:145], v[188:191], v[60:63]
	v_mfma_f32_16x16x32_bf16 v[56:59], v[180:183], v[188:191], v[56:59]
	v_mfma_f32_16x16x32_bf16 v[52:55], v[142:145], v[196:199], v[52:55]
	v_mfma_f32_16x16x32_bf16 v[48:51], v[180:183], v[196:199], v[48:51]
	v_mfma_f32_16x16x32_bf16 v[44:47], v[142:145], v[204:207], v[44:47]
	v_mfma_f32_16x16x32_bf16 v[40:43], v[180:183], v[204:207], v[40:43]
	v_mfma_f32_16x16x32_bf16 v[36:39], v[142:145], v[212:215], v[36:39]
	v_mfma_f32_16x16x32_bf16 v[32:35], v[180:183], v[212:215], v[32:35]
	v_mfma_f32_16x16x32_bf16 v[60:63], v[146:149], v[192:195], v[60:63]
	v_mfma_f32_16x16x32_bf16 v[56:59], v[184:187], v[192:195], v[56:59]
	v_mfma_f32_16x16x32_bf16 v[52:55], v[146:149], v[200:203], v[52:55]
	v_mfma_f32_16x16x32_bf16 v[48:51], v[184:187], v[200:203], v[48:51]
	v_mfma_f32_16x16x32_bf16 v[44:47], v[146:149], v[208:211], v[44:47]
	v_mfma_f32_16x16x32_bf16 v[40:43], v[184:187], v[208:211], v[40:43]
	v_mfma_f32_16x16x32_bf16 v[36:39], v[146:149], v[216:219], v[36:39]
	v_mfma_f32_16x16x32_bf16 v[32:35], v[184:187], v[216:219], v[32:35]
	v_mfma_f32_16x16x32_bf16 v[28:31], v[138:141], v[188:191], v[28:31]
	v_mfma_f32_16x16x32_bf16 v[24:27], v[224:227], v[188:191], v[24:27]
	v_mfma_f32_16x16x32_bf16 v[20:23], v[138:141], v[196:199], v[20:23]
	v_mfma_f32_16x16x32_bf16 v[16:19], v[224:227], v[196:199], v[16:19]
	v_mfma_f32_16x16x32_bf16 v[12:15], v[138:141], v[204:207], v[12:15]
	v_mfma_f32_16x16x32_bf16 v[8:11], v[224:227], v[204:207], v[8:11]
	v_mfma_f32_16x16x32_bf16 v[4:7], v[138:141], v[212:215], v[4:7]
	v_mfma_f32_16x16x32_bf16 v[0:3], v[224:227], v[212:215], v[0:3]
	v_mfma_f32_16x16x32_bf16 v[28:31], v[220:223], v[192:195], v[28:31]
	v_mfma_f32_16x16x32_bf16 v[24:27], v[168:171], v[192:195], v[24:27]
	v_mfma_f32_16x16x32_bf16 v[20:23], v[220:223], v[200:203], v[20:23]
	v_mfma_f32_16x16x32_bf16 v[16:19], v[168:171], v[200:203], v[16:19]
	v_mfma_f32_16x16x32_bf16 v[12:15], v[220:223], v[208:211], v[12:15]
	v_mfma_f32_16x16x32_bf16 v[8:11], v[168:171], v[208:211], v[8:11]
	v_mfma_f32_16x16x32_bf16 v[4:7], v[220:223], v[216:219], v[4:7]
	v_mfma_f32_16x16x32_bf16 v[0:3], v[168:171], v[216:219], v[0:3]
	s_barrier
	ds_read_b128 v[138:141], v163
	ds_read_b128 v[142:145], v163 offset:1024
	ds_read_b128 v[146:149], v163 offset:2048
	ds_read_b128 v[168:171], v163 offset:3072
	ds_read_b128 v[178:181], v161 offset:32768
	ds_read_b128 v[182:185], v161 offset:33792
	ds_read_b128 v[186:189], v160 offset:32768
	ds_read_b128 v[190:193], v160 offset:33792
	ds_read_b128 v[194:197], v159 offset:32768
	ds_read_b128 v[198:201], v159 offset:33792
	ds_read_b128 v[202:205], v158 offset:32768
	ds_read_b128 v[206:209], v158 offset:33792
	s_waitcnt vmcnt(2)
	s_barrier
	s_waitcnt lgkmcnt(0)
	v_mfma_f32_16x16x32_bf16 v[124:127], v[138:141], v[178:181], v[124:127]
	v_mfma_f32_16x16x32_bf16 v[120:123], v[146:149], v[178:181], v[120:123]
	v_mfma_f32_16x16x32_bf16 v[116:119], v[138:141], v[186:189], v[116:119]
	v_mfma_f32_16x16x32_bf16 v[112:115], v[146:149], v[186:189], v[112:115]
	v_mfma_f32_16x16x32_bf16 v[108:111], v[138:141], v[194:197], v[108:111]
	v_mfma_f32_16x16x32_bf16 v[104:107], v[146:149], v[194:197], v[104:107]
	v_mfma_f32_16x16x32_bf16 v[100:103], v[138:141], v[202:205], v[100:103]
	v_mfma_f32_16x16x32_bf16 v[96:99], v[146:149], v[202:205], v[96:99]
	v_mfma_f32_16x16x32_bf16 v[124:127], v[142:145], v[182:185], v[124:127]
	v_mfma_f32_16x16x32_bf16 v[120:123], v[168:171], v[182:185], v[120:123]
	v_mfma_f32_16x16x32_bf16 v[116:119], v[142:145], v[190:193], v[116:119]
	v_mfma_f32_16x16x32_bf16 v[112:115], v[168:171], v[190:193], v[112:115]
	v_mfma_f32_16x16x32_bf16 v[108:111], v[142:145], v[198:201], v[108:111]
	v_mfma_f32_16x16x32_bf16 v[104:107], v[168:171], v[198:201], v[104:107]
	v_mfma_f32_16x16x32_bf16 v[100:103], v[142:145], v[206:209], v[100:103]
	v_mfma_f32_16x16x32_bf16 v[96:99], v[168:171], v[206:209], v[96:99]
	s_barrier
	ds_read_b128 v[210:213], v162
	ds_read_b128 v[214:217], v162 offset:1024
	ds_read_b128 v[218:221], v162 offset:2048
	ds_read_b128 v[222:225], v162 offset:3072
	s_waitcnt vmcnt(0)
	s_barrier
	s_waitcnt lgkmcnt(0)
	v_mfma_f32_16x16x32_bf16 v[92:95], v[210:213], v[178:181], v[92:95]
	v_mfma_f32_16x16x32_bf16 v[88:91], v[218:221], v[178:181], v[88:91]
	v_mfma_f32_16x16x32_bf16 v[84:87], v[210:213], v[186:189], v[84:87]
	v_mfma_f32_16x16x32_bf16 v[80:83], v[218:221], v[186:189], v[80:83]
	v_mfma_f32_16x16x32_bf16 v[76:79], v[210:213], v[194:197], v[76:79]
	v_mfma_f32_16x16x32_bf16 v[72:75], v[218:221], v[194:197], v[72:75]
	v_mfma_f32_16x16x32_bf16 v[68:71], v[210:213], v[202:205], v[68:71]
	v_mfma_f32_16x16x32_bf16 v[64:67], v[218:221], v[202:205], v[64:67]
	v_mfma_f32_16x16x32_bf16 v[92:95], v[214:217], v[182:185], v[92:95]
	v_mfma_f32_16x16x32_bf16 v[88:91], v[222:225], v[182:185], v[88:91]
	v_mfma_f32_16x16x32_bf16 v[84:87], v[214:217], v[190:193], v[84:87]
	v_mfma_f32_16x16x32_bf16 v[80:83], v[222:225], v[190:193], v[80:83]
	v_mfma_f32_16x16x32_bf16 v[76:79], v[214:217], v[198:201], v[76:79]
	v_mfma_f32_16x16x32_bf16 v[72:75], v[222:225], v[198:201], v[72:75]
	v_mfma_f32_16x16x32_bf16 v[68:71], v[214:217], v[206:209], v[68:71]
	v_mfma_f32_16x16x32_bf16 v[64:67], v[222:225], v[206:209], v[64:67]
	s_barrier
	ds_read_b128 v[178:181], v161 offset:49152
	ds_read_b128 v[182:185], v161 offset:50176
	ds_read_b128 v[186:189], v160 offset:49152
	ds_read_b128 v[160:163], v160 offset:50176
	ds_read_b128 v[190:193], v159 offset:49152
	ds_read_b128 v[194:197], v159 offset:50176
	ds_read_b128 v[198:201], v158 offset:49152
	ds_read_b128 v[202:205], v158 offset:50176
	s_barrier
	s_waitcnt lgkmcnt(0)
	v_mfma_f32_16x16x32_bf16 v[60:63], v[138:141], v[178:181], v[60:63]
	v_mfma_f32_16x16x32_bf16 v[56:59], v[146:149], v[178:181], v[56:59]
	v_mfma_f32_16x16x32_bf16 v[52:55], v[138:141], v[186:189], v[52:55]
	v_mfma_f32_16x16x32_bf16 v[48:51], v[146:149], v[186:189], v[48:51]
	v_mfma_f32_16x16x32_bf16 v[44:47], v[138:141], v[190:193], v[44:47]
	v_mfma_f32_16x16x32_bf16 v[40:43], v[146:149], v[190:193], v[40:43]
	v_mfma_f32_16x16x32_bf16 v[36:39], v[138:141], v[198:201], v[36:39]
	v_mfma_f32_16x16x32_bf16 v[32:35], v[146:149], v[198:201], v[32:35]
	v_mfma_f32_16x16x32_bf16 v[60:63], v[142:145], v[182:185], v[60:63]
	v_mfma_f32_16x16x32_bf16 v[56:59], v[168:171], v[182:185], v[56:59]
	v_mfma_f32_16x16x32_bf16 v[52:55], v[142:145], v[160:163], v[52:55]
	v_mfma_f32_16x16x32_bf16 v[48:51], v[168:171], v[160:163], v[48:51]
	v_mfma_f32_16x16x32_bf16 v[44:47], v[142:145], v[194:197], v[44:47]
	v_mfma_f32_16x16x32_bf16 v[40:43], v[168:171], v[194:197], v[40:43]
	v_mfma_f32_16x16x32_bf16 v[36:39], v[142:145], v[202:205], v[36:39]
	v_mfma_f32_16x16x32_bf16 v[32:35], v[168:171], v[202:205], v[32:35]
	v_mfma_f32_16x16x32_bf16 v[28:31], v[210:213], v[178:181], v[28:31]
	v_mfma_f32_16x16x32_bf16 v[24:27], v[218:221], v[178:181], v[24:27]
	v_mfma_f32_16x16x32_bf16 v[20:23], v[210:213], v[186:189], v[20:23]
	v_mfma_f32_16x16x32_bf16 v[16:19], v[218:221], v[186:189], v[16:19]
	v_mfma_f32_16x16x32_bf16 v[12:15], v[210:213], v[190:193], v[12:15]
	v_mfma_f32_16x16x32_bf16 v[8:11], v[218:221], v[190:193], v[8:11]
	v_mfma_f32_16x16x32_bf16 v[4:7], v[210:213], v[198:201], v[4:7]
	v_mfma_f32_16x16x32_bf16 v[0:3], v[218:221], v[198:201], v[0:3]
	v_mfma_f32_16x16x32_bf16 v[28:31], v[214:217], v[182:185], v[28:31]
	v_mfma_f32_16x16x32_bf16 v[24:27], v[222:225], v[182:185], v[24:27]
	v_mfma_f32_16x16x32_bf16 v[20:23], v[214:217], v[160:163], v[20:23]
	v_mfma_f32_16x16x32_bf16 v[16:19], v[222:225], v[160:163], v[16:19]
	v_mfma_f32_16x16x32_bf16 v[12:15], v[214:217], v[194:197], v[12:15]
	v_mfma_f32_16x16x32_bf16 v[8:11], v[222:225], v[194:197], v[8:11]
	v_mfma_f32_16x16x32_bf16 v[4:7], v[214:217], v[202:205], v[4:7]
	v_mfma_f32_16x16x32_bf16 v[0:3], v[222:225], v[202:205], v[0:3]
	s_and_b64 vcc, exec, s[58:59]
	s_barrier
	s_cbranch_vccnz .LBB0_1664
	s_lshr_b32 s0, s70, 2
	s_and_b32 s1, s70, 3
	s_add_i32 s0, s0, s56
	s_or_b32 s1, s1, s53
	s_lshl_b32 s0, s0, 8
	s_lshl_b32 s1, s1, 19
	s_add_u32 s40, s57, s1
	s_addc_u32 s41, s62, 0
	v_lshl_add_u64 v[138:139], s[40:41], 0, v[130:131]
	v_readfirstlane_b32 s1, v153
	v_lshl_add_u64 v[138:139], v[138:139], 0, v[132:133]
	s_mov_b32 m0, s1
	v_readfirstlane_b32 s1, v173
	global_load_lds_dwordx4 v[138:139], off
	s_mov_b32 m0, s1
	s_ashr_i32 s1, s0, 31
	s_lshl_b64 s[42:43], s[0:1], 11
	v_lshl_add_u64 v[138:139], s[40:41], 0, v[134:135]
	s_add_u32 s42, s39, s42
	v_lshl_add_u64 v[138:139], v[138:139], 0, v[136:137]
	s_addc_u32 s43, s46, s43
	global_load_lds_dwordx4 v[138:139], off
	v_lshl_add_u64 v[138:139], s[42:43], 0, v[130:131]
	v_readfirstlane_b32 s1, v152
	v_lshl_add_u64 v[138:139], v[138:139], 0, v[132:133]
	s_mov_b32 m0, s1
	v_readfirstlane_b32 s1, v174
	global_load_lds_dwordx4 v[138:139], off
	v_lshl_add_u64 v[138:139], s[42:43], 0, v[134:135]
	s_add_u32 s40, s40, 0x40000
	v_lshl_add_u64 v[138:139], v[138:139], 0, v[136:137]
	s_mov_b32 m0, s1
	s_addc_u32 s41, s41, 0
	global_load_lds_dwordx4 v[138:139], off
	v_lshl_add_u64 v[138:139], s[40:41], 0, v[130:131]
	v_readfirstlane_b32 s1, v151
	v_lshl_add_u64 v[138:139], v[138:139], 0, v[132:133]
	s_mov_b32 m0, s1
	v_readfirstlane_b32 s1, v175
	s_bitset1_b32 s0, 7
	global_load_lds_dwordx4 v[138:139], off
	s_mov_b32 m0, s1
	s_ashr_i32 s1, s0, 31
	s_lshl_b64 s[0:1], s[0:1], 11
	s_add_u32 s0, s39, s0
	v_lshl_add_u64 v[138:139], s[40:41], 0, v[134:135]
	s_addc_u32 s1, s46, s1
	v_lshl_add_u64 v[138:139], v[138:139], 0, v[136:137]
	v_lshl_add_u64 v[130:131], s[0:1], 0, v[130:131]
	v_readfirstlane_b32 s2, v176
	global_load_lds_dwordx4 v[138:139], off
	v_lshl_add_u64 v[130:131], v[130:131], 0, v[132:133]
	s_mov_b32 m0, s2
	s_nop 0
	global_load_lds_dwordx4 v[130:131], off
	v_lshl_add_u64 v[130:131], s[0:1], 0, v[134:135]
	v_readfirstlane_b32 s0, v177
	v_lshl_add_u64 v[130:131], v[130:131], 0, v[136:137]
	s_mov_b32 m0, s0
	s_nop 0
	global_load_lds_dwordx4 v[130:131], off

.LBB0_1720:
	ds_read_b128 v[176:179], v173
	ds_read_b128 v[180:183], v173 offset:1024
	ds_read_b128 v[184:187], v173 offset:2048
	ds_read_b128 v[188:191], v173 offset:3072
	v_add_u32_e32 v174, 0xc000, v157
	v_lshl_add_u64 v[240:241], s[6:7], 0, v[142:143]
	v_readfirstlane_b32 s2, v174
	v_add_u32_e32 v175, 0xe000, v157
	v_lshl_add_u64 v[224:225], v[240:241], 0, s[14:15]
	s_mov_b32 m0, s2
	v_lshl_add_u64 v[242:243], s[6:7], 0, v[144:145]
	v_readfirstlane_b32 s2, v175
	ds_read_b128 v[192:195], v155
	ds_read_b128 v[196:199], v155 offset:1024
	ds_read_b128 v[200:203], v154
	ds_read_b128 v[204:207], v154 offset:1024
	ds_read_b128 v[208:211], v153
	ds_read_b128 v[212:215], v153 offset:1024
	ds_read_b128 v[216:219], v152
	ds_read_b128 v[220:223], v152 offset:1024
	global_load_lds_dwordx4 v[224:225], off
	v_lshl_add_u64 v[224:225], v[242:243], 0, s[14:15]
	s_mov_b32 m0, s2
	s_nop 0
	global_load_lds_dwordx4 v[224:225], off
	s_waitcnt lgkmcnt(8)
	s_barrier
	s_waitcnt lgkmcnt(0)
	v_mfma_f32_16x16x32_bf16 v[124:127], v[176:179], v[192:195], v[124:127]
	v_mfma_f32_16x16x32_bf16 v[120:123], v[184:187], v[192:195], v[120:123]
	v_mfma_f32_16x16x32_bf16 v[116:119], v[176:179], v[200:203], v[116:119]
	v_mfma_f32_16x16x32_bf16 v[112:115], v[184:187], v[200:203], v[112:115]
	v_mfma_f32_16x16x32_bf16 v[108:111], v[176:179], v[208:211], v[108:111]
	v_mfma_f32_16x16x32_bf16 v[104:107], v[184:187], v[208:211], v[104:107]
	v_mfma_f32_16x16x32_bf16 v[100:103], v[176:179], v[216:219], v[100:103]
	v_mfma_f32_16x16x32_bf16 v[96:99], v[184:187], v[216:219], v[96:99]
	v_mfma_f32_16x16x32_bf16 v[124:127], v[180:183], v[196:199], v[124:127]
	v_mfma_f32_16x16x32_bf16 v[120:123], v[188:191], v[196:199], v[120:123]
	v_mfma_f32_16x16x32_bf16 v[116:119], v[180:183], v[204:207], v[116:119]
	v_mfma_f32_16x16x32_bf16 v[112:115], v[188:191], v[204:207], v[112:115]
	v_mfma_f32_16x16x32_bf16 v[108:111], v[180:183], v[212:215], v[108:111]
	v_mfma_f32_16x16x32_bf16 v[104:107], v[188:191], v[212:215], v[104:107]
	v_mfma_f32_16x16x32_bf16 v[100:103], v[180:183], v[220:223], v[100:103]
	v_mfma_f32_16x16x32_bf16 v[96:99], v[188:191], v[220:223], v[96:99]
	s_barrier
	v_lshl_add_u64 v[244:245], s[6:7], 0, v[138:139]
	v_readfirstlane_b32 s2, v151
	v_lshl_add_u64 v[246:247], v[244:245], 0, s[16:17]
	s_mov_b32 m0, s2
	v_add_u32_e32 v250, 0x2000, v151
	ds_read_b128 v[224:227], v170
	ds_read_b128 v[228:231], v170 offset:1024
	ds_read_b128 v[232:235], v170 offset:2048
	ds_read_b128 v[236:239], v170 offset:3072
	global_load_lds_dwordx4 v[246:247], off
	v_lshl_add_u64 v[246:247], s[6:7], 0, v[140:141]
	v_readfirstlane_b32 s2, v250
	v_lshl_add_u64 v[248:249], v[246:247], 0, s[16:17]
	s_mov_b32 m0, s2
	s_nop 0
	global_load_lds_dwordx4 v[248:249], off
	s_barrier
	s_waitcnt lgkmcnt(0)
	v_mfma_f32_16x16x32_bf16 v[92:95], v[224:227], v[192:195], v[92:95]
	v_mfma_f32_16x16x32_bf16 v[88:91], v[232:235], v[192:195], v[88:91]
	v_mfma_f32_16x16x32_bf16 v[84:87], v[224:227], v[200:203], v[84:87]
	v_mfma_f32_16x16x32_bf16 v[80:83], v[232:235], v[200:203], v[80:83]
	v_mfma_f32_16x16x32_bf16 v[76:79], v[224:227], v[208:211], v[76:79]
	v_mfma_f32_16x16x32_bf16 v[72:75], v[232:235], v[208:211], v[72:75]
	v_mfma_f32_16x16x32_bf16 v[68:71], v[224:227], v[216:219], v[68:71]
	v_mfma_f32_16x16x32_bf16 v[64:67], v[232:235], v[216:219], v[64:67]
	v_mfma_f32_16x16x32_bf16 v[92:95], v[228:231], v[196:199], v[92:95]
	v_mfma_f32_16x16x32_bf16 v[88:91], v[236:239], v[196:199], v[88:91]
	v_mfma_f32_16x16x32_bf16 v[84:87], v[228:231], v[204:207], v[84:87]
	v_mfma_f32_16x16x32_bf16 v[80:83], v[236:239], v[204:207], v[80:83]
	v_mfma_f32_16x16x32_bf16 v[76:79], v[228:231], v[212:215], v[76:79]
	v_mfma_f32_16x16x32_bf16 v[72:75], v[236:239], v[212:215], v[72:75]
	v_mfma_f32_16x16x32_bf16 v[68:71], v[228:231], v[220:223], v[68:71]
	v_mfma_f32_16x16x32_bf16 v[64:67], v[236:239], v[220:223], v[64:67]
	v_readfirstlane_b32 s2, v157
	v_lshl_add_u64 v[248:249], v[240:241], 0, s[18:19]
	s_mov_b32 m0, s2
	v_readfirstlane_b32 s2, v158
	s_barrier
	ds_read_b128 v[192:195], v155 offset:16384
	ds_read_b128 v[196:199], v155 offset:17408
	ds_read_b128 v[200:203], v154 offset:16384
	ds_read_b128 v[204:207], v154 offset:17408
	ds_read_b128 v[208:211], v153 offset:16384
	ds_read_b128 v[212:215], v153 offset:17408
	ds_read_b128 v[216:219], v152 offset:16384
	ds_read_b128 v[220:223], v152 offset:17408
	global_load_lds_dwordx4 v[248:249], off
	v_lshl_add_u64 v[248:249], v[242:243], 0, s[18:19]
	s_mov_b32 m0, s2
	s_nop 0
	global_load_lds_dwordx4 v[248:249], off
	s_barrier
	s_waitcnt lgkmcnt(0)
	v_mfma_f32_16x16x32_bf16 v[60:63], v[176:179], v[192:195], v[60:63]
	v_mfma_f32_16x16x32_bf16 v[56:59], v[184:187], v[192:195], v[56:59]
	v_mfma_f32_16x16x32_bf16 v[52:55], v[176:179], v[200:203], v[52:55]
	v_mfma_f32_16x16x32_bf16 v[48:51], v[184:187], v[200:203], v[48:51]
	v_mfma_f32_16x16x32_bf16 v[44:47], v[176:179], v[208:211], v[44:47]
	v_mfma_f32_16x16x32_bf16 v[40:43], v[184:187], v[208:211], v[40:43]
	v_mfma_f32_16x16x32_bf16 v[36:39], v[176:179], v[216:219], v[36:39]
	v_mfma_f32_16x16x32_bf16 v[32:35], v[184:187], v[216:219], v[32:35]
	v_mfma_f32_16x16x32_bf16 v[60:63], v[180:183], v[196:199], v[60:63]
	v_mfma_f32_16x16x32_bf16 v[56:59], v[188:191], v[196:199], v[56:59]
	v_mfma_f32_16x16x32_bf16 v[52:55], v[180:183], v[204:207], v[52:55]
	v_mfma_f32_16x16x32_bf16 v[48:51], v[188:191], v[204:207], v[48:51]
	v_mfma_f32_16x16x32_bf16 v[44:47], v[180:183], v[212:215], v[44:47]
	v_mfma_f32_16x16x32_bf16 v[40:43], v[188:191], v[212:215], v[40:43]
	v_mfma_f32_16x16x32_bf16 v[36:39], v[180:183], v[220:223], v[36:39]
	v_mfma_f32_16x16x32_bf16 v[32:35], v[188:191], v[220:223], v[32:35]
	s_barrier
	v_readfirstlane_b32 s2, v159
	v_add_u32_e32 v178, 0x2000, v159
	v_lshl_add_u64 v[176:177], v[244:245], 0, s[20:21]
	s_mov_b32 m0, s2
	v_readfirstlane_b32 s2, v178
	global_load_lds_dwordx4 v[176:177], off
	v_lshl_add_u64 v[176:177], v[246:247], 0, s[20:21]
	s_mov_b32 m0, s2
	s_nop 0
	global_load_lds_dwordx4 v[176:177], off
	s_waitcnt vmcnt(6)
	s_barrier
	v_mfma_f32_16x16x32_bf16 v[28:31], v[224:227], v[192:195], v[28:31]
	v_mfma_f32_16x16x32_bf16 v[24:27], v[232:235], v[192:195], v[24:27]
	v_mfma_f32_16x16x32_bf16 v[20:23], v[224:227], v[200:203], v[20:23]
	v_mfma_f32_16x16x32_bf16 v[16:19], v[232:235], v[200:203], v[16:19]
	v_mfma_f32_16x16x32_bf16 v[12:15], v[224:227], v[208:211], v[12:15]
	v_mfma_f32_16x16x32_bf16 v[8:11], v[232:235], v[208:211], v[8:11]
	v_mfma_f32_16x16x32_bf16 v[4:7], v[224:227], v[216:219], v[4:7]
	v_mfma_f32_16x16x32_bf16 v[0:3], v[232:235], v[216:219], v[0:3]
	v_mfma_f32_16x16x32_bf16 v[28:31], v[228:231], v[196:199], v[28:31]
	v_mfma_f32_16x16x32_bf16 v[24:27], v[236:239], v[196:199], v[24:27]
	v_mfma_f32_16x16x32_bf16 v[20:23], v[228:231], v[204:207], v[20:23]
	v_mfma_f32_16x16x32_bf16 v[16:19], v[236:239], v[204:207], v[16:19]
	v_mfma_f32_16x16x32_bf16 v[12:15], v[228:231], v[212:215], v[12:15]
	v_mfma_f32_16x16x32_bf16 v[8:11], v[236:239], v[212:215], v[8:11]
	v_mfma_f32_16x16x32_bf16 v[4:7], v[228:231], v[220:223], v[4:7]
	v_mfma_f32_16x16x32_bf16 v[0:3], v[236:239], v[220:223], v[0:3]
	s_barrier
	ds_read_b128 v[176:179], v160
	ds_read_b128 v[180:183], v160 offset:1024
	ds_read_b128 v[184:187], v160 offset:2048
	ds_read_b128 v[188:191], v160 offset:3072
	v_readfirstlane_b32 s2, v161
	v_lshl_add_u64 v[224:225], v[240:241], 0, s[24:25]
	s_mov_b32 m0, s2
	v_readfirstlane_b32 s2, v162
	ds_read_b128 v[192:195], v155 offset:32768
	ds_read_b128 v[196:199], v155 offset:33792
	ds_read_b128 v[200:203], v154 offset:32768
	ds_read_b128 v[204:207], v154 offset:33792
	ds_read_b128 v[208:211], v153 offset:32768
	ds_read_b128 v[212:215], v153 offset:33792
	ds_read_b128 v[216:219], v152 offset:32768
	ds_read_b128 v[220:223], v152 offset:33792
	global_load_lds_dwordx4 v[224:225], off
	v_lshl_add_u64 v[224:225], v[242:243], 0, s[24:25]
	s_mov_b32 m0, s2
	s_nop 0
	global_load_lds_dwordx4 v[224:225], off
	s_waitcnt lgkmcnt(8)
	s_barrier
	s_waitcnt lgkmcnt(0)
	v_mfma_f32_16x16x32_bf16 v[124:127], v[176:179], v[192:195], v[124:127]
	v_mfma_f32_16x16x32_bf16 v[120:123], v[184:187], v[192:195], v[120:123]
	v_mfma_f32_16x16x32_bf16 v[116:119], v[176:179], v[200:203], v[116:119]
	v_mfma_f32_16x16x32_bf16 v[112:115], v[184:187], v[200:203], v[112:115]
	v_mfma_f32_16x16x32_bf16 v[108:111], v[176:179], v[208:211], v[108:111]
	v_mfma_f32_16x16x32_bf16 v[104:107], v[184:187], v[208:211], v[104:107]
	v_mfma_f32_16x16x32_bf16 v[100:103], v[176:179], v[216:219], v[100:103]
	v_mfma_f32_16x16x32_bf16 v[96:99], v[184:187], v[216:219], v[96:99]
	v_mfma_f32_16x16x32_bf16 v[124:127], v[180:183], v[196:199], v[124:127]
	v_mfma_f32_16x16x32_bf16 v[120:123], v[188:191], v[196:199], v[120:123]
	v_mfma_f32_16x16x32_bf16 v[116:119], v[180:183], v[204:207], v[116:119]
	v_mfma_f32_16x16x32_bf16 v[112:115], v[188:191], v[204:207], v[112:115]
	v_mfma_f32_16x16x32_bf16 v[108:111], v[180:183], v[212:215], v[108:111]
	v_mfma_f32_16x16x32_bf16 v[104:107], v[188:191], v[212:215], v[104:107]
	v_mfma_f32_16x16x32_bf16 v[100:103], v[180:183], v[220:223], v[100:103]
	v_mfma_f32_16x16x32_bf16 v[96:99], v[188:191], v[220:223], v[96:99]
	s_barrier
	v_readfirstlane_b32 s2, v163
	v_lshl_add_u64 v[248:249], v[244:245], 0, s[26:27]
	s_mov_b32 m0, s2
	v_readfirstlane_b32 s2, v167
	ds_read_b128 v[224:227], v156
	ds_read_b128 v[228:231], v156 offset:1024
	ds_read_b128 v[232:235], v156 offset:2048
	ds_read_b128 v[236:239], v156 offset:3072
	global_load_lds_dwordx4 v[248:249], off
	v_lshl_add_u64 v[248:249], v[246:247], 0, s[26:27]
	s_mov_b32 m0, s2
	s_nop 0
	global_load_lds_dwordx4 v[248:249], off
	s_barrier
	s_waitcnt lgkmcnt(0)
	v_mfma_f32_16x16x32_bf16 v[92:95], v[224:227], v[192:195], v[92:95]
	v_mfma_f32_16x16x32_bf16 v[88:91], v[232:235], v[192:195], v[88:91]
	v_mfma_f32_16x16x32_bf16 v[84:87], v[224:227], v[200:203], v[84:87]
	v_mfma_f32_16x16x32_bf16 v[80:83], v[232:235], v[200:203], v[80:83]
	v_mfma_f32_16x16x32_bf16 v[76:79], v[224:227], v[208:211], v[76:79]
	v_mfma_f32_16x16x32_bf16 v[72:75], v[232:235], v[208:211], v[72:75]
	v_mfma_f32_16x16x32_bf16 v[68:71], v[224:227], v[216:219], v[68:71]
	v_mfma_f32_16x16x32_bf16 v[64:67], v[232:235], v[216:219], v[64:67]
	v_mfma_f32_16x16x32_bf16 v[92:95], v[228:231], v[196:199], v[92:95]
	v_mfma_f32_16x16x32_bf16 v[88:91], v[236:239], v[196:199], v[88:91]
	v_mfma_f32_16x16x32_bf16 v[84:87], v[228:231], v[204:207], v[84:87]
	v_mfma_f32_16x16x32_bf16 v[80:83], v[236:239], v[204:207], v[80:83]
	v_mfma_f32_16x16x32_bf16 v[76:79], v[228:231], v[212:215], v[76:79]
	v_mfma_f32_16x16x32_bf16 v[72:75], v[236:239], v[212:215], v[72:75]
	v_mfma_f32_16x16x32_bf16 v[68:71], v[228:231], v[220:223], v[68:71]
	v_mfma_f32_16x16x32_bf16 v[64:67], v[236:239], v[220:223], v[64:67]
	v_readfirstlane_b32 s2, v168
	v_lshl_add_u64 v[240:241], v[240:241], 0, s[28:29]
	s_mov_b32 m0, s2
	v_readfirstlane_b32 s2, v169
	s_barrier
	ds_read_b128 v[192:195], v155 offset:49152
	ds_read_b128 v[196:199], v155 offset:50176
	ds_read_b128 v[200:203], v154 offset:49152
	ds_read_b128 v[204:207], v154 offset:50176
	ds_read_b128 v[208:211], v153 offset:49152
	ds_read_b128 v[212:215], v153 offset:50176
	ds_read_b128 v[216:219], v152 offset:49152
	ds_read_b128 v[220:223], v152 offset:50176
	global_load_lds_dwordx4 v[240:241], off
	v_lshl_add_u64 v[240:241], v[242:243], 0, s[28:29]
	s_mov_b32 m0, s2
	s_nop 0
	global_load_lds_dwordx4 v[240:241], off
	s_barrier
	s_waitcnt lgkmcnt(0)
	v_mfma_f32_16x16x32_bf16 v[60:63], v[176:179], v[192:195], v[60:63]
	v_mfma_f32_16x16x32_bf16 v[56:59], v[184:187], v[192:195], v[56:59]
	v_mfma_f32_16x16x32_bf16 v[52:55], v[176:179], v[200:203], v[52:55]
	v_mfma_f32_16x16x32_bf16 v[48:51], v[184:187], v[200:203], v[48:51]
	v_mfma_f32_16x16x32_bf16 v[44:47], v[176:179], v[208:211], v[44:47]
	v_mfma_f32_16x16x32_bf16 v[40:43], v[184:187], v[208:211], v[40:43]
	v_mfma_f32_16x16x32_bf16 v[36:39], v[176:179], v[216:219], v[36:39]
	v_mfma_f32_16x16x32_bf16 v[32:35], v[184:187], v[216:219], v[32:35]
	v_mfma_f32_16x16x32_bf16 v[60:63], v[180:183], v[196:199], v[60:63]
	v_mfma_f32_16x16x32_bf16 v[56:59], v[188:191], v[196:199], v[56:59]
	v_mfma_f32_16x16x32_bf16 v[52:55], v[180:183], v[204:207], v[52:55]
	v_mfma_f32_16x16x32_bf16 v[48:51], v[188:191], v[204:207], v[48:51]
	v_mfma_f32_16x16x32_bf16 v[44:47], v[180:183], v[212:215], v[44:47]
	v_mfma_f32_16x16x32_bf16 v[40:43], v[188:191], v[212:215], v[40:43]
	v_mfma_f32_16x16x32_bf16 v[36:39], v[180:183], v[220:223], v[36:39]
	v_mfma_f32_16x16x32_bf16 v[32:35], v[188:191], v[220:223], v[32:35]
	s_barrier
	v_readfirstlane_b32 s2, v171
	v_lshl_add_u64 v[176:177], v[244:245], 0, s[30:31]
	s_mov_b32 m0, s2
	v_readfirstlane_b32 s2, v172
	global_load_lds_dwordx4 v[176:177], off
	v_lshl_add_u64 v[176:177], v[246:247], 0, s[30:31]
	s_mov_b32 m0, s2
	s_nop 0
	global_load_lds_dwordx4 v[176:177], off
	s_add_i32 s1, s1, 2
	v_lshl_add_u64 v[138:139], v[138:139], 0, s[34:35]
	v_lshl_add_u64 v[140:141], v[140:141], 0, s[34:35]
	v_lshl_add_u64 v[142:143], v[142:143], 0, s[34:35]
	s_cmp_lt_u32 s1, 60
	v_lshl_add_u64 v[144:145], v[144:145], 0, s[34:35]
	s_waitcnt vmcnt(6)
	s_barrier
	v_mfma_f32_16x16x32_bf16 v[28:31], v[224:227], v[192:195], v[28:31]
	v_mfma_f32_16x16x32_bf16 v[24:27], v[232:235], v[192:195], v[24:27]
	v_mfma_f32_16x16x32_bf16 v[20:23], v[224:227], v[200:203], v[20:23]
	v_mfma_f32_16x16x32_bf16 v[16:19], v[232:235], v[200:203], v[16:19]
	v_mfma_f32_16x16x32_bf16 v[12:15], v[224:227], v[208:211], v[12:15]
	v_mfma_f32_16x16x32_bf16 v[8:11], v[232:235], v[208:211], v[8:11]
	v_mfma_f32_16x16x32_bf16 v[4:7], v[224:227], v[216:219], v[4:7]
	v_mfma_f32_16x16x32_bf16 v[0:3], v[232:235], v[216:219], v[0:3]
	v_mfma_f32_16x16x32_bf16 v[28:31], v[228:231], v[196:199], v[28:31]
	v_mfma_f32_16x16x32_bf16 v[24:27], v[236:239], v[196:199], v[24:27]
	v_mfma_f32_16x16x32_bf16 v[20:23], v[228:231], v[204:207], v[20:23]
	v_mfma_f32_16x16x32_bf16 v[16:19], v[236:239], v[204:207], v[16:19]
	v_mfma_f32_16x16x32_bf16 v[12:15], v[228:231], v[212:215], v[12:15]
	v_mfma_f32_16x16x32_bf16 v[8:11], v[236:239], v[212:215], v[8:11]
	v_mfma_f32_16x16x32_bf16 v[4:7], v[228:231], v[220:223], v[4:7]
	v_mfma_f32_16x16x32_bf16 v[0:3], v[236:239], v[220:223], v[0:3]
	s_barrier
	s_cbranch_scc1 .LBB0_1720
	s_add_u32 s4, s38, 0x1f80
	s_addc_u32 s5, s39, 0
	v_lshl_add_u64 v[132:133], s[4:5], 0, v[132:133]
	v_readfirstlane_b32 s1, v174
	v_lshl_add_u64 v[130:131], v[130:131], 1, v[132:133]
	s_mov_b32 m0, s1
	ds_read_b128 v[138:141], v173
	ds_read_b128 v[142:145], v173 offset:1024
	ds_read_b128 v[176:179], v173 offset:2048
	ds_read_b128 v[180:183], v173 offset:3072
	ds_read_b128 v[184:187], v155
	ds_read_b128 v[188:191], v155 offset:1024
	ds_read_b128 v[192:195], v154
	ds_read_b128 v[196:199], v154 offset:1024
	ds_read_b128 v[200:203], v153
	ds_read_b128 v[204:207], v153 offset:1024
	ds_read_b128 v[208:211], v152
	ds_read_b128 v[212:215], v152 offset:1024
	global_load_lds_dwordx4 v[130:131], off
	v_lshl_add_u64 v[130:131], s[4:5], 0, v[136:137]
	v_readfirstlane_b32 s1, v175
	v_lshl_add_u64 v[130:131], v[134:135], 1, v[130:131]
	s_mov_b32 m0, s1
	s_nop 0
	global_load_lds_dwordx4 v[130:131], off
	s_barrier
	s_waitcnt lgkmcnt(0)
	v_mfma_f32_16x16x32_bf16 v[124:127], v[138:141], v[184:187], v[124:127]
	v_mfma_f32_16x16x32_bf16 v[116:119], v[138:141], v[192:195], v[116:119]
	v_mfma_f32_16x16x32_bf16 v[108:111], v[138:141], v[200:203], v[108:111]
	v_mfma_f32_16x16x32_bf16 v[100:103], v[138:141], v[208:211], v[100:103]
	v_mfma_f32_16x16x32_bf16 v[124:127], v[142:145], v[188:191], v[124:127]
	v_mfma_f32_16x16x32_bf16 v[120:123], v[176:179], v[184:187], v[120:123]
	v_mfma_f32_16x16x32_bf16 v[116:119], v[142:145], v[196:199], v[116:119]
	v_mfma_f32_16x16x32_bf16 v[112:115], v[176:179], v[192:195], v[112:115]
	v_mfma_f32_16x16x32_bf16 v[108:111], v[142:145], v[204:207], v[108:111]
	v_mfma_f32_16x16x32_bf16 v[104:107], v[176:179], v[200:203], v[104:107]
	v_mfma_f32_16x16x32_bf16 v[100:103], v[142:145], v[212:215], v[100:103]
	v_mfma_f32_16x16x32_bf16 v[96:99], v[176:179], v[208:211], v[96:99]
	v_mfma_f32_16x16x32_bf16 v[130:133], v[180:183], v[188:191], v[120:123]
	v_mfma_f32_16x16x32_bf16 v[134:137], v[180:183], v[196:199], v[112:115]
	v_mfma_f32_16x16x32_bf16 v[172:175], v[180:183], v[204:207], v[104:107]
	v_mfma_f32_16x16x32_bf16 v[216:219], v[180:183], v[212:215], v[96:99]
	s_barrier
	s_nop 1
	ds_read_b128 v[96:99], v170
	ds_read_b128 v[104:107], v170 offset:1024
	ds_read_b128 v[112:115], v170 offset:2048
	ds_read_b128 v[120:123], v170 offset:3072
	s_barrier
	s_waitcnt lgkmcnt(0)
	v_mfma_f32_16x16x32_bf16 v[92:95], v[96:99], v[184:187], v[92:95]
	v_mfma_f32_16x16x32_bf16 v[84:87], v[96:99], v[192:195], v[84:87]
	v_mfma_f32_16x16x32_bf16 v[76:79], v[96:99], v[200:203], v[76:79]
	v_mfma_f32_16x16x32_bf16 v[68:71], v[96:99], v[208:211], v[68:71]
	v_mfma_f32_16x16x32_bf16 v[92:95], v[104:107], v[188:191], v[92:95]
	v_mfma_f32_16x16x32_bf16 v[88:91], v[112:115], v[184:187], v[88:91]
	v_mfma_f32_16x16x32_bf16 v[84:87], v[104:107], v[196:199], v[84:87]
	v_mfma_f32_16x16x32_bf16 v[80:83], v[112:115], v[192:195], v[80:83]
	v_mfma_f32_16x16x32_bf16 v[76:79], v[104:107], v[204:207], v[76:79]
	v_mfma_f32_16x16x32_bf16 v[72:75], v[112:115], v[200:203], v[72:75]
	v_mfma_f32_16x16x32_bf16 v[68:71], v[104:107], v[212:215], v[68:71]
	v_mfma_f32_16x16x32_bf16 v[64:67], v[112:115], v[208:211], v[64:67]
	v_mfma_f32_16x16x32_bf16 v[168:171], v[120:123], v[188:191], v[88:91]
	v_mfma_f32_16x16x32_bf16 v[184:187], v[120:123], v[196:199], v[80:83]
	v_mfma_f32_16x16x32_bf16 v[188:191], v[120:123], v[204:207], v[72:75]
	v_mfma_f32_16x16x32_bf16 v[192:195], v[120:123], v[212:215], v[64:67]
	s_barrier
	s_nop 1
	ds_read_b128 v[64:67], v155 offset:16384
	ds_read_b128 v[72:75], v155 offset:17408
	ds_read_b128 v[80:83], v154 offset:16384
	ds_read_b128 v[88:91], v154 offset:17408
	ds_read_b128 v[196:199], v153 offset:16384
	ds_read_b128 v[200:203], v153 offset:17408
	ds_read_b128 v[204:207], v152 offset:16384
	ds_read_b128 v[208:211], v152 offset:17408
	s_waitcnt vmcnt(4)
	s_barrier
	s_waitcnt lgkmcnt(0)
	v_mfma_f32_16x16x32_bf16 v[60:63], v[138:141], v[64:67], v[60:63]
	v_mfma_f32_16x16x32_bf16 v[52:55], v[138:141], v[80:83], v[52:55]
	v_mfma_f32_16x16x32_bf16 v[44:47], v[138:141], v[196:199], v[44:47]
	v_mfma_f32_16x16x32_bf16 v[36:39], v[138:141], v[204:207], v[36:39]
	v_mfma_f32_16x16x32_bf16 v[60:63], v[142:145], v[72:75], v[60:63]
	v_mfma_f32_16x16x32_bf16 v[56:59], v[176:179], v[64:67], v[56:59]
	v_mfma_f32_16x16x32_bf16 v[52:55], v[142:145], v[88:91], v[52:55]
	v_mfma_f32_16x16x32_bf16 v[48:51], v[176:179], v[80:83], v[48:51]
	v_mfma_f32_16x16x32_bf16 v[44:47], v[142:145], v[200:203], v[44:47]
	v_mfma_f32_16x16x32_bf16 v[40:43], v[176:179], v[196:199], v[40:43]
	v_mfma_f32_16x16x32_bf16 v[36:39], v[142:145], v[208:211], v[36:39]
	v_mfma_f32_16x16x32_bf16 v[32:35], v[176:179], v[204:207], v[32:35]
	v_mfma_f32_16x16x32_bf16 v[212:215], v[180:183], v[72:75], v[56:59]
	v_mfma_f32_16x16x32_bf16 v[220:223], v[180:183], v[88:91], v[48:51]
	v_mfma_f32_16x16x32_bf16 v[224:227], v[180:183], v[200:203], v[40:43]
	v_mfma_f32_16x16x32_bf16 v[138:141], v[180:183], v[208:211], v[32:35]
	v_mfma_f32_16x16x32_bf16 v[28:31], v[96:99], v[64:67], v[28:31]
	v_mfma_f32_16x16x32_bf16 v[20:23], v[96:99], v[80:83], v[20:23]
	v_mfma_f32_16x16x32_bf16 v[12:15], v[96:99], v[196:199], v[12:15]
	v_mfma_f32_16x16x32_bf16 v[4:7], v[96:99], v[204:207], v[4:7]
	v_mfma_f32_16x16x32_bf16 v[28:31], v[104:107], v[72:75], v[28:31]
	v_mfma_f32_16x16x32_bf16 v[24:27], v[112:115], v[64:67], v[24:27]
	v_mfma_f32_16x16x32_bf16 v[20:23], v[104:107], v[88:91], v[20:23]
	v_mfma_f32_16x16x32_bf16 v[16:19], v[112:115], v[80:83], v[16:19]
	v_mfma_f32_16x16x32_bf16 v[12:15], v[104:107], v[200:203], v[12:15]
	v_mfma_f32_16x16x32_bf16 v[8:11], v[112:115], v[196:199], v[8:11]
	v_mfma_f32_16x16x32_bf16 v[4:7], v[104:107], v[208:211], v[4:7]
	v_mfma_f32_16x16x32_bf16 v[0:3], v[112:115], v[204:207], v[0:3]
	v_mfma_f32_16x16x32_bf16 v[142:145], v[120:123], v[72:75], v[24:27]
	v_mfma_f32_16x16x32_bf16 v[176:179], v[120:123], v[88:91], v[16:19]
	v_mfma_f32_16x16x32_bf16 v[180:183], v[120:123], v[200:203], v[8:11]
	v_mfma_f32_16x16x32_bf16 v[196:199], v[120:123], v[208:211], v[0:3]
	s_barrier
	s_nop 1
	ds_read_b128 v[0:3], v160
	ds_read_b128 v[8:11], v160 offset:1024
	ds_read_b128 v[16:19], v160 offset:2048
	ds_read_b128 v[24:27], v160 offset:3072
	ds_read_b128 v[32:35], v155 offset:32768
	ds_read_b128 v[40:43], v155 offset:33792
	ds_read_b128 v[48:51], v154 offset:32768
	ds_read_b128 v[56:59], v154 offset:33792
	ds_read_b128 v[64:67], v153 offset:32768
	ds_read_b128 v[158:161], v153 offset:33792
	ds_read_b128 v[200:203], v152 offset:32768
	ds_read_b128 v[204:207], v152 offset:33792
	s_waitcnt vmcnt(2)
	s_barrier
	s_waitcnt lgkmcnt(0)
	v_mfma_f32_16x16x32_bf16 v[72:75], v[0:3], v[32:35], v[124:127]
	v_mfma_f32_16x16x32_bf16 v[120:123], v[8:11], v[40:43], v[72:75]
	v_mfma_f32_16x16x32_bf16 v[72:75], v[16:19], v[32:35], v[130:133]
	v_mfma_f32_16x16x32_bf16 v[124:127], v[24:27], v[40:43], v[72:75]
	v_mfma_f32_16x16x32_bf16 v[72:75], v[0:3], v[48:51], v[116:119]
	v_mfma_f32_16x16x32_bf16 v[112:115], v[8:11], v[56:59], v[72:75]
	v_mfma_f32_16x16x32_bf16 v[72:75], v[16:19], v[48:51], v[134:137]
	v_mfma_f32_16x16x32_bf16 v[116:119], v[24:27], v[56:59], v[72:75]
	v_mfma_f32_16x16x32_bf16 v[72:75], v[0:3], v[64:67], v[108:111]
	v_mfma_f32_16x16x32_bf16 v[104:107], v[8:11], v[158:161], v[72:75]
	v_mfma_f32_16x16x32_bf16 v[72:75], v[16:19], v[64:67], v[172:175]
	v_mfma_f32_16x16x32_bf16 v[108:111], v[24:27], v[158:161], v[72:75]
	v_mfma_f32_16x16x32_bf16 v[72:75], v[0:3], v[200:203], v[100:103]
	v_mfma_f32_16x16x32_bf16 v[96:99], v[8:11], v[204:207], v[72:75]
	v_mfma_f32_16x16x32_bf16 v[72:75], v[16:19], v[200:203], v[216:219]
	v_mfma_f32_16x16x32_bf16 v[100:103], v[24:27], v[204:207], v[72:75]
	s_barrier
	ds_read_b128 v[130:133], v156
	ds_read_b128 v[134:137], v156 offset:1024
	ds_read_b128 v[172:175], v156 offset:2048
	ds_read_b128 v[208:211], v156 offset:3072
	s_waitcnt vmcnt(0)
	s_barrier
	s_waitcnt lgkmcnt(0)
	v_mfma_f32_16x16x32_bf16 v[72:75], v[130:133], v[32:35], v[92:95]
	v_mfma_f32_16x16x32_bf16 v[32:35], v[172:175], v[32:35], v[168:171]
	v_mfma_f32_16x16x32_bf16 v[92:95], v[208:211], v[40:43], v[32:35]
	v_mfma_f32_16x16x32_bf16 v[32:35], v[130:133], v[48:51], v[84:87]
	v_mfma_f32_16x16x32_bf16 v[80:83], v[134:137], v[56:59], v[32:35]
	v_mfma_f32_16x16x32_bf16 v[32:35], v[172:175], v[48:51], v[184:187]
	v_mfma_f32_16x16x32_bf16 v[84:87], v[208:211], v[56:59], v[32:35]
	v_mfma_f32_16x16x32_bf16 v[32:35], v[130:133], v[64:67], v[76:79]
	v_mfma_f32_16x16x32_bf16 v[88:91], v[134:137], v[40:43], v[72:75]
	v_mfma_f32_16x16x32_bf16 v[72:75], v[134:137], v[158:161], v[32:35]
	v_mfma_f32_16x16x32_bf16 v[32:35], v[172:175], v[64:67], v[188:191]
	v_mfma_f32_16x16x32_bf16 v[76:79], v[208:211], v[158:161], v[32:35]
	v_mfma_f32_16x16x32_bf16 v[32:35], v[130:133], v[200:203], v[68:71]
	v_mfma_f32_16x16x32_bf16 v[64:67], v[134:137], v[204:207], v[32:35]
	v_mfma_f32_16x16x32_bf16 v[32:35], v[172:175], v[200:203], v[192:195]
	v_mfma_f32_16x16x32_bf16 v[68:71], v[208:211], v[204:207], v[32:35]
	s_barrier
	ds_read_b128 v[156:159], v155 offset:49152
	ds_read_b128 v[160:163], v155 offset:50176
	ds_read_b128 v[168:171], v154 offset:49152
	ds_read_b128 v[184:187], v154 offset:50176
	ds_read_b128 v[188:191], v153 offset:49152
	ds_read_b128 v[192:195], v153 offset:50176
	ds_read_b128 v[200:203], v152 offset:49152
	ds_read_b128 v[152:155], v152 offset:50176
	s_barrier
	s_waitcnt lgkmcnt(0)
	v_mfma_f32_16x16x32_bf16 v[32:35], v[0:3], v[156:159], v[60:63]
	v_mfma_f32_16x16x32_bf16 v[56:59], v[8:11], v[160:163], v[32:35]
	v_mfma_f32_16x16x32_bf16 v[32:35], v[16:19], v[156:159], v[212:215]
	v_mfma_f32_16x16x32_bf16 v[60:63], v[24:27], v[160:163], v[32:35]
	v_mfma_f32_16x16x32_bf16 v[32:35], v[0:3], v[168:171], v[52:55]
	v_mfma_f32_16x16x32_bf16 v[48:51], v[8:11], v[184:187], v[32:35]
	v_mfma_f32_16x16x32_bf16 v[32:35], v[16:19], v[168:171], v[220:223]
	v_mfma_f32_16x16x32_bf16 v[52:55], v[24:27], v[184:187], v[32:35]
	v_mfma_f32_16x16x32_bf16 v[32:35], v[0:3], v[188:191], v[44:47]
	v_mfma_f32_16x16x32_bf16 v[40:43], v[8:11], v[192:195], v[32:35]
	v_mfma_f32_16x16x32_bf16 v[32:35], v[16:19], v[188:191], v[224:227]
	v_mfma_f32_16x16x32_bf16 v[0:3], v[0:3], v[200:203], v[36:39]
	v_mfma_f32_16x16x32_bf16 v[44:47], v[24:27], v[192:195], v[32:35]
	v_mfma_f32_16x16x32_bf16 v[32:35], v[8:11], v[152:155], v[0:3]
	v_mfma_f32_16x16x32_bf16 v[0:3], v[16:19], v[200:203], v[138:141]
	v_mfma_f32_16x16x32_bf16 v[36:39], v[24:27], v[152:155], v[0:3]
	v_mfma_f32_16x16x32_bf16 v[0:3], v[130:133], v[156:159], v[28:31]
	v_mfma_f32_16x16x32_bf16 v[24:27], v[134:137], v[160:163], v[0:3]
	v_mfma_f32_16x16x32_bf16 v[0:3], v[172:175], v[156:159], v[142:145]
	v_mfma_f32_16x16x32_bf16 v[28:31], v[208:211], v[160:163], v[0:3]
	v_mfma_f32_16x16x32_bf16 v[0:3], v[130:133], v[168:171], v[20:23]
	v_mfma_f32_16x16x32_bf16 v[16:19], v[134:137], v[184:187], v[0:3]
	v_mfma_f32_16x16x32_bf16 v[0:3], v[172:175], v[168:171], v[176:179]
	v_mfma_f32_16x16x32_bf16 v[20:23], v[208:211], v[184:187], v[0:3]
	v_mfma_f32_16x16x32_bf16 v[0:3], v[130:133], v[188:191], v[12:15]
	v_mfma_f32_16x16x32_bf16 v[8:11], v[134:137], v[192:195], v[0:3]
	v_mfma_f32_16x16x32_bf16 v[0:3], v[172:175], v[188:191], v[180:183]
	v_mfma_f32_16x16x32_bf16 v[12:15], v[208:211], v[192:195], v[0:3]
	v_mfma_f32_16x16x32_bf16 v[0:3], v[130:133], v[200:203], v[4:7]
	v_mfma_f32_16x16x32_bf16 v[4:7], v[172:175], v[200:203], v[196:199]
	v_mfma_f32_16x16x32_bf16 v[0:3], v[134:137], v[152:155], v[0:3]
	v_mfma_f32_16x16x32_bf16 v[4:7], v[208:211], v[152:155], v[4:7]
	v_cmp_gt_u32_e32 vcc, s75, v128
	s_barrier
	s_and_saveexec_b64 s[38:39], vcc
	s_cbranch_execz .LBB0_1716
	s_barrier
	s_branch .LBB0_1716

.LBB0_1842:
	ds_read_b128 v[180:183], v172
	ds_read_b128 v[184:187], v172 offset:1024
	ds_read_b128 v[188:191], v172 offset:2048
	ds_read_b128 v[192:195], v172 offset:3072
	v_add_u32_e32 v178, 0xc000, v152
	v_lshl_add_u64 v[244:245], s[12:13], 0, v[146:147]
	v_readfirstlane_b32 s1, v178
	v_add_u32_e32 v179, 0xe000, v152
	v_lshl_add_u64 v[224:225], v[244:245], 0, s[20:21]
	s_mov_b32 m0, s1
	v_lshl_add_u64 v[246:247], s[12:13], 0, v[148:149]
	v_readfirstlane_b32 s1, v179
	ds_read_b128 v[174:177], v161
	ds_read_b128 v[196:199], v161 offset:1024
	ds_read_b128 v[200:203], v160
	ds_read_b128 v[204:207], v160 offset:1024
	ds_read_b128 v[208:211], v159
	ds_read_b128 v[212:215], v159 offset:1024
	ds_read_b128 v[216:219], v158
	ds_read_b128 v[220:223], v158 offset:1024
	global_load_lds_dwordx4 v[224:225], off
	v_lshl_add_u64 v[224:225], v[246:247], 0, s[20:21]
	s_mov_b32 m0, s1
	s_nop 0
	global_load_lds_dwordx4 v[224:225], off
	s_waitcnt lgkmcnt(8)
	s_barrier
	s_waitcnt lgkmcnt(0)
	v_mfma_f32_16x16x32_bf16 v[124:127], v[180:183], v[174:177], v[124:127]
	v_mfma_f32_16x16x32_bf16 v[120:123], v[188:191], v[174:177], v[120:123]
	v_mfma_f32_16x16x32_bf16 v[116:119], v[180:183], v[200:203], v[116:119]
	v_mfma_f32_16x16x32_bf16 v[112:115], v[188:191], v[200:203], v[112:115]
	v_mfma_f32_16x16x32_bf16 v[108:111], v[180:183], v[208:211], v[108:111]
	v_mfma_f32_16x16x32_bf16 v[104:107], v[188:191], v[208:211], v[104:107]
	v_mfma_f32_16x16x32_bf16 v[100:103], v[180:183], v[216:219], v[100:103]
	v_mfma_f32_16x16x32_bf16 v[96:99], v[188:191], v[216:219], v[96:99]
	v_mfma_f32_16x16x32_bf16 v[124:127], v[184:187], v[196:199], v[124:127]
	v_mfma_f32_16x16x32_bf16 v[120:123], v[192:195], v[196:199], v[120:123]
	v_mfma_f32_16x16x32_bf16 v[116:119], v[184:187], v[204:207], v[116:119]
	v_mfma_f32_16x16x32_bf16 v[112:115], v[192:195], v[204:207], v[112:115]
	v_mfma_f32_16x16x32_bf16 v[108:111], v[184:187], v[212:215], v[108:111]
	v_mfma_f32_16x16x32_bf16 v[104:107], v[192:195], v[212:215], v[104:107]
	v_mfma_f32_16x16x32_bf16 v[100:103], v[184:187], v[220:223], v[100:103]
	v_mfma_f32_16x16x32_bf16 v[96:99], v[192:195], v[220:223], v[96:99]
	s_barrier
	v_lshl_add_u64 v[248:249], s[12:13], 0, v[142:143]
	v_readfirstlane_b32 s1, v153
	v_add_u32_e32 v173, 0x2000, v153
	v_lshl_add_u64 v[240:241], v[248:249], 0, s[24:25]
	s_mov_b32 m0, s1
	v_lshl_add_u64 v[250:251], s[12:13], 0, v[144:145]
	v_readfirstlane_b32 s1, v173
	ds_read_b128 v[224:227], v169
	ds_read_b128 v[228:231], v169 offset:1024
	ds_read_b128 v[232:235], v169 offset:2048
	ds_read_b128 v[236:239], v169 offset:3072
	global_load_lds_dwordx4 v[240:241], off
	v_lshl_add_u64 v[240:241], v[250:251], 0, s[24:25]
	s_mov_b32 m0, s1
	s_nop 0
	global_load_lds_dwordx4 v[240:241], off
	s_barrier
	s_waitcnt lgkmcnt(0)
	v_mfma_f32_16x16x32_bf16 v[92:95], v[224:227], v[174:177], v[92:95]
	v_mfma_f32_16x16x32_bf16 v[88:91], v[232:235], v[174:177], v[88:91]
	v_mfma_f32_16x16x32_bf16 v[84:87], v[224:227], v[200:203], v[84:87]
	v_mfma_f32_16x16x32_bf16 v[80:83], v[232:235], v[200:203], v[80:83]
	v_mfma_f32_16x16x32_bf16 v[76:79], v[224:227], v[208:211], v[76:79]
	v_mfma_f32_16x16x32_bf16 v[72:75], v[232:235], v[208:211], v[72:75]
	v_mfma_f32_16x16x32_bf16 v[68:71], v[224:227], v[216:219], v[68:71]
	v_mfma_f32_16x16x32_bf16 v[64:67], v[232:235], v[216:219], v[64:67]
	v_mfma_f32_16x16x32_bf16 v[92:95], v[228:231], v[196:199], v[92:95]
	v_mfma_f32_16x16x32_bf16 v[88:91], v[236:239], v[196:199], v[88:91]
	v_mfma_f32_16x16x32_bf16 v[84:87], v[228:231], v[204:207], v[84:87]
	v_mfma_f32_16x16x32_bf16 v[80:83], v[236:239], v[204:207], v[80:83]
	v_mfma_f32_16x16x32_bf16 v[76:79], v[228:231], v[212:215], v[76:79]
	v_mfma_f32_16x16x32_bf16 v[72:75], v[236:239], v[212:215], v[72:75]
	v_mfma_f32_16x16x32_bf16 v[68:71], v[228:231], v[220:223], v[68:71]
	v_mfma_f32_16x16x32_bf16 v[64:67], v[236:239], v[220:223], v[64:67]
	v_readfirstlane_b32 s1, v152
	v_lshl_add_u64 v[174:175], v[244:245], 0, s[26:27]
	s_mov_b32 m0, s1
	s_barrier
	ds_read_b128 v[196:199], v161 offset:16384
	ds_read_b128 v[200:203], v161 offset:17408
	ds_read_b128 v[204:207], v160 offset:16384
	ds_read_b128 v[208:211], v160 offset:17408
	ds_read_b128 v[212:215], v159 offset:16384
	ds_read_b128 v[216:219], v159 offset:17408
	ds_read_b128 v[220:223], v158 offset:16384
	ds_read_b128 v[240:243], v158 offset:17408
	global_load_lds_dwordx4 v[174:175], off
	v_add_u32_e32 v174, 0x2000, v152
	v_lshl_add_u64 v[176:177], v[246:247], 0, s[26:27]
	v_readfirstlane_b32 s1, v174
	s_mov_b32 m0, s1
	s_nop 0
	global_load_lds_dwordx4 v[176:177], off
	s_barrier
	s_waitcnt lgkmcnt(0)
	v_mfma_f32_16x16x32_bf16 v[60:63], v[180:183], v[196:199], v[60:63]
	v_mfma_f32_16x16x32_bf16 v[56:59], v[188:191], v[196:199], v[56:59]
	v_mfma_f32_16x16x32_bf16 v[52:55], v[180:183], v[204:207], v[52:55]
	v_mfma_f32_16x16x32_bf16 v[48:51], v[188:191], v[204:207], v[48:51]
	v_mfma_f32_16x16x32_bf16 v[44:47], v[180:183], v[212:215], v[44:47]
	v_mfma_f32_16x16x32_bf16 v[40:43], v[188:191], v[212:215], v[40:43]
	v_mfma_f32_16x16x32_bf16 v[36:39], v[180:183], v[220:223], v[36:39]
	v_mfma_f32_16x16x32_bf16 v[32:35], v[188:191], v[220:223], v[32:35]
	v_mfma_f32_16x16x32_bf16 v[60:63], v[184:187], v[200:203], v[60:63]
	v_mfma_f32_16x16x32_bf16 v[56:59], v[192:195], v[200:203], v[56:59]
	v_mfma_f32_16x16x32_bf16 v[52:55], v[184:187], v[208:211], v[52:55]
	v_mfma_f32_16x16x32_bf16 v[48:51], v[192:195], v[208:211], v[48:51]
	v_mfma_f32_16x16x32_bf16 v[44:47], v[184:187], v[216:219], v[44:47]
	v_mfma_f32_16x16x32_bf16 v[40:43], v[192:195], v[216:219], v[40:43]
	v_mfma_f32_16x16x32_bf16 v[36:39], v[184:187], v[240:243], v[36:39]
	v_mfma_f32_16x16x32_bf16 v[32:35], v[192:195], v[240:243], v[32:35]
	s_barrier
	v_readfirstlane_b32 s1, v151
	v_add_u32_e32 v175, 0x2000, v151
	v_lshl_add_u64 v[176:177], v[248:249], 0, s[28:29]
	s_mov_b32 m0, s1
	v_readfirstlane_b32 s1, v175
	global_load_lds_dwordx4 v[176:177], off
	v_lshl_add_u64 v[176:177], v[250:251], 0, s[28:29]
	s_mov_b32 m0, s1
	s_nop 0
	global_load_lds_dwordx4 v[176:177], off
	s_waitcnt vmcnt(6)
	s_barrier
	v_mfma_f32_16x16x32_bf16 v[28:31], v[224:227], v[196:199], v[28:31]
	v_mfma_f32_16x16x32_bf16 v[24:27], v[232:235], v[196:199], v[24:27]
	v_mfma_f32_16x16x32_bf16 v[20:23], v[224:227], v[204:207], v[20:23]
	v_mfma_f32_16x16x32_bf16 v[16:19], v[232:235], v[204:207], v[16:19]
	v_mfma_f32_16x16x32_bf16 v[12:15], v[224:227], v[212:215], v[12:15]
	v_mfma_f32_16x16x32_bf16 v[8:11], v[232:235], v[212:215], v[8:11]
	v_mfma_f32_16x16x32_bf16 v[4:7], v[224:227], v[220:223], v[4:7]
	v_mfma_f32_16x16x32_bf16 v[0:3], v[232:235], v[220:223], v[0:3]
	v_mfma_f32_16x16x32_bf16 v[28:31], v[228:231], v[200:203], v[28:31]
	v_mfma_f32_16x16x32_bf16 v[24:27], v[236:239], v[200:203], v[24:27]
	v_mfma_f32_16x16x32_bf16 v[20:23], v[228:231], v[208:211], v[20:23]
	v_mfma_f32_16x16x32_bf16 v[16:19], v[236:239], v[208:211], v[16:19]
	v_mfma_f32_16x16x32_bf16 v[12:15], v[228:231], v[216:219], v[12:15]
	v_mfma_f32_16x16x32_bf16 v[8:11], v[236:239], v[216:219], v[8:11]
	v_mfma_f32_16x16x32_bf16 v[4:7], v[228:231], v[240:243], v[4:7]
	v_mfma_f32_16x16x32_bf16 v[0:3], v[236:239], v[240:243], v[0:3]
	s_barrier
	ds_read_b128 v[180:183], v163
	ds_read_b128 v[184:187], v163 offset:1024
	ds_read_b128 v[188:191], v163 offset:2048
	ds_read_b128 v[192:195], v163 offset:3072
	v_add_u32_e32 v176, 0x4000, v152
	v_add_u32_e32 v177, 0x6000, v152
	v_readfirstlane_b32 s1, v176
	v_lshl_add_u64 v[228:229], v[244:245], 0, s[30:31]
	s_mov_b32 m0, s1
	v_readfirstlane_b32 s1, v177
	ds_read_b128 v[196:199], v161 offset:32768
	ds_read_b128 v[200:203], v161 offset:33792
	ds_read_b128 v[204:207], v160 offset:32768
	ds_read_b128 v[208:211], v160 offset:33792
	ds_read_b128 v[212:215], v159 offset:32768
	ds_read_b128 v[216:219], v159 offset:33792
	ds_read_b128 v[220:223], v158 offset:32768
	ds_read_b128 v[224:227], v158 offset:33792
	global_load_lds_dwordx4 v[228:229], off
	v_lshl_add_u64 v[228:229], v[246:247], 0, s[30:31]
	s_mov_b32 m0, s1
	s_nop 0
	global_load_lds_dwordx4 v[228:229], off
	s_waitcnt lgkmcnt(8)
	s_barrier
	s_waitcnt lgkmcnt(0)
	v_mfma_f32_16x16x32_bf16 v[124:127], v[180:183], v[196:199], v[124:127]
	v_mfma_f32_16x16x32_bf16 v[120:123], v[188:191], v[196:199], v[120:123]
	v_mfma_f32_16x16x32_bf16 v[116:119], v[180:183], v[204:207], v[116:119]
	v_mfma_f32_16x16x32_bf16 v[112:115], v[188:191], v[204:207], v[112:115]
	v_mfma_f32_16x16x32_bf16 v[108:111], v[180:183], v[212:215], v[108:111]
	v_mfma_f32_16x16x32_bf16 v[104:107], v[188:191], v[212:215], v[104:107]
	v_mfma_f32_16x16x32_bf16 v[100:103], v[180:183], v[220:223], v[100:103]
	v_mfma_f32_16x16x32_bf16 v[96:99], v[188:191], v[220:223], v[96:99]
	v_mfma_f32_16x16x32_bf16 v[124:127], v[184:187], v[200:203], v[124:127]
	v_mfma_f32_16x16x32_bf16 v[120:123], v[192:195], v[200:203], v[120:123]
	v_mfma_f32_16x16x32_bf16 v[116:119], v[184:187], v[208:211], v[116:119]
	v_mfma_f32_16x16x32_bf16 v[112:115], v[192:195], v[208:211], v[112:115]
	v_mfma_f32_16x16x32_bf16 v[108:111], v[184:187], v[216:219], v[108:111]
	v_mfma_f32_16x16x32_bf16 v[104:107], v[192:195], v[216:219], v[104:107]
	v_mfma_f32_16x16x32_bf16 v[100:103], v[184:187], v[224:227], v[100:103]
	v_mfma_f32_16x16x32_bf16 v[96:99], v[192:195], v[224:227], v[96:99]
	s_barrier
	v_readfirstlane_b32 s1, v167
	v_add_u32_e32 v254, 0x2000, v167
	v_lshl_add_u64 v[252:253], v[248:249], 0, s[34:35]
	s_mov_b32 m0, s1
	v_readfirstlane_b32 s1, v254
	ds_read_b128 v[228:231], v162
	ds_read_b128 v[232:235], v162 offset:1024
	ds_read_b128 v[236:239], v162 offset:2048
	ds_read_b128 v[240:243], v162 offset:3072
	global_load_lds_dwordx4 v[252:253], off
	v_lshl_add_u64 v[252:253], v[250:251], 0, s[34:35]
	s_mov_b32 m0, s1
	s_nop 0
	global_load_lds_dwordx4 v[252:253], off
	s_barrier
	s_waitcnt lgkmcnt(0)
	v_mfma_f32_16x16x32_bf16 v[92:95], v[228:231], v[196:199], v[92:95]
	v_mfma_f32_16x16x32_bf16 v[88:91], v[236:239], v[196:199], v[88:91]
	v_mfma_f32_16x16x32_bf16 v[84:87], v[228:231], v[204:207], v[84:87]
	v_mfma_f32_16x16x32_bf16 v[80:83], v[236:239], v[204:207], v[80:83]
	v_mfma_f32_16x16x32_bf16 v[76:79], v[228:231], v[212:215], v[76:79]
	v_mfma_f32_16x16x32_bf16 v[72:75], v[236:239], v[212:215], v[72:75]
	v_mfma_f32_16x16x32_bf16 v[68:71], v[228:231], v[220:223], v[68:71]
	v_mfma_f32_16x16x32_bf16 v[64:67], v[236:239], v[220:223], v[64:67]
	v_mfma_f32_16x16x32_bf16 v[92:95], v[232:235], v[200:203], v[92:95]
	v_mfma_f32_16x16x32_bf16 v[88:91], v[240:243], v[200:203], v[88:91]
	v_mfma_f32_16x16x32_bf16 v[84:87], v[232:235], v[208:211], v[84:87]
	v_mfma_f32_16x16x32_bf16 v[80:83], v[240:243], v[208:211], v[80:83]
	v_mfma_f32_16x16x32_bf16 v[76:79], v[232:235], v[216:219], v[76:79]
	v_mfma_f32_16x16x32_bf16 v[72:75], v[240:243], v[216:219], v[72:75]
	v_mfma_f32_16x16x32_bf16 v[68:71], v[232:235], v[224:227], v[68:71]
	v_mfma_f32_16x16x32_bf16 v[64:67], v[240:243], v[224:227], v[64:67]
	v_readfirstlane_b32 s1, v168
	v_lshl_add_u64 v[244:245], v[244:245], 0, s[36:37]
	s_mov_b32 m0, s1
	v_readfirstlane_b32 s1, v170
	s_barrier
	ds_read_b128 v[196:199], v161 offset:49152
	ds_read_b128 v[200:203], v161 offset:50176
	ds_read_b128 v[204:207], v160 offset:49152
	ds_read_b128 v[208:211], v160 offset:50176
	ds_read_b128 v[212:215], v159 offset:49152
	ds_read_b128 v[216:219], v159 offset:50176
	ds_read_b128 v[220:223], v158 offset:49152
	ds_read_b128 v[224:227], v158 offset:50176
	global_load_lds_dwordx4 v[244:245], off
	v_lshl_add_u64 v[244:245], v[246:247], 0, s[36:37]
	s_mov_b32 m0, s1
	s_nop 0
	global_load_lds_dwordx4 v[244:245], off
	s_barrier
	s_waitcnt lgkmcnt(0)
	v_mfma_f32_16x16x32_bf16 v[60:63], v[180:183], v[196:199], v[60:63]
	v_mfma_f32_16x16x32_bf16 v[56:59], v[188:191], v[196:199], v[56:59]
	v_mfma_f32_16x16x32_bf16 v[52:55], v[180:183], v[204:207], v[52:55]
	v_mfma_f32_16x16x32_bf16 v[48:51], v[188:191], v[204:207], v[48:51]
	v_mfma_f32_16x16x32_bf16 v[44:47], v[180:183], v[212:215], v[44:47]
	v_mfma_f32_16x16x32_bf16 v[40:43], v[188:191], v[212:215], v[40:43]
	v_mfma_f32_16x16x32_bf16 v[36:39], v[180:183], v[220:223], v[36:39]
	v_mfma_f32_16x16x32_bf16 v[32:35], v[188:191], v[220:223], v[32:35]
	v_mfma_f32_16x16x32_bf16 v[60:63], v[184:187], v[200:203], v[60:63]
	v_mfma_f32_16x16x32_bf16 v[56:59], v[192:195], v[200:203], v[56:59]
	v_mfma_f32_16x16x32_bf16 v[52:55], v[184:187], v[208:211], v[52:55]
	v_mfma_f32_16x16x32_bf16 v[48:51], v[192:195], v[208:211], v[48:51]
	v_mfma_f32_16x16x32_bf16 v[44:47], v[184:187], v[216:219], v[44:47]
	v_mfma_f32_16x16x32_bf16 v[40:43], v[192:195], v[216:219], v[40:43]
	v_mfma_f32_16x16x32_bf16 v[36:39], v[184:187], v[224:227], v[36:39]
	v_mfma_f32_16x16x32_bf16 v[32:35], v[192:195], v[224:227], v[32:35]
	s_barrier
	v_readfirstlane_b32 s1, v171
	v_add_u32_e32 v182, 0x2000, v171
	v_lshl_add_u64 v[180:181], v[248:249], 0, s[38:39]
	s_mov_b32 m0, s1
	v_readfirstlane_b32 s1, v182
	global_load_lds_dwordx4 v[180:181], off
	v_lshl_add_u64 v[180:181], v[250:251], 0, s[38:39]
	s_mov_b32 m0, s1
	s_nop 0
	global_load_lds_dwordx4 v[180:181], off
	s_add_i32 s0, s0, 2
	v_lshl_add_u64 v[142:143], v[142:143], 0, s[46:47]
	v_lshl_add_u64 v[144:145], v[144:145], 0, s[46:47]
	v_lshl_add_u64 v[146:147], v[146:147], 0, s[46:47]
	s_cmp_lt_u32 s0, 12
	v_lshl_add_u64 v[148:149], v[148:149], 0, s[46:47]
	s_waitcnt vmcnt(6)
	s_barrier
	v_mfma_f32_16x16x32_bf16 v[28:31], v[228:231], v[196:199], v[28:31]
	v_mfma_f32_16x16x32_bf16 v[24:27], v[236:239], v[196:199], v[24:27]
	v_mfma_f32_16x16x32_bf16 v[20:23], v[228:231], v[204:207], v[20:23]
	v_mfma_f32_16x16x32_bf16 v[16:19], v[236:239], v[204:207], v[16:19]
	v_mfma_f32_16x16x32_bf16 v[12:15], v[228:231], v[212:215], v[12:15]
	v_mfma_f32_16x16x32_bf16 v[8:11], v[236:239], v[212:215], v[8:11]
	v_mfma_f32_16x16x32_bf16 v[4:7], v[228:231], v[220:223], v[4:7]
	v_mfma_f32_16x16x32_bf16 v[0:3], v[236:239], v[220:223], v[0:3]
	v_mfma_f32_16x16x32_bf16 v[28:31], v[232:235], v[200:203], v[28:31]
	v_mfma_f32_16x16x32_bf16 v[24:27], v[240:243], v[200:203], v[24:27]
	v_mfma_f32_16x16x32_bf16 v[20:23], v[232:235], v[208:211], v[20:23]
	v_mfma_f32_16x16x32_bf16 v[16:19], v[240:243], v[208:211], v[16:19]
	v_mfma_f32_16x16x32_bf16 v[12:15], v[232:235], v[216:219], v[12:15]
	v_mfma_f32_16x16x32_bf16 v[8:11], v[240:243], v[216:219], v[8:11]
	v_mfma_f32_16x16x32_bf16 v[4:7], v[232:235], v[224:227], v[4:7]
	v_mfma_f32_16x16x32_bf16 v[0:3], v[240:243], v[224:227], v[0:3]
	s_barrier
	s_cbranch_scc1 .LBB0_1842
	s_or_b32 s0, s8, 0x80
	s_ashr_i32 s1, s0, 31
	s_lshl_b64 s[0:1], s[0:1], 11
	s_add_u32 s0, s45, s0
	s_addc_u32 s1, s64, s1
	v_lshl_add_u64 v[170:171], s[0:1], 0, v[130:131]
	v_lshl_add_u64 v[138:139], v[138:139], 1, v[170:171]
	v_readfirstlane_b32 s2, v178
	v_lshl_add_u64 v[138:139], v[138:139], 0, s[58:59]
	s_mov_b32 m0, s2
	ds_read_b128 v[142:145], v172
	ds_read_b128 v[146:149], v172 offset:1024
	ds_read_b128 v[180:183], v172 offset:2048
	ds_read_b128 v[184:187], v172 offset:3072
	ds_read_b128 v[188:191], v161
	ds_read_b128 v[192:195], v161 offset:1024
	ds_read_b128 v[196:199], v160
	ds_read_b128 v[200:203], v160 offset:1024
	ds_read_b128 v[204:207], v159
	ds_read_b128 v[208:211], v159 offset:1024
	ds_read_b128 v[212:215], v158
	ds_read_b128 v[216:219], v158 offset:1024
	global_load_lds_dwordx4 v[138:139], off
	v_lshl_add_u64 v[138:139], s[0:1], 0, v[134:135]
	v_lshl_add_u64 v[138:139], v[140:141], 1, v[138:139]
	v_readfirstlane_b32 s0, v179
	v_lshl_add_u64 v[138:139], v[138:139], 0, s[58:59]
	s_mov_b32 m0, s0
	v_readlane_b32 s0, v255, 11
	global_load_lds_dwordx4 v[138:139], off
	s_add_i32 s79, s79, s0
	s_barrier
	s_waitcnt lgkmcnt(0)
	s_cmpk_gt_i32 s79, 0x54
	s_cselect_b64 s[60:61], -1, 0
	s_waitcnt lgkmcnt(0)
	v_mfma_f32_16x16x32_bf16 v[124:127], v[142:145], v[188:191], v[124:127]
	v_mfma_f32_16x16x32_bf16 v[116:119], v[142:145], v[196:199], v[116:119]
	v_mfma_f32_16x16x32_bf16 v[108:111], v[142:145], v[204:207], v[108:111]
	v_mfma_f32_16x16x32_bf16 v[100:103], v[142:145], v[212:215], v[100:103]
	v_mfma_f32_16x16x32_bf16 v[124:127], v[146:149], v[192:195], v[124:127]
	v_mfma_f32_16x16x32_bf16 v[120:123], v[180:183], v[188:191], v[120:123]
	v_mfma_f32_16x16x32_bf16 v[116:119], v[146:149], v[200:203], v[116:119]
	v_mfma_f32_16x16x32_bf16 v[112:115], v[180:183], v[196:199], v[112:115]
	v_mfma_f32_16x16x32_bf16 v[108:111], v[146:149], v[208:211], v[108:111]
	v_mfma_f32_16x16x32_bf16 v[104:107], v[180:183], v[204:207], v[104:107]
	v_mfma_f32_16x16x32_bf16 v[100:103], v[146:149], v[216:219], v[100:103]
	v_mfma_f32_16x16x32_bf16 v[96:99], v[180:183], v[212:215], v[96:99]
	v_mfma_f32_16x16x32_bf16 v[138:141], v[184:187], v[192:195], v[120:123]
	v_mfma_f32_16x16x32_bf16 v[220:223], v[184:187], v[200:203], v[112:115]
	v_mfma_f32_16x16x32_bf16 v[224:227], v[184:187], v[208:211], v[104:107]
	v_mfma_f32_16x16x32_bf16 v[228:231], v[184:187], v[216:219], v[96:99]
	s_barrier
	s_nop 1
	ds_read_b128 v[96:99], v169
	ds_read_b128 v[104:107], v169 offset:1024
	ds_read_b128 v[112:115], v169 offset:2048
	ds_read_b128 v[120:123], v169 offset:3072
	s_barrier
	s_waitcnt lgkmcnt(0)
	v_mfma_f32_16x16x32_bf16 v[92:95], v[96:99], v[188:191], v[92:95]
	v_mfma_f32_16x16x32_bf16 v[88:91], v[112:115], v[188:191], v[88:91]
	v_mfma_f32_16x16x32_bf16 v[84:87], v[96:99], v[196:199], v[84:87]
	v_mfma_f32_16x16x32_bf16 v[80:83], v[112:115], v[196:199], v[80:83]
	v_mfma_f32_16x16x32_bf16 v[76:79], v[96:99], v[204:207], v[76:79]
	v_mfma_f32_16x16x32_bf16 v[72:75], v[112:115], v[204:207], v[72:75]
	v_mfma_f32_16x16x32_bf16 v[68:71], v[96:99], v[212:215], v[68:71]
	v_mfma_f32_16x16x32_bf16 v[64:67], v[112:115], v[212:215], v[64:67]
	v_mfma_f32_16x16x32_bf16 v[92:95], v[104:107], v[192:195], v[92:95]
	v_mfma_f32_16x16x32_bf16 v[88:91], v[120:123], v[192:195], v[88:91]
	v_mfma_f32_16x16x32_bf16 v[84:87], v[104:107], v[200:203], v[84:87]
	v_mfma_f32_16x16x32_bf16 v[80:83], v[120:123], v[200:203], v[80:83]
	v_mfma_f32_16x16x32_bf16 v[76:79], v[104:107], v[208:211], v[76:79]
	v_mfma_f32_16x16x32_bf16 v[72:75], v[120:123], v[208:211], v[72:75]
	v_mfma_f32_16x16x32_bf16 v[68:71], v[104:107], v[216:219], v[68:71]
	v_mfma_f32_16x16x32_bf16 v[64:67], v[120:123], v[216:219], v[64:67]
	s_barrier
	ds_read_b128 v[168:171], v161 offset:16384
	ds_read_b128 v[188:191], v161 offset:17408
	ds_read_b128 v[192:195], v160 offset:16384
	ds_read_b128 v[196:199], v160 offset:17408
	ds_read_b128 v[200:203], v159 offset:16384
	ds_read_b128 v[204:207], v159 offset:17408
	ds_read_b128 v[208:211], v158 offset:16384
	ds_read_b128 v[212:215], v158 offset:17408
	s_waitcnt vmcnt(4)
	s_barrier
	s_waitcnt lgkmcnt(0)
	v_mfma_f32_16x16x32_bf16 v[60:63], v[142:145], v[168:171], v[60:63]
	v_mfma_f32_16x16x32_bf16 v[52:55], v[142:145], v[192:195], v[52:55]
	v_mfma_f32_16x16x32_bf16 v[44:47], v[142:145], v[200:203], v[44:47]
	v_mfma_f32_16x16x32_bf16 v[36:39], v[142:145], v[208:211], v[36:39]
	v_mfma_f32_16x16x32_bf16 v[60:63], v[146:149], v[188:191], v[60:63]
	v_mfma_f32_16x16x32_bf16 v[56:59], v[180:183], v[168:171], v[56:59]
	v_mfma_f32_16x16x32_bf16 v[52:55], v[146:149], v[196:199], v[52:55]
	v_mfma_f32_16x16x32_bf16 v[48:51], v[180:183], v[192:195], v[48:51]
	v_mfma_f32_16x16x32_bf16 v[44:47], v[146:149], v[204:207], v[44:47]
	v_mfma_f32_16x16x32_bf16 v[40:43], v[180:183], v[200:203], v[40:43]
	v_mfma_f32_16x16x32_bf16 v[36:39], v[146:149], v[212:215], v[36:39]
	v_mfma_f32_16x16x32_bf16 v[32:35], v[180:183], v[208:211], v[32:35]
	v_mfma_f32_16x16x32_bf16 v[216:219], v[184:187], v[188:191], v[56:59]
	v_mfma_f32_16x16x32_bf16 v[232:235], v[184:187], v[196:199], v[48:51]
	v_mfma_f32_16x16x32_bf16 v[236:239], v[184:187], v[204:207], v[40:43]
	v_mfma_f32_16x16x32_bf16 v[142:145], v[184:187], v[212:215], v[32:35]
	v_mfma_f32_16x16x32_bf16 v[28:31], v[96:99], v[168:171], v[28:31]
	v_mfma_f32_16x16x32_bf16 v[24:27], v[112:115], v[168:171], v[24:27]
	v_mfma_f32_16x16x32_bf16 v[20:23], v[96:99], v[192:195], v[20:23]
	v_mfma_f32_16x16x32_bf16 v[16:19], v[112:115], v[192:195], v[16:19]
	v_mfma_f32_16x16x32_bf16 v[12:15], v[96:99], v[200:203], v[12:15]
	v_mfma_f32_16x16x32_bf16 v[8:11], v[112:115], v[200:203], v[8:11]
	v_mfma_f32_16x16x32_bf16 v[4:7], v[96:99], v[208:211], v[4:7]
	v_mfma_f32_16x16x32_bf16 v[0:3], v[112:115], v[208:211], v[0:3]
	v_mfma_f32_16x16x32_bf16 v[28:31], v[104:107], v[188:191], v[28:31]
	v_mfma_f32_16x16x32_bf16 v[24:27], v[120:123], v[188:191], v[24:27]
	v_mfma_f32_16x16x32_bf16 v[20:23], v[104:107], v[196:199], v[20:23]
	v_mfma_f32_16x16x32_bf16 v[16:19], v[120:123], v[196:199], v[16:19]
	v_mfma_f32_16x16x32_bf16 v[12:15], v[104:107], v[204:207], v[12:15]
	v_mfma_f32_16x16x32_bf16 v[8:11], v[120:123], v[204:207], v[8:11]
	v_mfma_f32_16x16x32_bf16 v[4:7], v[104:107], v[212:215], v[4:7]
	v_mfma_f32_16x16x32_bf16 v[0:3], v[120:123], v[212:215], v[0:3]
	s_barrier
	ds_read_b128 v[32:35], v163
	ds_read_b128 v[146:149], v163 offset:1024
	ds_read_b128 v[168:171], v163 offset:2048
	ds_read_b128 v[178:181], v163 offset:3072
	ds_read_b128 v[40:43], v161 offset:32768
	ds_read_b128 v[48:51], v161 offset:33792
	ds_read_b128 v[56:59], v160 offset:32768
	ds_read_b128 v[182:185], v160 offset:33792
	ds_read_b128 v[186:189], v159 offset:32768
	ds_read_b128 v[190:193], v159 offset:33792
	ds_read_b128 v[194:197], v158 offset:32768
	ds_read_b128 v[198:201], v158 offset:33792
	s_waitcnt vmcnt(2)
	s_barrier
	s_waitcnt lgkmcnt(0)
	v_mfma_f32_16x16x32_bf16 v[96:99], v[32:35], v[40:43], v[124:127]
	v_mfma_f32_16x16x32_bf16 v[120:123], v[146:149], v[48:51], v[96:99]
	v_mfma_f32_16x16x32_bf16 v[96:99], v[168:171], v[40:43], v[138:141]
	v_mfma_f32_16x16x32_bf16 v[124:127], v[178:181], v[48:51], v[96:99]
	v_mfma_f32_16x16x32_bf16 v[96:99], v[32:35], v[56:59], v[116:119]
	v_mfma_f32_16x16x32_bf16 v[112:115], v[146:149], v[182:185], v[96:99]
	v_mfma_f32_16x16x32_bf16 v[96:99], v[168:171], v[56:59], v[220:223]
	v_mfma_f32_16x16x32_bf16 v[116:119], v[178:181], v[182:185], v[96:99]
	v_mfma_f32_16x16x32_bf16 v[96:99], v[32:35], v[186:189], v[108:111]
	v_mfma_f32_16x16x32_bf16 v[104:107], v[146:149], v[190:193], v[96:99]
	v_mfma_f32_16x16x32_bf16 v[96:99], v[168:171], v[186:189], v[224:227]
	v_mfma_f32_16x16x32_bf16 v[108:111], v[178:181], v[190:193], v[96:99]
	v_mfma_f32_16x16x32_bf16 v[96:99], v[32:35], v[194:197], v[100:103]
	v_mfma_f32_16x16x32_bf16 v[100:103], v[168:171], v[194:197], v[228:231]
	v_mfma_f32_16x16x32_bf16 v[96:99], v[146:149], v[198:201], v[96:99]
	v_mfma_f32_16x16x32_bf16 v[100:103], v[178:181], v[198:201], v[100:103]
	s_barrier
	ds_read_b128 v[138:141], v162
	ds_read_b128 v[202:205], v162 offset:1024
	ds_read_b128 v[206:209], v162 offset:2048
	ds_read_b128 v[210:213], v162 offset:3072
	s_waitcnt vmcnt(0)
	s_barrier
	s_waitcnt lgkmcnt(0)
	v_mfma_f32_16x16x32_bf16 v[92:95], v[138:141], v[40:43], v[92:95]
	v_mfma_f32_16x16x32_bf16 v[40:43], v[206:209], v[40:43], v[88:91]
	v_mfma_f32_16x16x32_bf16 v[88:91], v[210:213], v[48:51], v[40:43]
	v_mfma_f32_16x16x32_bf16 v[40:43], v[138:141], v[56:59], v[84:87]
	v_mfma_f32_16x16x32_bf16 v[84:87], v[202:205], v[182:185], v[40:43]
	v_mfma_f32_16x16x32_bf16 v[40:43], v[206:209], v[56:59], v[80:83]
	v_mfma_f32_16x16x32_bf16 v[80:83], v[210:213], v[182:185], v[40:43]
	v_mfma_f32_16x16x32_bf16 v[40:43], v[138:141], v[186:189], v[76:79]
	v_mfma_f32_16x16x32_bf16 v[76:79], v[202:205], v[190:193], v[40:43]
	v_mfma_f32_16x16x32_bf16 v[40:43], v[206:209], v[186:189], v[72:75]
	v_mfma_f32_16x16x32_bf16 v[72:75], v[210:213], v[190:193], v[40:43]
	v_mfma_f32_16x16x32_bf16 v[40:43], v[138:141], v[194:197], v[68:71]
	v_mfma_f32_16x16x32_bf16 v[68:71], v[202:205], v[198:201], v[40:43]
	v_mfma_f32_16x16x32_bf16 v[40:43], v[206:209], v[194:197], v[64:67]
	v_mfma_f32_16x16x32_bf16 v[92:95], v[202:205], v[48:51], v[92:95]
	v_mfma_f32_16x16x32_bf16 v[64:67], v[210:213], v[198:201], v[40:43]
	s_barrier
	ds_read_b128 v[182:185], v161 offset:49152
	ds_read_b128 v[186:189], v161 offset:50176
	ds_read_b128 v[190:193], v160 offset:49152
	ds_read_b128 v[160:163], v160 offset:50176
	ds_read_b128 v[194:197], v159 offset:49152
	ds_read_b128 v[198:201], v159 offset:50176
	ds_read_b128 v[220:223], v158 offset:49152
	ds_read_b128 v[224:227], v158 offset:50176
	s_barrier
	s_waitcnt lgkmcnt(0)
	v_mfma_f32_16x16x32_bf16 v[40:43], v[32:35], v[182:185], v[60:63]
	v_mfma_f32_16x16x32_bf16 v[56:59], v[146:149], v[186:189], v[40:43]
	v_mfma_f32_16x16x32_bf16 v[40:43], v[168:171], v[182:185], v[216:219]
	v_mfma_f32_16x16x32_bf16 v[60:63], v[178:181], v[186:189], v[40:43]
	v_mfma_f32_16x16x32_bf16 v[40:43], v[32:35], v[190:193], v[52:55]
	v_mfma_f32_16x16x32_bf16 v[48:51], v[146:149], v[160:163], v[40:43]
	v_mfma_f32_16x16x32_bf16 v[40:43], v[168:171], v[190:193], v[232:235]
	v_mfma_f32_16x16x32_bf16 v[52:55], v[178:181], v[160:163], v[40:43]
	v_mfma_f32_16x16x32_bf16 v[40:43], v[32:35], v[194:197], v[44:47]
	v_mfma_f32_16x16x32_bf16 v[44:47], v[168:171], v[194:197], v[236:239]
	v_mfma_f32_16x16x32_bf16 v[32:35], v[32:35], v[220:223], v[36:39]
	v_mfma_f32_16x16x32_bf16 v[36:39], v[168:171], v[220:223], v[142:145]
	v_mfma_f32_16x16x32_bf16 v[40:43], v[146:149], v[198:201], v[40:43]
	v_mfma_f32_16x16x32_bf16 v[44:47], v[178:181], v[198:201], v[44:47]
	v_mfma_f32_16x16x32_bf16 v[32:35], v[146:149], v[224:227], v[32:35]
	v_mfma_f32_16x16x32_bf16 v[36:39], v[178:181], v[224:227], v[36:39]
	v_mfma_f32_16x16x32_bf16 v[28:31], v[138:141], v[182:185], v[28:31]
	v_mfma_f32_16x16x32_bf16 v[24:27], v[206:209], v[182:185], v[24:27]
	v_mfma_f32_16x16x32_bf16 v[20:23], v[138:141], v[190:193], v[20:23]
	v_mfma_f32_16x16x32_bf16 v[16:19], v[206:209], v[190:193], v[16:19]
	v_mfma_f32_16x16x32_bf16 v[12:15], v[138:141], v[194:197], v[12:15]
	v_mfma_f32_16x16x32_bf16 v[8:11], v[206:209], v[194:197], v[8:11]
	v_mfma_f32_16x16x32_bf16 v[4:7], v[138:141], v[220:223], v[4:7]
	v_mfma_f32_16x16x32_bf16 v[0:3], v[206:209], v[220:223], v[0:3]
	v_mfma_f32_16x16x32_bf16 v[28:31], v[202:205], v[186:189], v[28:31]
	v_mfma_f32_16x16x32_bf16 v[24:27], v[210:213], v[186:189], v[24:27]
	v_mfma_f32_16x16x32_bf16 v[20:23], v[202:205], v[160:163], v[20:23]
	v_mfma_f32_16x16x32_bf16 v[16:19], v[210:213], v[160:163], v[16:19]
	v_mfma_f32_16x16x32_bf16 v[12:15], v[202:205], v[198:201], v[12:15]
	v_mfma_f32_16x16x32_bf16 v[8:11], v[210:213], v[198:201], v[8:11]
	v_mfma_f32_16x16x32_bf16 v[4:7], v[202:205], v[224:227], v[4:7]
	v_mfma_f32_16x16x32_bf16 v[0:3], v[210:213], v[224:227], v[0:3]
	s_and_b64 vcc, exec, s[60:61]
	s_barrier
	s_cbranch_vccnz .LBB0_1845
	s_mul_hi_i32 s0, s79, 0x66666667
	s_lshr_b32 s1, s0, 31
	s_ashr_i32 s0, s0, 1
	s_add_i32 s0, s0, s1
	v_readlane_b32 s1, v255, 15
	s_add_i32 s1, s0, s1
	s_mul_i32 s0, s0, 5
	s_sub_i32 s0, s79, s0
	v_readlane_b32 s2, v255, 14
	s_add_i32 s2, s0, s2
	s_lshl_b32 s4, s2, 8
	s_ashr_i32 s5, s4, 31
	s_lshl_b32 s0, s1, 8
	s_lshl_b64 s[10:11], s[4:5], 11
	s_add_u32 s10, s65, s10
	s_addc_u32 s11, s66, s11
	v_lshl_add_u64 v[138:139], s[10:11], 0, v[130:131]
	v_readfirstlane_b32 s1, v153
	v_lshl_add_u64 v[138:139], v[138:139], 0, v[132:133]
	s_mov_b32 m0, s1
	v_readfirstlane_b32 s1, v173
	global_load_lds_dwordx4 v[138:139], off
	s_mov_b32 m0, s1
	s_ashr_i32 s1, s0, 31
	v_lshl_add_u64 v[138:139], s[10:11], 0, v[134:135]
	s_lshl_b64 s[10:11], s[0:1], 11
	s_add_u32 s10, s45, s10
	v_lshl_add_u64 v[138:139], v[138:139], 0, v[136:137]
	s_addc_u32 s11, s64, s11
	s_bitset1_b32 s4, 7
	global_load_lds_dwordx4 v[138:139], off
	v_lshl_add_u64 v[138:139], s[10:11], 0, v[130:131]
	v_readfirstlane_b32 s1, v152
	s_ashr_i32 s5, s4, 31
	v_lshl_add_u64 v[138:139], v[138:139], 0, v[132:133]
	s_mov_b32 m0, s1
	s_lshl_b64 s[4:5], s[4:5], 11
	global_load_lds_dwordx4 v[138:139], off
	v_lshl_add_u64 v[138:139], s[10:11], 0, v[134:135]
	v_readfirstlane_b32 s1, v174
	s_add_u32 s4, s65, s4
	v_lshl_add_u64 v[138:139], v[138:139], 0, v[136:137]
	s_mov_b32 m0, s1
	s_addc_u32 s5, s66, s5
	global_load_lds_dwordx4 v[138:139], off
	v_lshl_add_u64 v[138:139], s[4:5], 0, v[130:131]
	v_readfirstlane_b32 s1, v151
	v_lshl_add_u64 v[138:139], v[138:139], 0, v[132:133]
	s_mov_b32 m0, s1
	v_readfirstlane_b32 s1, v175
	s_bitset1_b32 s0, 7
	global_load_lds_dwordx4 v[138:139], off
	s_mov_b32 m0, s1
	s_ashr_i32 s1, s0, 31
	s_lshl_b64 s[0:1], s[0:1], 11
	s_add_u32 s0, s45, s0
	v_lshl_add_u64 v[138:139], s[4:5], 0, v[134:135]
	s_addc_u32 s1, s64, s1
	v_lshl_add_u64 v[138:139], v[138:139], 0, v[136:137]
	v_lshl_add_u64 v[130:131], s[0:1], 0, v[130:131]
	v_readfirstlane_b32 s2, v176
	global_load_lds_dwordx4 v[138:139], off
	v_lshl_add_u64 v[130:131], v[130:131], 0, v[132:133]
	s_mov_b32 m0, s2
	s_nop 0
	global_load_lds_dwordx4 v[130:131], off
	v_lshl_add_u64 v[130:131], s[0:1], 0, v[134:135]
	v_readfirstlane_b32 s0, v177
	v_lshl_add_u64 v[130:131], v[130:131], 0, v[136:137]
	s_mov_b32 m0, s0
	s_nop 0
	global_load_lds_dwordx4 v[130:131], off

.LBB0_2916:
	ds_read_b128 v[180:183], v172
	ds_read_b128 v[184:187], v172 offset:1024
	ds_read_b128 v[188:191], v172 offset:2048
	ds_read_b128 v[192:195], v172 offset:3072
	v_add_u32_e32 v178, 0xc000, v152
	v_lshl_add_u64 v[244:245], s[6:7], 0, v[146:147]
	v_readfirstlane_b32 s4, v178
	v_add_u32_e32 v179, 0xe000, v152
	v_lshl_add_u64 v[224:225], v[244:245], 0, s[12:13]
	s_mov_b32 m0, s4
	v_lshl_add_u64 v[246:247], s[6:7], 0, v[148:149]
	v_readfirstlane_b32 s4, v179
	ds_read_b128 v[174:177], v161
	ds_read_b128 v[196:199], v161 offset:1024
	ds_read_b128 v[200:203], v160
	ds_read_b128 v[204:207], v160 offset:1024
	ds_read_b128 v[208:211], v159
	ds_read_b128 v[212:215], v159 offset:1024
	ds_read_b128 v[216:219], v158
	ds_read_b128 v[220:223], v158 offset:1024
	global_load_lds_dwordx4 v[224:225], off
	v_lshl_add_u64 v[224:225], v[246:247], 0, s[12:13]
	s_mov_b32 m0, s4
	s_nop 0
	global_load_lds_dwordx4 v[224:225], off
	s_waitcnt lgkmcnt(8)
	s_barrier
	s_waitcnt lgkmcnt(0)
	v_mfma_f32_16x16x32_bf16 v[124:127], v[180:183], v[174:177], v[124:127]
	v_mfma_f32_16x16x32_bf16 v[120:123], v[188:191], v[174:177], v[120:123]
	v_mfma_f32_16x16x32_bf16 v[116:119], v[180:183], v[200:203], v[116:119]
	v_mfma_f32_16x16x32_bf16 v[112:115], v[188:191], v[200:203], v[112:115]
	v_mfma_f32_16x16x32_bf16 v[108:111], v[180:183], v[208:211], v[108:111]
	v_mfma_f32_16x16x32_bf16 v[104:107], v[188:191], v[208:211], v[104:107]
	v_mfma_f32_16x16x32_bf16 v[100:103], v[180:183], v[216:219], v[100:103]
	v_mfma_f32_16x16x32_bf16 v[96:99], v[188:191], v[216:219], v[96:99]
	v_mfma_f32_16x16x32_bf16 v[124:127], v[184:187], v[196:199], v[124:127]
	v_mfma_f32_16x16x32_bf16 v[120:123], v[192:195], v[196:199], v[120:123]
	v_mfma_f32_16x16x32_bf16 v[116:119], v[184:187], v[204:207], v[116:119]
	v_mfma_f32_16x16x32_bf16 v[112:115], v[192:195], v[204:207], v[112:115]
	v_mfma_f32_16x16x32_bf16 v[108:111], v[184:187], v[212:215], v[108:111]
	v_mfma_f32_16x16x32_bf16 v[104:107], v[192:195], v[212:215], v[104:107]
	v_mfma_f32_16x16x32_bf16 v[100:103], v[184:187], v[220:223], v[100:103]
	v_mfma_f32_16x16x32_bf16 v[96:99], v[192:195], v[220:223], v[96:99]
	s_barrier
	v_lshl_add_u64 v[248:249], s[6:7], 0, v[142:143]
	v_readfirstlane_b32 s4, v153
	v_add_u32_e32 v173, 0x2000, v153
	v_lshl_add_u64 v[240:241], v[248:249], 0, s[14:15]
	s_mov_b32 m0, s4
	v_lshl_add_u64 v[250:251], s[6:7], 0, v[144:145]
	v_readfirstlane_b32 s4, v173
	ds_read_b128 v[224:227], v168
	ds_read_b128 v[228:231], v168 offset:1024
	ds_read_b128 v[232:235], v168 offset:2048
	ds_read_b128 v[236:239], v168 offset:3072
	global_load_lds_dwordx4 v[240:241], off
	v_lshl_add_u64 v[240:241], v[250:251], 0, s[14:15]
	s_mov_b32 m0, s4
	s_nop 0
	global_load_lds_dwordx4 v[240:241], off
	s_barrier
	s_waitcnt lgkmcnt(0)
	v_mfma_f32_16x16x32_bf16 v[92:95], v[224:227], v[174:177], v[92:95]
	v_mfma_f32_16x16x32_bf16 v[88:91], v[232:235], v[174:177], v[88:91]
	v_mfma_f32_16x16x32_bf16 v[84:87], v[224:227], v[200:203], v[84:87]
	v_mfma_f32_16x16x32_bf16 v[80:83], v[232:235], v[200:203], v[80:83]
	v_mfma_f32_16x16x32_bf16 v[76:79], v[224:227], v[208:211], v[76:79]
	v_mfma_f32_16x16x32_bf16 v[72:75], v[232:235], v[208:211], v[72:75]
	v_mfma_f32_16x16x32_bf16 v[68:71], v[224:227], v[216:219], v[68:71]
	v_mfma_f32_16x16x32_bf16 v[64:67], v[232:235], v[216:219], v[64:67]
	v_mfma_f32_16x16x32_bf16 v[92:95], v[228:231], v[196:199], v[92:95]
	v_mfma_f32_16x16x32_bf16 v[88:91], v[236:239], v[196:199], v[88:91]
	v_mfma_f32_16x16x32_bf16 v[84:87], v[228:231], v[204:207], v[84:87]
	v_mfma_f32_16x16x32_bf16 v[80:83], v[236:239], v[204:207], v[80:83]
	v_mfma_f32_16x16x32_bf16 v[76:79], v[228:231], v[212:215], v[76:79]
	v_mfma_f32_16x16x32_bf16 v[72:75], v[236:239], v[212:215], v[72:75]
	v_mfma_f32_16x16x32_bf16 v[68:71], v[228:231], v[220:223], v[68:71]
	v_mfma_f32_16x16x32_bf16 v[64:67], v[236:239], v[220:223], v[64:67]
	v_readfirstlane_b32 s4, v152
	v_lshl_add_u64 v[174:175], v[244:245], 0, s[16:17]
	s_mov_b32 m0, s4
	s_barrier
	ds_read_b128 v[196:199], v161 offset:16384
	ds_read_b128 v[200:203], v161 offset:17408
	ds_read_b128 v[204:207], v160 offset:16384
	ds_read_b128 v[208:211], v160 offset:17408
	ds_read_b128 v[212:215], v159 offset:16384
	ds_read_b128 v[216:219], v159 offset:17408
	ds_read_b128 v[220:223], v158 offset:16384
	ds_read_b128 v[240:243], v158 offset:17408
	global_load_lds_dwordx4 v[174:175], off
	v_add_u32_e32 v174, 0x2000, v152
	v_lshl_add_u64 v[176:177], v[246:247], 0, s[16:17]
	v_readfirstlane_b32 s4, v174
	s_mov_b32 m0, s4
	s_nop 0
	global_load_lds_dwordx4 v[176:177], off
	s_barrier
	s_waitcnt lgkmcnt(0)
	v_mfma_f32_16x16x32_bf16 v[60:63], v[180:183], v[196:199], v[60:63]
	v_mfma_f32_16x16x32_bf16 v[56:59], v[188:191], v[196:199], v[56:59]
	v_mfma_f32_16x16x32_bf16 v[52:55], v[180:183], v[204:207], v[52:55]
	v_mfma_f32_16x16x32_bf16 v[48:51], v[188:191], v[204:207], v[48:51]
	v_mfma_f32_16x16x32_bf16 v[44:47], v[180:183], v[212:215], v[44:47]
	v_mfma_f32_16x16x32_bf16 v[40:43], v[188:191], v[212:215], v[40:43]
	v_mfma_f32_16x16x32_bf16 v[36:39], v[180:183], v[220:223], v[36:39]
	v_mfma_f32_16x16x32_bf16 v[32:35], v[188:191], v[220:223], v[32:35]
	v_mfma_f32_16x16x32_bf16 v[60:63], v[184:187], v[200:203], v[60:63]
	v_mfma_f32_16x16x32_bf16 v[56:59], v[192:195], v[200:203], v[56:59]
	v_mfma_f32_16x16x32_bf16 v[52:55], v[184:187], v[208:211], v[52:55]
	v_mfma_f32_16x16x32_bf16 v[48:51], v[192:195], v[208:211], v[48:51]
	v_mfma_f32_16x16x32_bf16 v[44:47], v[184:187], v[216:219], v[44:47]
	v_mfma_f32_16x16x32_bf16 v[40:43], v[192:195], v[216:219], v[40:43]
	v_mfma_f32_16x16x32_bf16 v[36:39], v[184:187], v[240:243], v[36:39]
	v_mfma_f32_16x16x32_bf16 v[32:35], v[192:195], v[240:243], v[32:35]
	s_barrier
	v_readfirstlane_b32 s4, v151
	v_add_u32_e32 v175, 0x2000, v151
	v_lshl_add_u64 v[176:177], v[248:249], 0, s[18:19]
	s_mov_b32 m0, s4
	v_readfirstlane_b32 s4, v175
	global_load_lds_dwordx4 v[176:177], off
	v_lshl_add_u64 v[176:177], v[250:251], 0, s[18:19]
	s_mov_b32 m0, s4
	s_nop 0
	global_load_lds_dwordx4 v[176:177], off
	s_waitcnt vmcnt(6)
	s_barrier
	v_mfma_f32_16x16x32_bf16 v[28:31], v[224:227], v[196:199], v[28:31]
	v_mfma_f32_16x16x32_bf16 v[24:27], v[232:235], v[196:199], v[24:27]
	v_mfma_f32_16x16x32_bf16 v[20:23], v[224:227], v[204:207], v[20:23]
	v_mfma_f32_16x16x32_bf16 v[16:19], v[232:235], v[204:207], v[16:19]
	v_mfma_f32_16x16x32_bf16 v[12:15], v[224:227], v[212:215], v[12:15]
	v_mfma_f32_16x16x32_bf16 v[8:11], v[232:235], v[212:215], v[8:11]
	v_mfma_f32_16x16x32_bf16 v[4:7], v[224:227], v[220:223], v[4:7]
	v_mfma_f32_16x16x32_bf16 v[0:3], v[232:235], v[220:223], v[0:3]
	v_mfma_f32_16x16x32_bf16 v[28:31], v[228:231], v[200:203], v[28:31]
	v_mfma_f32_16x16x32_bf16 v[24:27], v[236:239], v[200:203], v[24:27]
	v_mfma_f32_16x16x32_bf16 v[20:23], v[228:231], v[208:211], v[20:23]
	v_mfma_f32_16x16x32_bf16 v[16:19], v[236:239], v[208:211], v[16:19]
	v_mfma_f32_16x16x32_bf16 v[12:15], v[228:231], v[216:219], v[12:15]
	v_mfma_f32_16x16x32_bf16 v[8:11], v[236:239], v[216:219], v[8:11]
	v_mfma_f32_16x16x32_bf16 v[4:7], v[228:231], v[240:243], v[4:7]
	v_mfma_f32_16x16x32_bf16 v[0:3], v[236:239], v[240:243], v[0:3]
	s_barrier
	ds_read_b128 v[180:183], v163
	ds_read_b128 v[184:187], v163 offset:1024
	ds_read_b128 v[188:191], v163 offset:2048
	ds_read_b128 v[192:195], v163 offset:3072
	v_add_u32_e32 v176, 0x4000, v152
	v_add_u32_e32 v177, 0x6000, v152
	v_readfirstlane_b32 s4, v176
	v_lshl_add_u64 v[228:229], v[244:245], 0, s[20:21]
	s_mov_b32 m0, s4
	v_readfirstlane_b32 s4, v177
	ds_read_b128 v[196:199], v161 offset:32768
	ds_read_b128 v[200:203], v161 offset:33792
	ds_read_b128 v[204:207], v160 offset:32768
	ds_read_b128 v[208:211], v160 offset:33792
	ds_read_b128 v[212:215], v159 offset:32768
	ds_read_b128 v[216:219], v159 offset:33792
	ds_read_b128 v[220:223], v158 offset:32768
	ds_read_b128 v[224:227], v158 offset:33792
	global_load_lds_dwordx4 v[228:229], off
	v_lshl_add_u64 v[228:229], v[246:247], 0, s[20:21]
	s_mov_b32 m0, s4
	s_nop 0
	global_load_lds_dwordx4 v[228:229], off
	s_waitcnt lgkmcnt(8)
	s_barrier
	s_waitcnt lgkmcnt(0)
	v_mfma_f32_16x16x32_bf16 v[124:127], v[180:183], v[196:199], v[124:127]
	v_mfma_f32_16x16x32_bf16 v[120:123], v[188:191], v[196:199], v[120:123]
	v_mfma_f32_16x16x32_bf16 v[116:119], v[180:183], v[204:207], v[116:119]
	v_mfma_f32_16x16x32_bf16 v[112:115], v[188:191], v[204:207], v[112:115]
	v_mfma_f32_16x16x32_bf16 v[108:111], v[180:183], v[212:215], v[108:111]
	v_mfma_f32_16x16x32_bf16 v[104:107], v[188:191], v[212:215], v[104:107]
	v_mfma_f32_16x16x32_bf16 v[100:103], v[180:183], v[220:223], v[100:103]
	v_mfma_f32_16x16x32_bf16 v[96:99], v[188:191], v[220:223], v[96:99]
	v_mfma_f32_16x16x32_bf16 v[124:127], v[184:187], v[200:203], v[124:127]
	v_mfma_f32_16x16x32_bf16 v[120:123], v[192:195], v[200:203], v[120:123]
	v_mfma_f32_16x16x32_bf16 v[116:119], v[184:187], v[208:211], v[116:119]
	v_mfma_f32_16x16x32_bf16 v[112:115], v[192:195], v[208:211], v[112:115]
	v_mfma_f32_16x16x32_bf16 v[108:111], v[184:187], v[216:219], v[108:111]
	v_mfma_f32_16x16x32_bf16 v[104:107], v[192:195], v[216:219], v[104:107]
	v_mfma_f32_16x16x32_bf16 v[100:103], v[184:187], v[224:227], v[100:103]
	v_mfma_f32_16x16x32_bf16 v[96:99], v[192:195], v[224:227], v[96:99]
	s_barrier
	v_readfirstlane_b32 s4, v167
	v_add_u32_e32 v254, 0x2000, v167
	v_lshl_add_u64 v[252:253], v[248:249], 0, s[24:25]
	s_mov_b32 m0, s4
	v_readfirstlane_b32 s4, v254
	ds_read_b128 v[228:231], v162
	ds_read_b128 v[232:235], v162 offset:1024
	ds_read_b128 v[236:239], v162 offset:2048
	ds_read_b128 v[240:243], v162 offset:3072
	global_load_lds_dwordx4 v[252:253], off
	v_lshl_add_u64 v[252:253], v[250:251], 0, s[24:25]
	s_mov_b32 m0, s4
	s_nop 0
	global_load_lds_dwordx4 v[252:253], off
	s_barrier
	s_waitcnt lgkmcnt(0)
	v_mfma_f32_16x16x32_bf16 v[92:95], v[228:231], v[196:199], v[92:95]
	v_mfma_f32_16x16x32_bf16 v[88:91], v[236:239], v[196:199], v[88:91]
	v_mfma_f32_16x16x32_bf16 v[84:87], v[228:231], v[204:207], v[84:87]
	v_mfma_f32_16x16x32_bf16 v[80:83], v[236:239], v[204:207], v[80:83]
	v_mfma_f32_16x16x32_bf16 v[76:79], v[228:231], v[212:215], v[76:79]
	v_mfma_f32_16x16x32_bf16 v[72:75], v[236:239], v[212:215], v[72:75]
	v_mfma_f32_16x16x32_bf16 v[68:71], v[228:231], v[220:223], v[68:71]
	v_mfma_f32_16x16x32_bf16 v[64:67], v[236:239], v[220:223], v[64:67]
	v_mfma_f32_16x16x32_bf16 v[92:95], v[232:235], v[200:203], v[92:95]
	v_mfma_f32_16x16x32_bf16 v[88:91], v[240:243], v[200:203], v[88:91]
	v_mfma_f32_16x16x32_bf16 v[84:87], v[232:235], v[208:211], v[84:87]
	v_mfma_f32_16x16x32_bf16 v[80:83], v[240:243], v[208:211], v[80:83]
	v_mfma_f32_16x16x32_bf16 v[76:79], v[232:235], v[216:219], v[76:79]
	v_mfma_f32_16x16x32_bf16 v[72:75], v[240:243], v[216:219], v[72:75]
	v_mfma_f32_16x16x32_bf16 v[68:71], v[232:235], v[224:227], v[68:71]
	v_mfma_f32_16x16x32_bf16 v[64:67], v[240:243], v[224:227], v[64:67]
	v_readfirstlane_b32 s4, v169
	v_lshl_add_u64 v[244:245], v[244:245], 0, s[26:27]
	s_mov_b32 m0, s4
	v_readfirstlane_b32 s4, v170
	s_barrier
	ds_read_b128 v[196:199], v161 offset:49152
	ds_read_b128 v[200:203], v161 offset:50176
	ds_read_b128 v[204:207], v160 offset:49152
	ds_read_b128 v[208:211], v160 offset:50176
	ds_read_b128 v[212:215], v159 offset:49152
	ds_read_b128 v[216:219], v159 offset:50176
	ds_read_b128 v[220:223], v158 offset:49152
	ds_read_b128 v[224:227], v158 offset:50176
	global_load_lds_dwordx4 v[244:245], off
	v_lshl_add_u64 v[244:245], v[246:247], 0, s[26:27]
	s_mov_b32 m0, s4
	s_nop 0
	global_load_lds_dwordx4 v[244:245], off
	s_barrier
	s_waitcnt lgkmcnt(0)
	v_mfma_f32_16x16x32_bf16 v[60:63], v[180:183], v[196:199], v[60:63]
	v_mfma_f32_16x16x32_bf16 v[56:59], v[188:191], v[196:199], v[56:59]
	v_mfma_f32_16x16x32_bf16 v[52:55], v[180:183], v[204:207], v[52:55]
	v_mfma_f32_16x16x32_bf16 v[48:51], v[188:191], v[204:207], v[48:51]
	v_mfma_f32_16x16x32_bf16 v[44:47], v[180:183], v[212:215], v[44:47]
	v_mfma_f32_16x16x32_bf16 v[40:43], v[188:191], v[212:215], v[40:43]
	v_mfma_f32_16x16x32_bf16 v[36:39], v[180:183], v[220:223], v[36:39]
	v_mfma_f32_16x16x32_bf16 v[32:35], v[188:191], v[220:223], v[32:35]
	v_mfma_f32_16x16x32_bf16 v[60:63], v[184:187], v[200:203], v[60:63]
	v_mfma_f32_16x16x32_bf16 v[56:59], v[192:195], v[200:203], v[56:59]
	v_mfma_f32_16x16x32_bf16 v[52:55], v[184:187], v[208:211], v[52:55]
	v_mfma_f32_16x16x32_bf16 v[48:51], v[192:195], v[208:211], v[48:51]
	v_mfma_f32_16x16x32_bf16 v[44:47], v[184:187], v[216:219], v[44:47]
	v_mfma_f32_16x16x32_bf16 v[40:43], v[192:195], v[216:219], v[40:43]
	v_mfma_f32_16x16x32_bf16 v[36:39], v[184:187], v[224:227], v[36:39]
	v_mfma_f32_16x16x32_bf16 v[32:35], v[192:195], v[224:227], v[32:35]
	s_barrier
	v_readfirstlane_b32 s4, v171
	v_add_u32_e32 v182, 0x2000, v171
	v_lshl_add_u64 v[180:181], v[248:249], 0, s[28:29]
	s_mov_b32 m0, s4
	v_readfirstlane_b32 s4, v182
	global_load_lds_dwordx4 v[180:181], off
	v_lshl_add_u64 v[180:181], v[250:251], 0, s[28:29]
	s_mov_b32 m0, s4
	s_nop 0
	global_load_lds_dwordx4 v[180:181], off
	s_add_i32 s2, s2, 2
	v_lshl_add_u64 v[142:143], v[142:143], 0, s[30:31]
	v_lshl_add_u64 v[144:145], v[144:145], 0, s[30:31]
	v_lshl_add_u64 v[146:147], v[146:147], 0, s[30:31]
	s_cmp_lt_u32 s2, 12
	v_lshl_add_u64 v[148:149], v[148:149], 0, s[30:31]
	s_waitcnt vmcnt(6)
	s_barrier
	v_mfma_f32_16x16x32_bf16 v[28:31], v[228:231], v[196:199], v[28:31]
	v_mfma_f32_16x16x32_bf16 v[24:27], v[236:239], v[196:199], v[24:27]
	v_mfma_f32_16x16x32_bf16 v[20:23], v[228:231], v[204:207], v[20:23]
	v_mfma_f32_16x16x32_bf16 v[16:19], v[236:239], v[204:207], v[16:19]
	v_mfma_f32_16x16x32_bf16 v[12:15], v[228:231], v[212:215], v[12:15]
	v_mfma_f32_16x16x32_bf16 v[8:11], v[236:239], v[212:215], v[8:11]
	v_mfma_f32_16x16x32_bf16 v[4:7], v[228:231], v[220:223], v[4:7]
	v_mfma_f32_16x16x32_bf16 v[0:3], v[236:239], v[220:223], v[0:3]
	v_mfma_f32_16x16x32_bf16 v[28:31], v[232:235], v[200:203], v[28:31]
	v_mfma_f32_16x16x32_bf16 v[24:27], v[240:243], v[200:203], v[24:27]
	v_mfma_f32_16x16x32_bf16 v[20:23], v[232:235], v[208:211], v[20:23]
	v_mfma_f32_16x16x32_bf16 v[16:19], v[240:243], v[208:211], v[16:19]
	v_mfma_f32_16x16x32_bf16 v[12:15], v[232:235], v[216:219], v[12:15]
	v_mfma_f32_16x16x32_bf16 v[8:11], v[240:243], v[216:219], v[8:11]
	v_mfma_f32_16x16x32_bf16 v[4:7], v[232:235], v[224:227], v[4:7]
	v_mfma_f32_16x16x32_bf16 v[0:3], v[240:243], v[224:227], v[0:3]
	s_barrier
	s_cbranch_scc1 .LBB0_2916
	s_or_b32 s4, s36, 0x80
	s_ashr_i32 s5, s4, 31
	s_lshl_b64 s[4:5], s[4:5], 11
	s_add_u32 s4, s1, s4
	s_addc_u32 s5, s23, s5
	v_lshl_add_u64 v[170:171], s[4:5], 0, v[130:131]
	v_lshl_add_u64 v[138:139], v[138:139], 1, v[170:171]
	v_readfirstlane_b32 s2, v178
	v_lshl_add_u64 v[138:139], v[138:139], 0, s[34:35]
	s_mov_b32 m0, s2
	ds_read_b128 v[142:145], v172
	ds_read_b128 v[146:149], v172 offset:1024
	ds_read_b128 v[180:183], v172 offset:2048
	ds_read_b128 v[184:187], v172 offset:3072
	ds_read_b128 v[188:191], v161
	ds_read_b128 v[192:195], v161 offset:1024
	ds_read_b128 v[196:199], v160
	ds_read_b128 v[200:203], v160 offset:1024
	ds_read_b128 v[204:207], v159
	ds_read_b128 v[208:211], v159 offset:1024
	ds_read_b128 v[212:215], v158
	ds_read_b128 v[216:219], v158 offset:1024
	global_load_lds_dwordx4 v[138:139], off
	v_lshl_add_u64 v[138:139], s[4:5], 0, v[134:135]
	v_lshl_add_u64 v[138:139], v[140:141], 1, v[138:139]
	v_readfirstlane_b32 s2, v179
	v_lshl_add_u64 v[138:139], v[138:139], 0, s[34:35]
	s_mov_b32 m0, s2
	v_readlane_b32 s2, v255, 11
	global_load_lds_dwordx4 v[138:139], off
	s_add_i32 s60, s60, s2
	s_barrier
	s_waitcnt lgkmcnt(0)
	s_cmpk_gt_i32 s60, 0x7f
	s_cselect_b64 s[38:39], -1, 0
	s_waitcnt lgkmcnt(0)
	v_mfma_f32_16x16x32_bf16 v[124:127], v[142:145], v[188:191], v[124:127]
	v_mfma_f32_16x16x32_bf16 v[120:123], v[180:183], v[188:191], v[120:123]
	v_mfma_f32_16x16x32_bf16 v[116:119], v[142:145], v[196:199], v[116:119]
	v_mfma_f32_16x16x32_bf16 v[112:115], v[180:183], v[196:199], v[112:115]
	v_mfma_f32_16x16x32_bf16 v[108:111], v[142:145], v[204:207], v[108:111]
	v_mfma_f32_16x16x32_bf16 v[104:107], v[180:183], v[204:207], v[104:107]
	v_mfma_f32_16x16x32_bf16 v[100:103], v[142:145], v[212:215], v[100:103]
	v_mfma_f32_16x16x32_bf16 v[96:99], v[180:183], v[212:215], v[96:99]
	v_mfma_f32_16x16x32_bf16 v[124:127], v[146:149], v[192:195], v[124:127]
	v_mfma_f32_16x16x32_bf16 v[120:123], v[184:187], v[192:195], v[120:123]
	v_mfma_f32_16x16x32_bf16 v[116:119], v[146:149], v[200:203], v[116:119]
	v_mfma_f32_16x16x32_bf16 v[112:115], v[184:187], v[200:203], v[112:115]
	v_mfma_f32_16x16x32_bf16 v[108:111], v[146:149], v[208:211], v[108:111]
	v_mfma_f32_16x16x32_bf16 v[104:107], v[184:187], v[208:211], v[104:107]
	v_mfma_f32_16x16x32_bf16 v[100:103], v[146:149], v[216:219], v[100:103]
	v_mfma_f32_16x16x32_bf16 v[96:99], v[184:187], v[216:219], v[96:99]
	s_barrier
	ds_read_b128 v[138:141], v168
	ds_read_b128 v[220:223], v168 offset:1024
	ds_read_b128 v[224:227], v168 offset:2048
	ds_read_b128 v[168:171], v168 offset:3072
	s_barrier
	s_waitcnt lgkmcnt(0)
	v_mfma_f32_16x16x32_bf16 v[92:95], v[138:141], v[188:191], v[92:95]
	v_mfma_f32_16x16x32_bf16 v[88:91], v[224:227], v[188:191], v[88:91]
	v_mfma_f32_16x16x32_bf16 v[84:87], v[138:141], v[196:199], v[84:87]
	v_mfma_f32_16x16x32_bf16 v[80:83], v[224:227], v[196:199], v[80:83]
	v_mfma_f32_16x16x32_bf16 v[76:79], v[138:141], v[204:207], v[76:79]
	v_mfma_f32_16x16x32_bf16 v[72:75], v[224:227], v[204:207], v[72:75]
	v_mfma_f32_16x16x32_bf16 v[68:71], v[138:141], v[212:215], v[68:71]
	v_mfma_f32_16x16x32_bf16 v[64:67], v[224:227], v[212:215], v[64:67]
	v_mfma_f32_16x16x32_bf16 v[92:95], v[220:223], v[192:195], v[92:95]
	v_mfma_f32_16x16x32_bf16 v[88:91], v[168:171], v[192:195], v[88:91]
	v_mfma_f32_16x16x32_bf16 v[84:87], v[220:223], v[200:203], v[84:87]
	v_mfma_f32_16x16x32_bf16 v[80:83], v[168:171], v[200:203], v[80:83]
	v_mfma_f32_16x16x32_bf16 v[76:79], v[220:223], v[208:211], v[76:79]
	v_mfma_f32_16x16x32_bf16 v[72:75], v[168:171], v[208:211], v[72:75]
	v_mfma_f32_16x16x32_bf16 v[68:71], v[220:223], v[216:219], v[68:71]
	v_mfma_f32_16x16x32_bf16 v[64:67], v[168:171], v[216:219], v[64:67]
	s_barrier
	ds_read_b128 v[188:191], v161 offset:16384
	ds_read_b128 v[192:195], v161 offset:17408
	ds_read_b128 v[196:199], v160 offset:16384
	ds_read_b128 v[200:203], v160 offset:17408
	ds_read_b128 v[204:207], v159 offset:16384
	ds_read_b128 v[208:211], v159 offset:17408
	ds_read_b128 v[212:215], v158 offset:16384
	ds_read_b128 v[216:219], v158 offset:17408
	s_waitcnt vmcnt(4)
	s_barrier
	s_waitcnt lgkmcnt(0)
	v_mfma_f32_16x16x32_bf16 v[60:63], v[142:145], v[188:191], v[60:63]
	v_mfma_f32_16x16x32_bf16 v[56:59], v[180:183], v[188:191], v[56:59]
	v_mfma_f32_16x16x32_bf16 v[52:55], v[142:145], v[196:199], v[52:55]
	v_mfma_f32_16x16x32_bf16 v[48:51], v[180:183], v[196:199], v[48:51]
	v_mfma_f32_16x16x32_bf16 v[44:47], v[142:145], v[204:207], v[44:47]
	v_mfma_f32_16x16x32_bf16 v[40:43], v[180:183], v[204:207], v[40:43]
	v_mfma_f32_16x16x32_bf16 v[36:39], v[142:145], v[212:215], v[36:39]
	v_mfma_f32_16x16x32_bf16 v[32:35], v[180:183], v[212:215], v[32:35]
	v_mfma_f32_16x16x32_bf16 v[60:63], v[146:149], v[192:195], v[60:63]
	v_mfma_f32_16x16x32_bf16 v[56:59], v[184:187], v[192:195], v[56:59]
	v_mfma_f32_16x16x32_bf16 v[52:55], v[146:149], v[200:203], v[52:55]
	v_mfma_f32_16x16x32_bf16 v[48:51], v[184:187], v[200:203], v[48:51]
	v_mfma_f32_16x16x32_bf16 v[44:47], v[146:149], v[208:211], v[44:47]
	v_mfma_f32_16x16x32_bf16 v[40:43], v[184:187], v[208:211], v[40:43]
	v_mfma_f32_16x16x32_bf16 v[36:39], v[146:149], v[216:219], v[36:39]
	v_mfma_f32_16x16x32_bf16 v[32:35], v[184:187], v[216:219], v[32:35]
	v_mfma_f32_16x16x32_bf16 v[28:31], v[138:141], v[188:191], v[28:31]
	v_mfma_f32_16x16x32_bf16 v[24:27], v[224:227], v[188:191], v[24:27]
	v_mfma_f32_16x16x32_bf16 v[20:23], v[138:141], v[196:199], v[20:23]
	v_mfma_f32_16x16x32_bf16 v[16:19], v[224:227], v[196:199], v[16:19]
	v_mfma_f32_16x16x32_bf16 v[12:15], v[138:141], v[204:207], v[12:15]
	v_mfma_f32_16x16x32_bf16 v[8:11], v[224:227], v[204:207], v[8:11]
	v_mfma_f32_16x16x32_bf16 v[4:7], v[138:141], v[212:215], v[4:7]
	v_mfma_f32_16x16x32_bf16 v[0:3], v[224:227], v[212:215], v[0:3]
	v_mfma_f32_16x16x32_bf16 v[28:31], v[220:223], v[192:195], v[28:31]
	v_mfma_f32_16x16x32_bf16 v[24:27], v[168:171], v[192:195], v[24:27]
	v_mfma_f32_16x16x32_bf16 v[20:23], v[220:223], v[200:203], v[20:23]
	v_mfma_f32_16x16x32_bf16 v[16:19], v[168:171], v[200:203], v[16:19]
	v_mfma_f32_16x16x32_bf16 v[12:15], v[220:223], v[208:211], v[12:15]
	v_mfma_f32_16x16x32_bf16 v[8:11], v[168:171], v[208:211], v[8:11]
	v_mfma_f32_16x16x32_bf16 v[4:7], v[220:223], v[216:219], v[4:7]
	v_mfma_f32_16x16x32_bf16 v[0:3], v[168:171], v[216:219], v[0:3]
	s_barrier
	ds_read_b128 v[138:141], v163
	ds_read_b128 v[142:145], v163 offset:1024
	ds_read_b128 v[146:149], v163 offset:2048
	ds_read_b128 v[168:171], v163 offset:3072
	ds_read_b128 v[178:181], v161 offset:32768
	ds_read_b128 v[182:185], v161 offset:33792
	ds_read_b128 v[186:189], v160 offset:32768
	ds_read_b128 v[190:193], v160 offset:33792
	ds_read_b128 v[194:197], v159 offset:32768
	ds_read_b128 v[198:201], v159 offset:33792
	ds_read_b128 v[202:205], v158 offset:32768
	ds_read_b128 v[206:209], v158 offset:33792
	s_waitcnt vmcnt(2)
	s_barrier
	s_waitcnt lgkmcnt(0)
	v_mfma_f32_16x16x32_bf16 v[124:127], v[138:141], v[178:181], v[124:127]
	v_mfma_f32_16x16x32_bf16 v[120:123], v[146:149], v[178:181], v[120:123]
	v_mfma_f32_16x16x32_bf16 v[116:119], v[138:141], v[186:189], v[116:119]
	v_mfma_f32_16x16x32_bf16 v[112:115], v[146:149], v[186:189], v[112:115]
	v_mfma_f32_16x16x32_bf16 v[108:111], v[138:141], v[194:197], v[108:111]
	v_mfma_f32_16x16x32_bf16 v[104:107], v[146:149], v[194:197], v[104:107]
	v_mfma_f32_16x16x32_bf16 v[100:103], v[138:141], v[202:205], v[100:103]
	v_mfma_f32_16x16x32_bf16 v[96:99], v[146:149], v[202:205], v[96:99]
	v_mfma_f32_16x16x32_bf16 v[124:127], v[142:145], v[182:185], v[124:127]
	v_mfma_f32_16x16x32_bf16 v[120:123], v[168:171], v[182:185], v[120:123]
	v_mfma_f32_16x16x32_bf16 v[116:119], v[142:145], v[190:193], v[116:119]
	v_mfma_f32_16x16x32_bf16 v[112:115], v[168:171], v[190:193], v[112:115]
	v_mfma_f32_16x16x32_bf16 v[108:111], v[142:145], v[198:201], v[108:111]
	v_mfma_f32_16x16x32_bf16 v[104:107], v[168:171], v[198:201], v[104:107]
	v_mfma_f32_16x16x32_bf16 v[100:103], v[142:145], v[206:209], v[100:103]
	v_mfma_f32_16x16x32_bf16 v[96:99], v[168:171], v[206:209], v[96:99]
	s_barrier
	ds_read_b128 v[210:213], v162
	ds_read_b128 v[214:217], v162 offset:1024
	ds_read_b128 v[218:221], v162 offset:2048
	ds_read_b128 v[222:225], v162 offset:3072
	s_waitcnt vmcnt(0)
	s_barrier
	s_waitcnt lgkmcnt(0)
	v_mfma_f32_16x16x32_bf16 v[92:95], v[210:213], v[178:181], v[92:95]
	v_mfma_f32_16x16x32_bf16 v[88:91], v[218:221], v[178:181], v[88:91]
	v_mfma_f32_16x16x32_bf16 v[84:87], v[210:213], v[186:189], v[84:87]
	v_mfma_f32_16x16x32_bf16 v[80:83], v[218:221], v[186:189], v[80:83]
	v_mfma_f32_16x16x32_bf16 v[76:79], v[210:213], v[194:197], v[76:79]
	v_mfma_f32_16x16x32_bf16 v[72:75], v[218:221], v[194:197], v[72:75]
	v_mfma_f32_16x16x32_bf16 v[68:71], v[210:213], v[202:205], v[68:71]
	v_mfma_f32_16x16x32_bf16 v[64:67], v[218:221], v[202:205], v[64:67]
	v_mfma_f32_16x16x32_bf16 v[92:95], v[214:217], v[182:185], v[92:95]
	v_mfma_f32_16x16x32_bf16 v[88:91], v[222:225], v[182:185], v[88:91]
	v_mfma_f32_16x16x32_bf16 v[84:87], v[214:217], v[190:193], v[84:87]
	v_mfma_f32_16x16x32_bf16 v[80:83], v[222:225], v[190:193], v[80:83]
	v_mfma_f32_16x16x32_bf16 v[76:79], v[214:217], v[198:201], v[76:79]
	v_mfma_f32_16x16x32_bf16 v[72:75], v[222:225], v[198:201], v[72:75]
	v_mfma_f32_16x16x32_bf16 v[68:71], v[214:217], v[206:209], v[68:71]
	v_mfma_f32_16x16x32_bf16 v[64:67], v[222:225], v[206:209], v[64:67]
	s_barrier
	ds_read_b128 v[178:181], v161 offset:49152
	ds_read_b128 v[182:185], v161 offset:50176
	ds_read_b128 v[186:189], v160 offset:49152
	ds_read_b128 v[160:163], v160 offset:50176
	ds_read_b128 v[190:193], v159 offset:49152
	ds_read_b128 v[194:197], v159 offset:50176
	ds_read_b128 v[198:201], v158 offset:49152
	ds_read_b128 v[202:205], v158 offset:50176
	s_barrier
	s_waitcnt lgkmcnt(0)
	v_mfma_f32_16x16x32_bf16 v[60:63], v[138:141], v[178:181], v[60:63]
	v_mfma_f32_16x16x32_bf16 v[56:59], v[146:149], v[178:181], v[56:59]
	v_mfma_f32_16x16x32_bf16 v[52:55], v[138:141], v[186:189], v[52:55]
	v_mfma_f32_16x16x32_bf16 v[48:51], v[146:149], v[186:189], v[48:51]
	v_mfma_f32_16x16x32_bf16 v[44:47], v[138:141], v[190:193], v[44:47]
	v_mfma_f32_16x16x32_bf16 v[40:43], v[146:149], v[190:193], v[40:43]
	v_mfma_f32_16x16x32_bf16 v[36:39], v[138:141], v[198:201], v[36:39]
	v_mfma_f32_16x16x32_bf16 v[32:35], v[146:149], v[198:201], v[32:35]
	v_mfma_f32_16x16x32_bf16 v[60:63], v[142:145], v[182:185], v[60:63]
	v_mfma_f32_16x16x32_bf16 v[56:59], v[168:171], v[182:185], v[56:59]
	v_mfma_f32_16x16x32_bf16 v[52:55], v[142:145], v[160:163], v[52:55]
	v_mfma_f32_16x16x32_bf16 v[48:51], v[168:171], v[160:163], v[48:51]
	v_mfma_f32_16x16x32_bf16 v[44:47], v[142:145], v[194:197], v[44:47]
	v_mfma_f32_16x16x32_bf16 v[40:43], v[168:171], v[194:197], v[40:43]
	v_mfma_f32_16x16x32_bf16 v[36:39], v[142:145], v[202:205], v[36:39]
	v_mfma_f32_16x16x32_bf16 v[32:35], v[168:171], v[202:205], v[32:35]
	v_mfma_f32_16x16x32_bf16 v[28:31], v[210:213], v[178:181], v[28:31]
	v_mfma_f32_16x16x32_bf16 v[24:27], v[218:221], v[178:181], v[24:27]
	v_mfma_f32_16x16x32_bf16 v[20:23], v[210:213], v[186:189], v[20:23]
	v_mfma_f32_16x16x32_bf16 v[16:19], v[218:221], v[186:189], v[16:19]
	v_mfma_f32_16x16x32_bf16 v[12:15], v[210:213], v[190:193], v[12:15]
	v_mfma_f32_16x16x32_bf16 v[8:11], v[218:221], v[190:193], v[8:11]
	v_mfma_f32_16x16x32_bf16 v[4:7], v[210:213], v[198:201], v[4:7]
	v_mfma_f32_16x16x32_bf16 v[0:3], v[218:221], v[198:201], v[0:3]
	v_mfma_f32_16x16x32_bf16 v[28:31], v[214:217], v[182:185], v[28:31]
	v_mfma_f32_16x16x32_bf16 v[24:27], v[222:225], v[182:185], v[24:27]
	v_mfma_f32_16x16x32_bf16 v[20:23], v[214:217], v[160:163], v[20:23]
	v_mfma_f32_16x16x32_bf16 v[16:19], v[222:225], v[160:163], v[16:19]
	v_mfma_f32_16x16x32_bf16 v[12:15], v[214:217], v[194:197], v[12:15]
	v_mfma_f32_16x16x32_bf16 v[8:11], v[222:225], v[194:197], v[8:11]
	v_mfma_f32_16x16x32_bf16 v[4:7], v[214:217], v[202:205], v[4:7]
	v_mfma_f32_16x16x32_bf16 v[0:3], v[222:225], v[202:205], v[0:3]
	s_and_b64 vcc, exec, s[38:39]
	s_barrier
	s_cbranch_vccnz .LBB0_2919
	s_lshr_b32 s2, s60, 2
	s_and_b32 s4, s60, 3
	s_add_i32 s2, s2, s56
	s_or_b32 s5, s4, s53
	s_lshl_b32 s4, s2, 8
	s_lshl_b32 s2, s5, 19
	s_add_u32 s42, s40, s2
	s_addc_u32 s43, s46, 0
	v_lshl_add_u64 v[138:139], s[42:43], 0, v[130:131]
	v_readfirstlane_b32 s2, v153
	s_ashr_i32 s5, s4, 31
	v_lshl_add_u64 v[138:139], v[138:139], 0, v[132:133]
	s_mov_b32 m0, s2
	s_lshl_b64 s[44:45], s[4:5], 11
	global_load_lds_dwordx4 v[138:139], off
	v_lshl_add_u64 v[138:139], s[42:43], 0, v[134:135]
	v_readfirstlane_b32 s2, v173
	s_add_u32 s44, s1, s44
	v_lshl_add_u64 v[138:139], v[138:139], 0, v[136:137]
	s_mov_b32 m0, s2
	s_addc_u32 s45, s23, s45
	global_load_lds_dwordx4 v[138:139], off
	v_lshl_add_u64 v[138:139], s[44:45], 0, v[130:131]
	v_readfirstlane_b32 s2, v152
	v_lshl_add_u64 v[138:139], v[138:139], 0, v[132:133]
	s_mov_b32 m0, s2
	s_add_u32 s42, s42, 0x40000
	global_load_lds_dwordx4 v[138:139], off
	v_lshl_add_u64 v[138:139], s[44:45], 0, v[134:135]
	v_readfirstlane_b32 s2, v174
	s_addc_u32 s43, s43, 0
	s_bitset1_b32 s4, 7
	v_lshl_add_u64 v[138:139], v[138:139], 0, v[136:137]
	s_mov_b32 m0, s2
	s_ashr_i32 s5, s4, 31
	global_load_lds_dwordx4 v[138:139], off
	v_lshl_add_u64 v[138:139], s[42:43], 0, v[130:131]
	v_readfirstlane_b32 s2, v151
	s_lshl_b64 s[4:5], s[4:5], 11
	v_lshl_add_u64 v[138:139], v[138:139], 0, v[132:133]
	s_mov_b32 m0, s2
	s_add_u32 s4, s1, s4
	global_load_lds_dwordx4 v[138:139], off
	v_lshl_add_u64 v[138:139], s[42:43], 0, v[134:135]
	v_readfirstlane_b32 s2, v175
	s_addc_u32 s5, s23, s5
	v_lshl_add_u64 v[138:139], v[138:139], 0, v[136:137]
	s_mov_b32 m0, s2
	v_lshl_add_u64 v[130:131], s[4:5], 0, v[130:131]
	v_readfirstlane_b32 s2, v176
	global_load_lds_dwordx4 v[138:139], off
	v_lshl_add_u64 v[130:131], v[130:131], 0, v[132:133]
	s_mov_b32 m0, s2
	v_readfirstlane_b32 s2, v177
	global_load_lds_dwordx4 v[130:131], off
	v_lshl_add_u64 v[130:131], s[4:5], 0, v[134:135]
	v_lshl_add_u64 v[130:131], v[130:131], 0, v[136:137]
	s_mov_b32 m0, s2
	s_nop 0
	global_load_lds_dwordx4 v[130:131], off

.LBB0_2971:
	ds_read_b128 v[176:179], v173
	ds_read_b128 v[180:183], v173 offset:1024
	ds_read_b128 v[184:187], v173 offset:2048
	ds_read_b128 v[188:191], v173 offset:3072
	v_add_u32_e32 v174, 0xc000, v157
	v_lshl_add_u64 v[240:241], s[2:3], 0, v[142:143]
	v_readfirstlane_b32 s31, v174
	v_add_u32_e32 v175, 0xe000, v157
	v_lshl_add_u64 v[224:225], v[240:241], 0, s[10:11]
	s_mov_b32 m0, s31
	v_lshl_add_u64 v[242:243], s[2:3], 0, v[144:145]
	v_readfirstlane_b32 s31, v175
	ds_read_b128 v[192:195], v155
	ds_read_b128 v[196:199], v155 offset:1024
	ds_read_b128 v[200:203], v154
	ds_read_b128 v[204:207], v154 offset:1024
	ds_read_b128 v[208:211], v153
	ds_read_b128 v[212:215], v153 offset:1024
	ds_read_b128 v[216:219], v152
	ds_read_b128 v[220:223], v152 offset:1024
	global_load_lds_dwordx4 v[224:225], off
	v_lshl_add_u64 v[224:225], v[242:243], 0, s[10:11]
	s_mov_b32 m0, s31
	s_nop 0
	global_load_lds_dwordx4 v[224:225], off
	s_waitcnt lgkmcnt(8)
	s_barrier
	s_waitcnt lgkmcnt(0)
	v_mfma_f32_16x16x32_bf16 v[124:127], v[176:179], v[192:195], v[124:127]
	v_mfma_f32_16x16x32_bf16 v[120:123], v[184:187], v[192:195], v[120:123]
	v_mfma_f32_16x16x32_bf16 v[116:119], v[176:179], v[200:203], v[116:119]
	v_mfma_f32_16x16x32_bf16 v[112:115], v[184:187], v[200:203], v[112:115]
	v_mfma_f32_16x16x32_bf16 v[108:111], v[176:179], v[208:211], v[108:111]
	v_mfma_f32_16x16x32_bf16 v[104:107], v[184:187], v[208:211], v[104:107]
	v_mfma_f32_16x16x32_bf16 v[100:103], v[176:179], v[216:219], v[100:103]
	v_mfma_f32_16x16x32_bf16 v[96:99], v[184:187], v[216:219], v[96:99]
	v_mfma_f32_16x16x32_bf16 v[124:127], v[180:183], v[196:199], v[124:127]
	v_mfma_f32_16x16x32_bf16 v[120:123], v[188:191], v[196:199], v[120:123]
	v_mfma_f32_16x16x32_bf16 v[116:119], v[180:183], v[204:207], v[116:119]
	v_mfma_f32_16x16x32_bf16 v[112:115], v[188:191], v[204:207], v[112:115]
	v_mfma_f32_16x16x32_bf16 v[108:111], v[180:183], v[212:215], v[108:111]
	v_mfma_f32_16x16x32_bf16 v[104:107], v[188:191], v[212:215], v[104:107]
	v_mfma_f32_16x16x32_bf16 v[100:103], v[180:183], v[220:223], v[100:103]
	v_mfma_f32_16x16x32_bf16 v[96:99], v[188:191], v[220:223], v[96:99]
	s_barrier
	v_lshl_add_u64 v[244:245], s[2:3], 0, v[138:139]
	v_readfirstlane_b32 s31, v151
	v_lshl_add_u64 v[246:247], v[244:245], 0, s[12:13]
	s_mov_b32 m0, s31
	v_add_u32_e32 v250, 0x2000, v151
	ds_read_b128 v[224:227], v170
	ds_read_b128 v[228:231], v170 offset:1024
	ds_read_b128 v[232:235], v170 offset:2048
	ds_read_b128 v[236:239], v170 offset:3072
	global_load_lds_dwordx4 v[246:247], off
	v_lshl_add_u64 v[246:247], s[2:3], 0, v[140:141]
	v_readfirstlane_b32 s31, v250
	v_lshl_add_u64 v[248:249], v[246:247], 0, s[12:13]
	s_mov_b32 m0, s31
	s_nop 0
	global_load_lds_dwordx4 v[248:249], off
	s_barrier
	s_waitcnt lgkmcnt(0)
	v_mfma_f32_16x16x32_bf16 v[92:95], v[224:227], v[192:195], v[92:95]
	v_mfma_f32_16x16x32_bf16 v[88:91], v[232:235], v[192:195], v[88:91]
	v_mfma_f32_16x16x32_bf16 v[84:87], v[224:227], v[200:203], v[84:87]
	v_mfma_f32_16x16x32_bf16 v[80:83], v[232:235], v[200:203], v[80:83]
	v_mfma_f32_16x16x32_bf16 v[76:79], v[224:227], v[208:211], v[76:79]
	v_mfma_f32_16x16x32_bf16 v[72:75], v[232:235], v[208:211], v[72:75]
	v_mfma_f32_16x16x32_bf16 v[68:71], v[224:227], v[216:219], v[68:71]
	v_mfma_f32_16x16x32_bf16 v[64:67], v[232:235], v[216:219], v[64:67]
	v_mfma_f32_16x16x32_bf16 v[92:95], v[228:231], v[196:199], v[92:95]
	v_mfma_f32_16x16x32_bf16 v[88:91], v[236:239], v[196:199], v[88:91]
	v_mfma_f32_16x16x32_bf16 v[84:87], v[228:231], v[204:207], v[84:87]
	v_mfma_f32_16x16x32_bf16 v[80:83], v[236:239], v[204:207], v[80:83]
	v_mfma_f32_16x16x32_bf16 v[76:79], v[228:231], v[212:215], v[76:79]
	v_mfma_f32_16x16x32_bf16 v[72:75], v[236:239], v[212:215], v[72:75]
	v_mfma_f32_16x16x32_bf16 v[68:71], v[228:231], v[220:223], v[68:71]
	v_mfma_f32_16x16x32_bf16 v[64:67], v[236:239], v[220:223], v[64:67]
	v_readfirstlane_b32 s31, v157
	v_lshl_add_u64 v[248:249], v[240:241], 0, s[14:15]
	s_mov_b32 m0, s31
	v_readfirstlane_b32 s31, v158
	s_barrier
	ds_read_b128 v[192:195], v155 offset:16384
	ds_read_b128 v[196:199], v155 offset:17408
	ds_read_b128 v[200:203], v154 offset:16384
	ds_read_b128 v[204:207], v154 offset:17408
	ds_read_b128 v[208:211], v153 offset:16384
	ds_read_b128 v[212:215], v153 offset:17408
	ds_read_b128 v[216:219], v152 offset:16384
	ds_read_b128 v[220:223], v152 offset:17408
	global_load_lds_dwordx4 v[248:249], off
	v_lshl_add_u64 v[248:249], v[242:243], 0, s[14:15]
	s_mov_b32 m0, s31
	s_nop 0
	global_load_lds_dwordx4 v[248:249], off
	s_barrier
	s_waitcnt lgkmcnt(0)
	v_mfma_f32_16x16x32_bf16 v[60:63], v[176:179], v[192:195], v[60:63]
	v_mfma_f32_16x16x32_bf16 v[56:59], v[184:187], v[192:195], v[56:59]
	v_mfma_f32_16x16x32_bf16 v[52:55], v[176:179], v[200:203], v[52:55]
	v_mfma_f32_16x16x32_bf16 v[48:51], v[184:187], v[200:203], v[48:51]
	v_mfma_f32_16x16x32_bf16 v[44:47], v[176:179], v[208:211], v[44:47]
	v_mfma_f32_16x16x32_bf16 v[40:43], v[184:187], v[208:211], v[40:43]
	v_mfma_f32_16x16x32_bf16 v[36:39], v[176:179], v[216:219], v[36:39]
	v_mfma_f32_16x16x32_bf16 v[32:35], v[184:187], v[216:219], v[32:35]
	v_mfma_f32_16x16x32_bf16 v[60:63], v[180:183], v[196:199], v[60:63]
	v_mfma_f32_16x16x32_bf16 v[56:59], v[188:191], v[196:199], v[56:59]
	v_mfma_f32_16x16x32_bf16 v[52:55], v[180:183], v[204:207], v[52:55]
	v_mfma_f32_16x16x32_bf16 v[48:51], v[188:191], v[204:207], v[48:51]
	v_mfma_f32_16x16x32_bf16 v[44:47], v[180:183], v[212:215], v[44:47]
	v_mfma_f32_16x16x32_bf16 v[40:43], v[188:191], v[212:215], v[40:43]
	v_mfma_f32_16x16x32_bf16 v[36:39], v[180:183], v[220:223], v[36:39]
	v_mfma_f32_16x16x32_bf16 v[32:35], v[188:191], v[220:223], v[32:35]
	s_barrier
	v_readfirstlane_b32 s31, v159
	v_add_u32_e32 v178, 0x2000, v159
	v_lshl_add_u64 v[176:177], v[244:245], 0, s[16:17]
	s_mov_b32 m0, s31
	v_readfirstlane_b32 s31, v178
	global_load_lds_dwordx4 v[176:177], off
	v_lshl_add_u64 v[176:177], v[246:247], 0, s[16:17]
	s_mov_b32 m0, s31
	s_nop 0
	global_load_lds_dwordx4 v[176:177], off
	s_waitcnt vmcnt(6)
	s_barrier
	v_mfma_f32_16x16x32_bf16 v[28:31], v[224:227], v[192:195], v[28:31]
	v_mfma_f32_16x16x32_bf16 v[24:27], v[232:235], v[192:195], v[24:27]
	v_mfma_f32_16x16x32_bf16 v[20:23], v[224:227], v[200:203], v[20:23]
	v_mfma_f32_16x16x32_bf16 v[16:19], v[232:235], v[200:203], v[16:19]
	v_mfma_f32_16x16x32_bf16 v[12:15], v[224:227], v[208:211], v[12:15]
	v_mfma_f32_16x16x32_bf16 v[8:11], v[232:235], v[208:211], v[8:11]
	v_mfma_f32_16x16x32_bf16 v[4:7], v[224:227], v[216:219], v[4:7]
	v_mfma_f32_16x16x32_bf16 v[0:3], v[232:235], v[216:219], v[0:3]
	v_mfma_f32_16x16x32_bf16 v[28:31], v[228:231], v[196:199], v[28:31]
	v_mfma_f32_16x16x32_bf16 v[24:27], v[236:239], v[196:199], v[24:27]
	v_mfma_f32_16x16x32_bf16 v[20:23], v[228:231], v[204:207], v[20:23]
	v_mfma_f32_16x16x32_bf16 v[16:19], v[236:239], v[204:207], v[16:19]
	v_mfma_f32_16x16x32_bf16 v[12:15], v[228:231], v[212:215], v[12:15]
	v_mfma_f32_16x16x32_bf16 v[8:11], v[236:239], v[212:215], v[8:11]
	v_mfma_f32_16x16x32_bf16 v[4:7], v[228:231], v[220:223], v[4:7]
	v_mfma_f32_16x16x32_bf16 v[0:3], v[236:239], v[220:223], v[0:3]
	s_barrier
	ds_read_b128 v[176:179], v160
	ds_read_b128 v[180:183], v160 offset:1024
	ds_read_b128 v[184:187], v160 offset:2048
	ds_read_b128 v[188:191], v160 offset:3072
	v_readfirstlane_b32 s31, v161
	v_lshl_add_u64 v[224:225], v[240:241], 0, s[18:19]
	s_mov_b32 m0, s31
	v_readfirstlane_b32 s31, v162
	ds_read_b128 v[192:195], v155 offset:32768
	ds_read_b128 v[196:199], v155 offset:33792
	ds_read_b128 v[200:203], v154 offset:32768
	ds_read_b128 v[204:207], v154 offset:33792
	ds_read_b128 v[208:211], v153 offset:32768
	ds_read_b128 v[212:215], v153 offset:33792
	ds_read_b128 v[216:219], v152 offset:32768
	ds_read_b128 v[220:223], v152 offset:33792
	global_load_lds_dwordx4 v[224:225], off
	v_lshl_add_u64 v[224:225], v[242:243], 0, s[18:19]
	s_mov_b32 m0, s31
	s_nop 0
	global_load_lds_dwordx4 v[224:225], off
	s_waitcnt lgkmcnt(8)
	s_barrier
	s_waitcnt lgkmcnt(0)
	v_mfma_f32_16x16x32_bf16 v[124:127], v[176:179], v[192:195], v[124:127]
	v_mfma_f32_16x16x32_bf16 v[120:123], v[184:187], v[192:195], v[120:123]
	v_mfma_f32_16x16x32_bf16 v[116:119], v[176:179], v[200:203], v[116:119]
	v_mfma_f32_16x16x32_bf16 v[112:115], v[184:187], v[200:203], v[112:115]
	v_mfma_f32_16x16x32_bf16 v[108:111], v[176:179], v[208:211], v[108:111]
	v_mfma_f32_16x16x32_bf16 v[104:107], v[184:187], v[208:211], v[104:107]
	v_mfma_f32_16x16x32_bf16 v[100:103], v[176:179], v[216:219], v[100:103]
	v_mfma_f32_16x16x32_bf16 v[96:99], v[184:187], v[216:219], v[96:99]
	v_mfma_f32_16x16x32_bf16 v[124:127], v[180:183], v[196:199], v[124:127]
	v_mfma_f32_16x16x32_bf16 v[120:123], v[188:191], v[196:199], v[120:123]
	v_mfma_f32_16x16x32_bf16 v[116:119], v[180:183], v[204:207], v[116:119]
	v_mfma_f32_16x16x32_bf16 v[112:115], v[188:191], v[204:207], v[112:115]
	v_mfma_f32_16x16x32_bf16 v[108:111], v[180:183], v[212:215], v[108:111]
	v_mfma_f32_16x16x32_bf16 v[104:107], v[188:191], v[212:215], v[104:107]
	v_mfma_f32_16x16x32_bf16 v[100:103], v[180:183], v[220:223], v[100:103]
	v_mfma_f32_16x16x32_bf16 v[96:99], v[188:191], v[220:223], v[96:99]
	s_barrier
	v_readfirstlane_b32 s31, v163
	v_lshl_add_u64 v[248:249], v[244:245], 0, s[20:21]
	s_mov_b32 m0, s31
	v_readfirstlane_b32 s31, v167
	ds_read_b128 v[224:227], v156
	ds_read_b128 v[228:231], v156 offset:1024
	ds_read_b128 v[232:235], v156 offset:2048
	ds_read_b128 v[236:239], v156 offset:3072
	global_load_lds_dwordx4 v[248:249], off
	v_lshl_add_u64 v[248:249], v[246:247], 0, s[20:21]
	s_mov_b32 m0, s31
	s_nop 0
	global_load_lds_dwordx4 v[248:249], off
	s_barrier
	s_waitcnt lgkmcnt(0)
	v_mfma_f32_16x16x32_bf16 v[92:95], v[224:227], v[192:195], v[92:95]
	v_mfma_f32_16x16x32_bf16 v[88:91], v[232:235], v[192:195], v[88:91]
	v_mfma_f32_16x16x32_bf16 v[84:87], v[224:227], v[200:203], v[84:87]
	v_mfma_f32_16x16x32_bf16 v[80:83], v[232:235], v[200:203], v[80:83]
	v_mfma_f32_16x16x32_bf16 v[76:79], v[224:227], v[208:211], v[76:79]
	v_mfma_f32_16x16x32_bf16 v[72:75], v[232:235], v[208:211], v[72:75]
	v_mfma_f32_16x16x32_bf16 v[68:71], v[224:227], v[216:219], v[68:71]
	v_mfma_f32_16x16x32_bf16 v[64:67], v[232:235], v[216:219], v[64:67]
	v_mfma_f32_16x16x32_bf16 v[92:95], v[228:231], v[196:199], v[92:95]
	v_mfma_f32_16x16x32_bf16 v[88:91], v[236:239], v[196:199], v[88:91]
	v_mfma_f32_16x16x32_bf16 v[84:87], v[228:231], v[204:207], v[84:87]
	v_mfma_f32_16x16x32_bf16 v[80:83], v[236:239], v[204:207], v[80:83]
	v_mfma_f32_16x16x32_bf16 v[76:79], v[228:231], v[212:215], v[76:79]
	v_mfma_f32_16x16x32_bf16 v[72:75], v[236:239], v[212:215], v[72:75]
	v_mfma_f32_16x16x32_bf16 v[68:71], v[228:231], v[220:223], v[68:71]
	v_mfma_f32_16x16x32_bf16 v[64:67], v[236:239], v[220:223], v[64:67]
	v_readfirstlane_b32 s31, v168
	v_lshl_add_u64 v[240:241], v[240:241], 0, s[24:25]
	s_mov_b32 m0, s31
	v_readfirstlane_b32 s31, v169
	s_barrier
	ds_read_b128 v[192:195], v155 offset:49152
	ds_read_b128 v[196:199], v155 offset:50176
	ds_read_b128 v[200:203], v154 offset:49152
	ds_read_b128 v[204:207], v154 offset:50176
	ds_read_b128 v[208:211], v153 offset:49152
	ds_read_b128 v[212:215], v153 offset:50176
	ds_read_b128 v[216:219], v152 offset:49152
	ds_read_b128 v[220:223], v152 offset:50176
	global_load_lds_dwordx4 v[240:241], off
	v_lshl_add_u64 v[240:241], v[242:243], 0, s[24:25]
	s_mov_b32 m0, s31
	s_nop 0
	global_load_lds_dwordx4 v[240:241], off
	s_barrier
	s_waitcnt lgkmcnt(0)
	v_mfma_f32_16x16x32_bf16 v[60:63], v[176:179], v[192:195], v[60:63]
	v_mfma_f32_16x16x32_bf16 v[56:59], v[184:187], v[192:195], v[56:59]
	v_mfma_f32_16x16x32_bf16 v[52:55], v[176:179], v[200:203], v[52:55]
	v_mfma_f32_16x16x32_bf16 v[48:51], v[184:187], v[200:203], v[48:51]
	v_mfma_f32_16x16x32_bf16 v[44:47], v[176:179], v[208:211], v[44:47]
	v_mfma_f32_16x16x32_bf16 v[40:43], v[184:187], v[208:211], v[40:43]
	v_mfma_f32_16x16x32_bf16 v[36:39], v[176:179], v[216:219], v[36:39]
	v_mfma_f32_16x16x32_bf16 v[32:35], v[184:187], v[216:219], v[32:35]
	v_mfma_f32_16x16x32_bf16 v[60:63], v[180:183], v[196:199], v[60:63]
	v_mfma_f32_16x16x32_bf16 v[56:59], v[188:191], v[196:199], v[56:59]
	v_mfma_f32_16x16x32_bf16 v[52:55], v[180:183], v[204:207], v[52:55]
	v_mfma_f32_16x16x32_bf16 v[48:51], v[188:191], v[204:207], v[48:51]
	v_mfma_f32_16x16x32_bf16 v[44:47], v[180:183], v[212:215], v[44:47]
	v_mfma_f32_16x16x32_bf16 v[40:43], v[188:191], v[212:215], v[40:43]
	v_mfma_f32_16x16x32_bf16 v[36:39], v[180:183], v[220:223], v[36:39]
	v_mfma_f32_16x16x32_bf16 v[32:35], v[188:191], v[220:223], v[32:35]
	s_barrier
	v_readfirstlane_b32 s31, v171
	v_lshl_add_u64 v[176:177], v[244:245], 0, s[26:27]
	s_mov_b32 m0, s31
	v_readfirstlane_b32 s31, v172
	global_load_lds_dwordx4 v[176:177], off
	v_lshl_add_u64 v[176:177], v[246:247], 0, s[26:27]
	s_mov_b32 m0, s31
	s_nop 0
	global_load_lds_dwordx4 v[176:177], off
	s_add_i32 s6, s6, 2
	v_lshl_add_u64 v[138:139], v[138:139], 0, s[28:29]
	v_lshl_add_u64 v[140:141], v[140:141], 0, s[28:29]
	v_lshl_add_u64 v[142:143], v[142:143], 0, s[28:29]
	s_cmp_lt_u32 s6, 60
	v_lshl_add_u64 v[144:145], v[144:145], 0, s[28:29]
	s_waitcnt vmcnt(6)
	s_barrier
	v_mfma_f32_16x16x32_bf16 v[28:31], v[224:227], v[192:195], v[28:31]
	v_mfma_f32_16x16x32_bf16 v[24:27], v[232:235], v[192:195], v[24:27]
	v_mfma_f32_16x16x32_bf16 v[20:23], v[224:227], v[200:203], v[20:23]
	v_mfma_f32_16x16x32_bf16 v[16:19], v[232:235], v[200:203], v[16:19]
	v_mfma_f32_16x16x32_bf16 v[12:15], v[224:227], v[208:211], v[12:15]
	v_mfma_f32_16x16x32_bf16 v[8:11], v[232:235], v[208:211], v[8:11]
	v_mfma_f32_16x16x32_bf16 v[4:7], v[224:227], v[216:219], v[4:7]
	v_mfma_f32_16x16x32_bf16 v[0:3], v[232:235], v[216:219], v[0:3]
	v_mfma_f32_16x16x32_bf16 v[28:31], v[228:231], v[196:199], v[28:31]
	v_mfma_f32_16x16x32_bf16 v[24:27], v[236:239], v[196:199], v[24:27]
	v_mfma_f32_16x16x32_bf16 v[20:23], v[228:231], v[204:207], v[20:23]
	v_mfma_f32_16x16x32_bf16 v[16:19], v[236:239], v[204:207], v[16:19]
	v_mfma_f32_16x16x32_bf16 v[12:15], v[228:231], v[212:215], v[12:15]
	v_mfma_f32_16x16x32_bf16 v[8:11], v[236:239], v[212:215], v[8:11]
	v_mfma_f32_16x16x32_bf16 v[4:7], v[228:231], v[220:223], v[4:7]
	v_mfma_f32_16x16x32_bf16 v[0:3], v[236:239], v[220:223], v[0:3]
	s_barrier
	s_cbranch_scc1 .LBB0_2971
	s_add_u32 s34, s34, 0x1f80
	s_addc_u32 s35, s35, 0
	v_lshl_add_u64 v[132:133], s[34:35], 0, v[132:133]
	v_readfirstlane_b32 s6, v174
	v_lshl_add_u64 v[130:131], v[130:131], 1, v[132:133]
	s_mov_b32 m0, s6
	ds_read_b128 v[138:141], v173
	ds_read_b128 v[142:145], v173 offset:1024
	ds_read_b128 v[176:179], v173 offset:2048
	ds_read_b128 v[180:183], v173 offset:3072
	ds_read_b128 v[184:187], v155
	ds_read_b128 v[188:191], v155 offset:1024
	ds_read_b128 v[192:195], v154
	ds_read_b128 v[196:199], v154 offset:1024
	ds_read_b128 v[200:203], v153
	ds_read_b128 v[204:207], v153 offset:1024
	ds_read_b128 v[208:211], v152
	ds_read_b128 v[212:215], v152 offset:1024
	global_load_lds_dwordx4 v[130:131], off
	v_lshl_add_u64 v[130:131], s[34:35], 0, v[136:137]
	v_readfirstlane_b32 s6, v175
	v_lshl_add_u64 v[130:131], v[134:135], 1, v[130:131]
	s_mov_b32 m0, s6
	s_nop 0
	global_load_lds_dwordx4 v[130:131], off
	s_barrier
	s_waitcnt lgkmcnt(0)
	v_mfma_f32_16x16x32_bf16 v[124:127], v[138:141], v[184:187], v[124:127]
	v_mfma_f32_16x16x32_bf16 v[116:119], v[138:141], v[192:195], v[116:119]
	v_mfma_f32_16x16x32_bf16 v[108:111], v[138:141], v[200:203], v[108:111]
	v_mfma_f32_16x16x32_bf16 v[100:103], v[138:141], v[208:211], v[100:103]
	v_mfma_f32_16x16x32_bf16 v[124:127], v[142:145], v[188:191], v[124:127]
	v_mfma_f32_16x16x32_bf16 v[120:123], v[176:179], v[184:187], v[120:123]
	v_mfma_f32_16x16x32_bf16 v[116:119], v[142:145], v[196:199], v[116:119]
	v_mfma_f32_16x16x32_bf16 v[112:115], v[176:179], v[192:195], v[112:115]
	v_mfma_f32_16x16x32_bf16 v[108:111], v[142:145], v[204:207], v[108:111]
	v_mfma_f32_16x16x32_bf16 v[104:107], v[176:179], v[200:203], v[104:107]
	v_mfma_f32_16x16x32_bf16 v[100:103], v[142:145], v[212:215], v[100:103]
	v_mfma_f32_16x16x32_bf16 v[96:99], v[176:179], v[208:211], v[96:99]
	v_mfma_f32_16x16x32_bf16 v[130:133], v[180:183], v[188:191], v[120:123]
	v_mfma_f32_16x16x32_bf16 v[134:137], v[180:183], v[196:199], v[112:115]
	v_mfma_f32_16x16x32_bf16 v[172:175], v[180:183], v[204:207], v[104:107]
	v_mfma_f32_16x16x32_bf16 v[216:219], v[180:183], v[212:215], v[96:99]
	s_barrier
	s_nop 1
	ds_read_b128 v[96:99], v170
	ds_read_b128 v[104:107], v170 offset:1024
	ds_read_b128 v[112:115], v170 offset:2048
	ds_read_b128 v[120:123], v170 offset:3072
	s_barrier
	s_waitcnt lgkmcnt(0)
	v_mfma_f32_16x16x32_bf16 v[92:95], v[96:99], v[184:187], v[92:95]
	v_mfma_f32_16x16x32_bf16 v[84:87], v[96:99], v[192:195], v[84:87]
	v_mfma_f32_16x16x32_bf16 v[76:79], v[96:99], v[200:203], v[76:79]
	v_mfma_f32_16x16x32_bf16 v[68:71], v[96:99], v[208:211], v[68:71]
	v_mfma_f32_16x16x32_bf16 v[92:95], v[104:107], v[188:191], v[92:95]
	v_mfma_f32_16x16x32_bf16 v[88:91], v[112:115], v[184:187], v[88:91]
	v_mfma_f32_16x16x32_bf16 v[84:87], v[104:107], v[196:199], v[84:87]
	v_mfma_f32_16x16x32_bf16 v[80:83], v[112:115], v[192:195], v[80:83]
	v_mfma_f32_16x16x32_bf16 v[76:79], v[104:107], v[204:207], v[76:79]
	v_mfma_f32_16x16x32_bf16 v[72:75], v[112:115], v[200:203], v[72:75]
	v_mfma_f32_16x16x32_bf16 v[68:71], v[104:107], v[212:215], v[68:71]
	v_mfma_f32_16x16x32_bf16 v[64:67], v[112:115], v[208:211], v[64:67]
	v_mfma_f32_16x16x32_bf16 v[168:171], v[120:123], v[188:191], v[88:91]
	v_mfma_f32_16x16x32_bf16 v[184:187], v[120:123], v[196:199], v[80:83]
	v_mfma_f32_16x16x32_bf16 v[188:191], v[120:123], v[204:207], v[72:75]
	v_mfma_f32_16x16x32_bf16 v[192:195], v[120:123], v[212:215], v[64:67]
	s_barrier
	s_nop 1
	ds_read_b128 v[64:67], v155 offset:16384
	ds_read_b128 v[72:75], v155 offset:17408
	ds_read_b128 v[80:83], v154 offset:16384
	ds_read_b128 v[88:91], v154 offset:17408
	ds_read_b128 v[196:199], v153 offset:16384
	ds_read_b128 v[200:203], v153 offset:17408
	ds_read_b128 v[204:207], v152 offset:16384
	ds_read_b128 v[208:211], v152 offset:17408
	s_waitcnt vmcnt(4)
	s_barrier
	s_waitcnt lgkmcnt(0)
	v_mfma_f32_16x16x32_bf16 v[60:63], v[138:141], v[64:67], v[60:63]
	v_mfma_f32_16x16x32_bf16 v[52:55], v[138:141], v[80:83], v[52:55]
	v_mfma_f32_16x16x32_bf16 v[44:47], v[138:141], v[196:199], v[44:47]
	v_mfma_f32_16x16x32_bf16 v[36:39], v[138:141], v[204:207], v[36:39]
	v_mfma_f32_16x16x32_bf16 v[60:63], v[142:145], v[72:75], v[60:63]
	v_mfma_f32_16x16x32_bf16 v[56:59], v[176:179], v[64:67], v[56:59]
	v_mfma_f32_16x16x32_bf16 v[52:55], v[142:145], v[88:91], v[52:55]
	v_mfma_f32_16x16x32_bf16 v[48:51], v[176:179], v[80:83], v[48:51]
	v_mfma_f32_16x16x32_bf16 v[44:47], v[142:145], v[200:203], v[44:47]
	v_mfma_f32_16x16x32_bf16 v[40:43], v[176:179], v[196:199], v[40:43]
	v_mfma_f32_16x16x32_bf16 v[36:39], v[142:145], v[208:211], v[36:39]
	v_mfma_f32_16x16x32_bf16 v[32:35], v[176:179], v[204:207], v[32:35]
	v_mfma_f32_16x16x32_bf16 v[212:215], v[180:183], v[72:75], v[56:59]
	v_mfma_f32_16x16x32_bf16 v[220:223], v[180:183], v[88:91], v[48:51]
	v_mfma_f32_16x16x32_bf16 v[224:227], v[180:183], v[200:203], v[40:43]
	v_mfma_f32_16x16x32_bf16 v[138:141], v[180:183], v[208:211], v[32:35]
	v_mfma_f32_16x16x32_bf16 v[28:31], v[96:99], v[64:67], v[28:31]
	v_mfma_f32_16x16x32_bf16 v[20:23], v[96:99], v[80:83], v[20:23]
	v_mfma_f32_16x16x32_bf16 v[12:15], v[96:99], v[196:199], v[12:15]
	v_mfma_f32_16x16x32_bf16 v[4:7], v[96:99], v[204:207], v[4:7]
	v_mfma_f32_16x16x32_bf16 v[28:31], v[104:107], v[72:75], v[28:31]
	v_mfma_f32_16x16x32_bf16 v[24:27], v[112:115], v[64:67], v[24:27]
	v_mfma_f32_16x16x32_bf16 v[20:23], v[104:107], v[88:91], v[20:23]
	v_mfma_f32_16x16x32_bf16 v[16:19], v[112:115], v[80:83], v[16:19]
	v_mfma_f32_16x16x32_bf16 v[12:15], v[104:107], v[200:203], v[12:15]
	v_mfma_f32_16x16x32_bf16 v[8:11], v[112:115], v[196:199], v[8:11]
	v_mfma_f32_16x16x32_bf16 v[4:7], v[104:107], v[208:211], v[4:7]
	v_mfma_f32_16x16x32_bf16 v[0:3], v[112:115], v[204:207], v[0:3]
	v_mfma_f32_16x16x32_bf16 v[142:145], v[120:123], v[72:75], v[24:27]
	v_mfma_f32_16x16x32_bf16 v[176:179], v[120:123], v[88:91], v[16:19]
	v_mfma_f32_16x16x32_bf16 v[180:183], v[120:123], v[200:203], v[8:11]
	v_mfma_f32_16x16x32_bf16 v[196:199], v[120:123], v[208:211], v[0:3]
	s_barrier
	s_nop 1
	ds_read_b128 v[0:3], v160
	ds_read_b128 v[8:11], v160 offset:1024
	ds_read_b128 v[16:19], v160 offset:2048
	ds_read_b128 v[24:27], v160 offset:3072
	ds_read_b128 v[32:35], v155 offset:32768
	ds_read_b128 v[40:43], v155 offset:33792
	ds_read_b128 v[48:51], v154 offset:32768
	ds_read_b128 v[56:59], v154 offset:33792
	ds_read_b128 v[64:67], v153 offset:32768
	ds_read_b128 v[158:161], v153 offset:33792
	ds_read_b128 v[200:203], v152 offset:32768
	ds_read_b128 v[204:207], v152 offset:33792
	s_waitcnt vmcnt(2)
	s_barrier
	s_waitcnt lgkmcnt(0)
	v_mfma_f32_16x16x32_bf16 v[72:75], v[0:3], v[32:35], v[124:127]
	v_mfma_f32_16x16x32_bf16 v[120:123], v[8:11], v[40:43], v[72:75]
	v_mfma_f32_16x16x32_bf16 v[72:75], v[16:19], v[32:35], v[130:133]
	v_mfma_f32_16x16x32_bf16 v[124:127], v[24:27], v[40:43], v[72:75]
	v_mfma_f32_16x16x32_bf16 v[72:75], v[0:3], v[48:51], v[116:119]
	v_mfma_f32_16x16x32_bf16 v[112:115], v[8:11], v[56:59], v[72:75]
	v_mfma_f32_16x16x32_bf16 v[72:75], v[16:19], v[48:51], v[134:137]
	v_mfma_f32_16x16x32_bf16 v[116:119], v[24:27], v[56:59], v[72:75]
	v_mfma_f32_16x16x32_bf16 v[72:75], v[0:3], v[64:67], v[108:111]
	v_mfma_f32_16x16x32_bf16 v[104:107], v[8:11], v[158:161], v[72:75]
	v_mfma_f32_16x16x32_bf16 v[72:75], v[16:19], v[64:67], v[172:175]
	v_mfma_f32_16x16x32_bf16 v[108:111], v[24:27], v[158:161], v[72:75]
	v_mfma_f32_16x16x32_bf16 v[72:75], v[0:3], v[200:203], v[100:103]
	v_mfma_f32_16x16x32_bf16 v[96:99], v[8:11], v[204:207], v[72:75]
	v_mfma_f32_16x16x32_bf16 v[72:75], v[16:19], v[200:203], v[216:219]
	v_mfma_f32_16x16x32_bf16 v[100:103], v[24:27], v[204:207], v[72:75]
	s_barrier
	ds_read_b128 v[130:133], v156
	ds_read_b128 v[134:137], v156 offset:1024
	ds_read_b128 v[172:175], v156 offset:2048
	ds_read_b128 v[208:211], v156 offset:3072
	s_waitcnt vmcnt(0)
	s_barrier
	s_waitcnt lgkmcnt(0)
	v_mfma_f32_16x16x32_bf16 v[72:75], v[130:133], v[32:35], v[92:95]
	v_mfma_f32_16x16x32_bf16 v[32:35], v[172:175], v[32:35], v[168:171]
	v_mfma_f32_16x16x32_bf16 v[92:95], v[208:211], v[40:43], v[32:35]
	v_mfma_f32_16x16x32_bf16 v[32:35], v[130:133], v[48:51], v[84:87]
	v_mfma_f32_16x16x32_bf16 v[80:83], v[134:137], v[56:59], v[32:35]
	v_mfma_f32_16x16x32_bf16 v[32:35], v[172:175], v[48:51], v[184:187]
	v_mfma_f32_16x16x32_bf16 v[84:87], v[208:211], v[56:59], v[32:35]
	v_mfma_f32_16x16x32_bf16 v[32:35], v[130:133], v[64:67], v[76:79]
	v_mfma_f32_16x16x32_bf16 v[88:91], v[134:137], v[40:43], v[72:75]
	v_mfma_f32_16x16x32_bf16 v[72:75], v[134:137], v[158:161], v[32:35]
	v_mfma_f32_16x16x32_bf16 v[32:35], v[172:175], v[64:67], v[188:191]
	v_mfma_f32_16x16x32_bf16 v[76:79], v[208:211], v[158:161], v[32:35]
	v_mfma_f32_16x16x32_bf16 v[32:35], v[130:133], v[200:203], v[68:71]
	v_mfma_f32_16x16x32_bf16 v[64:67], v[134:137], v[204:207], v[32:35]
	v_mfma_f32_16x16x32_bf16 v[32:35], v[172:175], v[200:203], v[192:195]
	v_mfma_f32_16x16x32_bf16 v[68:71], v[208:211], v[204:207], v[32:35]
	s_barrier
	ds_read_b128 v[156:159], v155 offset:49152
	ds_read_b128 v[160:163], v155 offset:50176
	ds_read_b128 v[168:171], v154 offset:49152
	ds_read_b128 v[184:187], v154 offset:50176
	ds_read_b128 v[188:191], v153 offset:49152
	ds_read_b128 v[192:195], v153 offset:50176
	ds_read_b128 v[200:203], v152 offset:49152
	ds_read_b128 v[152:155], v152 offset:50176
	s_barrier
	s_waitcnt lgkmcnt(0)
	v_mfma_f32_16x16x32_bf16 v[32:35], v[0:3], v[156:159], v[60:63]
	v_mfma_f32_16x16x32_bf16 v[56:59], v[8:11], v[160:163], v[32:35]
	v_mfma_f32_16x16x32_bf16 v[32:35], v[16:19], v[156:159], v[212:215]
	v_mfma_f32_16x16x32_bf16 v[60:63], v[24:27], v[160:163], v[32:35]
	v_mfma_f32_16x16x32_bf16 v[32:35], v[0:3], v[168:171], v[52:55]
	v_mfma_f32_16x16x32_bf16 v[48:51], v[8:11], v[184:187], v[32:35]
	v_mfma_f32_16x16x32_bf16 v[32:35], v[16:19], v[168:171], v[220:223]
	v_mfma_f32_16x16x32_bf16 v[52:55], v[24:27], v[184:187], v[32:35]
	v_mfma_f32_16x16x32_bf16 v[32:35], v[0:3], v[188:191], v[44:47]
	v_mfma_f32_16x16x32_bf16 v[40:43], v[8:11], v[192:195], v[32:35]
	v_mfma_f32_16x16x32_bf16 v[32:35], v[16:19], v[188:191], v[224:227]
	v_mfma_f32_16x16x32_bf16 v[0:3], v[0:3], v[200:203], v[36:39]
	v_mfma_f32_16x16x32_bf16 v[44:47], v[24:27], v[192:195], v[32:35]
	v_mfma_f32_16x16x32_bf16 v[32:35], v[8:11], v[152:155], v[0:3]
	v_mfma_f32_16x16x32_bf16 v[0:3], v[16:19], v[200:203], v[138:141]
	v_mfma_f32_16x16x32_bf16 v[36:39], v[24:27], v[152:155], v[0:3]
	v_mfma_f32_16x16x32_bf16 v[0:3], v[130:133], v[156:159], v[28:31]
	v_mfma_f32_16x16x32_bf16 v[24:27], v[134:137], v[160:163], v[0:3]
	v_mfma_f32_16x16x32_bf16 v[0:3], v[172:175], v[156:159], v[142:145]
	v_mfma_f32_16x16x32_bf16 v[28:31], v[208:211], v[160:163], v[0:3]
	v_mfma_f32_16x16x32_bf16 v[0:3], v[130:133], v[168:171], v[20:23]
	v_mfma_f32_16x16x32_bf16 v[16:19], v[134:137], v[184:187], v[0:3]
	v_mfma_f32_16x16x32_bf16 v[0:3], v[172:175], v[168:171], v[176:179]
	v_mfma_f32_16x16x32_bf16 v[20:23], v[208:211], v[184:187], v[0:3]
	v_mfma_f32_16x16x32_bf16 v[0:3], v[130:133], v[188:191], v[12:15]
	v_mfma_f32_16x16x32_bf16 v[8:11], v[134:137], v[192:195], v[0:3]
	v_mfma_f32_16x16x32_bf16 v[0:3], v[172:175], v[188:191], v[180:183]
	v_mfma_f32_16x16x32_bf16 v[12:15], v[208:211], v[192:195], v[0:3]
	v_mfma_f32_16x16x32_bf16 v[0:3], v[130:133], v[200:203], v[4:7]
	v_mfma_f32_16x16x32_bf16 v[4:7], v[172:175], v[200:203], v[196:199]
	v_mfma_f32_16x16x32_bf16 v[0:3], v[134:137], v[152:155], v[0:3]
	v_mfma_f32_16x16x32_bf16 v[4:7], v[208:211], v[152:155], v[4:7]
	v_cmp_gt_u32_e32 vcc, s56, v128
	s_barrier
	s_and_saveexec_b64 s[34:35], vcc
	s_cbranch_execz .LBB0_2967
	s_barrier
	s_branch .LBB0_2967
